# xor-16/32 cross-lane reductions done with v_permlane16/32_swap instead of ds_bpermute: 64 sites in the residual / final-norm epilogues + 6 in the attention unit
# baseline (speedup 1.0000x reference)
.LBB0_372:
	v_readlane_b32 s8, v250, 7
	s_and_b32 s8, s8, 32
	s_lshl_b32 s11, s92, 14
	v_add_u32_e32 v146, s8, v146
	v_ashrrev_i32_e32 v147, 5, v146
	v_lshlrev_b32_e32 v146, 10, v147
	s_add_i32 s8, s86, 0
	v_add3_u32 v146, s8, v188, v146
	s_and_b32 s17, s11, 0x8000
	v_add_u32_e32 v156, s17, v146
	ds_read_b128 v[148:151], v156
	s_waitcnt lgkmcnt(0)
	v_lshlrev_b32_e32 v154, 16, v150
	v_and_b32_e32 v155, 0xffff0000, v150
	v_lshlrev_b32_e32 v152, 16, v148
	v_and_b32_e32 v153, 0xffff0000, v148
	v_lshlrev_b32_e32 v148, 16, v149
	v_and_b32_e32 v149, 0xffff0000, v149
	v_lshlrev_b32_e32 v150, 16, v151
	v_and_b32_e32 v151, 0xffff0000, v151
	v_pk_fma_f32 v[120:121], v[120:121], 0.5, v[154:155] op_sel_hi:[1,0,1]
	v_pk_fma_f32 v[126:127], v[126:127], 0.5, v[148:149] op_sel_hi:[1,0,1]
	v_pk_fma_f32 v[148:149], v[124:125], 0.5, v[152:153] op_sel_hi:[1,0,1]
	v_pk_fma_f32 v[152:153], v[122:123], 0.5, v[150:151] op_sel_hi:[1,0,1]
	v_cvt_pk_bf16_f32 v122, v148, v149
	v_cvt_pk_bf16_f32 v123, v126, v127
	v_cvt_pk_bf16_f32 v124, v120, v121
	v_mul_f32_e32 v121, v121, v121
	v_mul_f32_e32 v149, v149, v149
	v_mul_f32_e32 v127, v127, v127
	v_fmac_f32_e32 v121, v120, v120
	v_add_u32_e32 v120, 0x10000, v146
	v_fmac_f32_e32 v149, v148, v148
	v_fmac_f32_e32 v127, v126, v126
	v_add_u32_e32 v154, s17, v120
	v_cvt_pk_bf16_f32 v125, v152, v153
	v_add_f32_e32 v126, v149, v127
	ds_read_b128 v[148:151], v154
	v_add_f32_e32 v121, v121, v126
	v_mul_f32_e32 v126, v153, v153
	v_fmac_f32_e32 v126, v152, v152
	v_add_f32_e32 v121, v126, v121
	s_waitcnt lgkmcnt(0)
	v_lshlrev_b32_e32 v126, 16, v148
	v_and_b32_e32 v127, 0xffff0000, v148
	v_lshlrev_b32_e32 v148, 16, v149
	v_and_b32_e32 v149, 0xffff0000, v149
	v_lshlrev_b32_e32 v152, 16, v150
	v_and_b32_e32 v153, 0xffff0000, v150
	v_pk_fma_f32 v[118:119], v[118:119], 0.5, v[148:149] op_sel_hi:[1,0,1]
	v_pk_fma_f32 v[116:117], v[116:117], 0.5, v[126:127] op_sel_hi:[1,0,1]
	v_pk_fma_f32 v[148:149], v[112:113], 0.5, v[152:153] op_sel_hi:[1,0,1]
	v_mul_f32_e32 v112, v117, v117
	v_mul_f32_e32 v113, v119, v119
	v_fmac_f32_e32 v112, v116, v116
	v_fmac_f32_e32 v113, v118, v118
	v_lshlrev_b32_e32 v150, 16, v151
	v_and_b32_e32 v151, 0xffff0000, v151
	v_add_f32_e32 v112, v112, v113
	v_mul_f32_e32 v113, v149, v149
	v_pk_fma_f32 v[126:127], v[114:115], 0.5, v[150:151] op_sel_hi:[1,0,1]
	v_fmac_f32_e32 v113, v148, v148
	v_add_f32_e32 v112, v113, v112
	v_mul_f32_e32 v113, v127, v127
	v_fmac_f32_e32 v113, v126, v126
	v_mbcnt_hi_u32_b32 v115, -1, v225
	v_add_f32_e32 v112, v113, v112
	v_and_b32_e32 v114, 64, v115
	v_add_f32_e32 v113, v121, v112
	v_xor_b32_e32 v112, 16, v115
	v_add_u32_e32 v121, 64, v114
	v_cmp_lt_i32_e32 vcc, v112, v121
	ds_write_b128 v156, v[122:125]
	v_cvt_pk_bf16_f32 v116, v116, v117
	v_cvt_pk_bf16_f32 v117, v118, v119
	v_cvt_pk_bf16_f32 v118, v148, v149
	v_cvt_pk_bf16_f32 v119, v126, v127
	s_nop 0
	v_cndmask_b32_e32 v112, v115, v112, vcc
	v_lshlrev_b32_e32 v112, 2, v112
	v_mov_b32_e32 v114, v113
	s_nop 1
	v_permlane16_swap_b32 v114, v113
	v_cmp_gt_u32_e32 vcc, 16, v184
	ds_write_b128 v154, v[116:119]
	s_waitcnt lgkmcnt(0)
	v_add_f32_e32 v114, v113, v114
	v_xor_b32_e32 v113, 32, v115
	v_cmp_lt_i32_e64 s[8:9], v113, v121
	s_nop 1
	v_cndmask_b32_e64 v113, v115, v113, s[8:9]
	v_lshlrev_b32_e32 v113, 2, v113
	v_mov_b32_e32 v115, v114
	s_nop 1
	v_permlane32_swap_b32 v115, v114
	s_and_saveexec_b64 s[8:9], vcc
	s_cbranch_execz .LBB0_374
	v_lshl_add_u64 v[116:117], v[144:145], 2, s[14:15]
	s_waitcnt lgkmcnt(0)
	v_add_f32_e32 v114, v114, v115
	global_atomic_add_f32 v[116:117], v114, off
.LBB0_374:
	s_or_b64 exec, exec, s[8:9]
	s_or_b32 s8, s87, 16
	v_or_b32_e32 v114, s8, v187
	s_waitcnt lgkmcnt(0)
	v_lshlrev_b32_e32 v115, 6, v114
	v_lshlrev_b32_e32 v114, 2, v114
	s_lshr_b32 s8, s8, 3
	v_and_b32_e32 v115, 0x3c0, v115
	v_and_b32_e32 v114, 32, v114
	v_add_lshl_u32 v116, v147, s8, 10
	v_bitop3_b32 v114, v115, v114, v186 bitop3:0x36
	v_add3_u32 v114, 0, v114, v116
	v_add_u32_e32 v115, s17, v114
	ds_read_b128 v[116:119], v115
	s_waitcnt lgkmcnt(0)
	v_lshlrev_b32_e32 v124, 16, v118
	v_and_b32_e32 v125, 0xffff0000, v118
	v_lshlrev_b32_e32 v122, 16, v116
	v_and_b32_e32 v123, 0xffff0000, v116
	v_lshlrev_b32_e32 v116, 16, v117
	v_and_b32_e32 v117, 0xffff0000, v117
	v_lshlrev_b32_e32 v118, 16, v119
	v_and_b32_e32 v119, 0xffff0000, v119
	v_pk_fma_f32 v[104:105], v[104:105], 0.5, v[124:125] op_sel_hi:[1,0,1]
	v_pk_fma_f32 v[110:111], v[110:111], 0.5, v[116:117] op_sel_hi:[1,0,1]
	v_pk_fma_f32 v[116:117], v[108:109], 0.5, v[122:123] op_sel_hi:[1,0,1]
	v_pk_fma_f32 v[122:123], v[106:107], 0.5, v[118:119] op_sel_hi:[1,0,1]
	v_cvt_pk_bf16_f32 v106, v116, v117
	v_cvt_pk_bf16_f32 v107, v110, v111
	v_cvt_pk_bf16_f32 v108, v104, v105
	v_mul_f32_e32 v105, v105, v105
	v_mul_f32_e32 v117, v117, v117
	v_mul_f32_e32 v111, v111, v111
	v_fmac_f32_e32 v105, v104, v104
	v_add_u32_e32 v104, 0x10000, v114
	v_fmac_f32_e32 v117, v116, v116
	v_fmac_f32_e32 v111, v110, v110
	v_add_u32_e32 v121, s17, v104
	v_cvt_pk_bf16_f32 v109, v122, v123
	v_add_f32_e32 v110, v117, v111
	ds_read_b128 v[116:119], v121
	v_add_f32_e32 v105, v105, v110
	v_mul_f32_e32 v110, v123, v123
	v_fmac_f32_e32 v110, v122, v122
	v_add_f32_e32 v105, v110, v105
	s_waitcnt lgkmcnt(0)
	v_lshlrev_b32_e32 v110, 16, v116
	v_and_b32_e32 v111, 0xffff0000, v116
	v_lshlrev_b32_e32 v116, 16, v117
	v_and_b32_e32 v117, 0xffff0000, v117
	v_lshlrev_b32_e32 v122, 16, v118
	v_and_b32_e32 v123, 0xffff0000, v118
	v_pk_fma_f32 v[102:103], v[102:103], 0.5, v[116:117] op_sel_hi:[1,0,1]
	v_pk_fma_f32 v[100:101], v[100:101], 0.5, v[110:111] op_sel_hi:[1,0,1]
	v_pk_fma_f32 v[116:117], v[96:97], 0.5, v[122:123] op_sel_hi:[1,0,1]
	v_mul_f32_e32 v96, v101, v101
	v_mul_f32_e32 v97, v103, v103
	v_fmac_f32_e32 v96, v100, v100
	v_fmac_f32_e32 v97, v102, v102
	v_lshlrev_b32_e32 v118, 16, v119
	v_and_b32_e32 v119, 0xffff0000, v119
	v_add_f32_e32 v96, v96, v97
	v_mul_f32_e32 v97, v117, v117
	v_pk_fma_f32 v[110:111], v[98:99], 0.5, v[118:119] op_sel_hi:[1,0,1]
	v_fmac_f32_e32 v97, v116, v116
	v_add_f32_e32 v96, v97, v96
	v_mul_f32_e32 v97, v111, v111
	v_fmac_f32_e32 v97, v110, v110
	v_add_f32_e32 v96, v97, v96
	v_add_f32_e32 v96, v105, v96
	v_mov_b32_e32 v97, v96
	s_nop 1
	v_permlane16_swap_b32 v97, v96
	ds_write_b128 v115, v[106:109]
	v_cvt_pk_bf16_f32 v98, v100, v101
	v_cvt_pk_bf16_f32 v99, v102, v103
	v_cvt_pk_bf16_f32 v100, v116, v117
	s_waitcnt lgkmcnt(0)
	v_add_f32_e32 v96, v96, v97
	v_mov_b32_e32 v97, v96
	s_nop 1
	v_permlane32_swap_b32 v97, v96
	v_cvt_pk_bf16_f32 v101, v110, v111
	ds_write_b128 v121, v[98:101]
	s_and_saveexec_b64 s[8:9], vcc
	s_cbranch_execz .LBB0_376
	v_lshl_add_u64 v[98:99], v[144:145], 2, s[14:15]
	s_waitcnt lgkmcnt(0)
	v_add_f32_e32 v96, v96, v97
	global_atomic_add_f32 v[98:99], v96, off offset:64
.LBB0_376:
	s_or_b64 exec, exec, s[8:9]
	s_or_b32 s8, s87, 32
	v_or_b32_e32 v96, s8, v187
	s_waitcnt lgkmcnt(0)
	v_lshlrev_b32_e32 v97, 6, v96
	v_lshlrev_b32_e32 v96, 2, v96
	s_lshr_b32 s8, s8, 3
	v_and_b32_e32 v97, 0x3c0, v97
	v_and_b32_e32 v96, 32, v96
	v_add_lshl_u32 v98, v147, s8, 10
	v_bitop3_b32 v96, v97, v96, v186 bitop3:0x36
	v_add3_u32 v96, 0, v96, v98
	v_add_u32_e32 v97, s17, v96
	ds_read_b128 v[98:101], v97
	s_waitcnt lgkmcnt(0)
	v_lshlrev_b32_e32 v106, 16, v100
	v_and_b32_e32 v107, 0xffff0000, v100
	v_lshlrev_b32_e32 v102, 16, v98
	v_and_b32_e32 v103, 0xffff0000, v98
	v_lshlrev_b32_e32 v98, 16, v99
	v_and_b32_e32 v99, 0xffff0000, v99
	v_lshlrev_b32_e32 v100, 16, v101
	v_and_b32_e32 v101, 0xffff0000, v101
	v_pk_fma_f32 v[88:89], v[88:89], 0.5, v[106:107] op_sel_hi:[1,0,1]
	v_pk_fma_f32 v[94:95], v[94:95], 0.5, v[98:99] op_sel_hi:[1,0,1]
	v_pk_fma_f32 v[98:99], v[92:93], 0.5, v[102:103] op_sel_hi:[1,0,1]
	v_pk_fma_f32 v[102:103], v[90:91], 0.5, v[100:101] op_sel_hi:[1,0,1]
	v_cvt_pk_bf16_f32 v90, v98, v99
	v_cvt_pk_bf16_f32 v91, v94, v95
	v_cvt_pk_bf16_f32 v92, v88, v89
	v_mul_f32_e32 v89, v89, v89
	v_mul_f32_e32 v99, v99, v99
	v_mul_f32_e32 v95, v95, v95
	v_fmac_f32_e32 v89, v88, v88
	v_add_u32_e32 v88, 0x10000, v96
	v_fmac_f32_e32 v99, v98, v98
	v_fmac_f32_e32 v95, v94, v94
	v_add_u32_e32 v105, s17, v88
	v_cvt_pk_bf16_f32 v93, v102, v103
	v_add_f32_e32 v94, v99, v95
	ds_read_b128 v[98:101], v105
	v_add_f32_e32 v89, v89, v94
	v_mul_f32_e32 v94, v103, v103
	v_fmac_f32_e32 v94, v102, v102
	v_add_f32_e32 v89, v94, v89
	s_waitcnt lgkmcnt(0)
	v_lshlrev_b32_e32 v94, 16, v98
	v_and_b32_e32 v95, 0xffff0000, v98
	v_lshlrev_b32_e32 v98, 16, v99
	v_and_b32_e32 v99, 0xffff0000, v99
	v_lshlrev_b32_e32 v102, 16, v100
	v_and_b32_e32 v103, 0xffff0000, v100
	v_pk_fma_f32 v[86:87], v[86:87], 0.5, v[98:99] op_sel_hi:[1,0,1]
	v_pk_fma_f32 v[84:85], v[84:85], 0.5, v[94:95] op_sel_hi:[1,0,1]
	v_pk_fma_f32 v[98:99], v[80:81], 0.5, v[102:103] op_sel_hi:[1,0,1]
	v_mul_f32_e32 v80, v85, v85
	v_mul_f32_e32 v81, v87, v87
	v_fmac_f32_e32 v80, v84, v84
	v_fmac_f32_e32 v81, v86, v86
	v_lshlrev_b32_e32 v100, 16, v101
	v_and_b32_e32 v101, 0xffff0000, v101
	v_add_f32_e32 v80, v80, v81
	v_mul_f32_e32 v81, v99, v99
	v_pk_fma_f32 v[94:95], v[82:83], 0.5, v[100:101] op_sel_hi:[1,0,1]
	v_fmac_f32_e32 v81, v98, v98
	v_add_f32_e32 v80, v81, v80
	v_mul_f32_e32 v81, v95, v95
	v_fmac_f32_e32 v81, v94, v94
	v_add_f32_e32 v80, v81, v80
	v_add_f32_e32 v80, v89, v80
	v_mov_b32_e32 v81, v80
	s_nop 1
	v_permlane16_swap_b32 v81, v80
	ds_write_b128 v97, v[90:93]
	v_cvt_pk_bf16_f32 v82, v84, v85
	v_cvt_pk_bf16_f32 v83, v86, v87
	v_cvt_pk_bf16_f32 v84, v98, v99
	s_waitcnt lgkmcnt(0)
	v_add_f32_e32 v80, v80, v81
	v_mov_b32_e32 v81, v80
	s_nop 1
	v_permlane32_swap_b32 v81, v80
	v_cvt_pk_bf16_f32 v85, v94, v95
	ds_write_b128 v105, v[82:85]
	s_and_saveexec_b64 s[8:9], vcc
	s_cbranch_execz .LBB0_378
	v_lshl_add_u64 v[82:83], v[144:145], 2, s[14:15]
	s_waitcnt lgkmcnt(0)
	v_add_f32_e32 v80, v80, v81
	global_atomic_add_f32 v[82:83], v80, off offset:128
.LBB0_378:
	s_or_b64 exec, exec, s[8:9]
	s_or_b32 s8, s87, 48
	v_or_b32_e32 v80, s8, v187
	s_waitcnt lgkmcnt(0)
	v_lshlrev_b32_e32 v81, 6, v80
	v_lshlrev_b32_e32 v80, 2, v80
	s_lshr_b32 s8, s8, 3
	v_and_b32_e32 v81, 0x3c0, v81
	v_and_b32_e32 v80, 32, v80
	v_add_lshl_u32 v82, v147, s8, 10
	v_bitop3_b32 v80, v81, v80, v186 bitop3:0x36
	v_add3_u32 v80, 0, v80, v82
	v_add_u32_e32 v81, s17, v80
	ds_read_b128 v[82:85], v81
	s_waitcnt lgkmcnt(0)
	v_lshlrev_b32_e32 v90, 16, v84
	v_and_b32_e32 v91, 0xffff0000, v84
	v_lshlrev_b32_e32 v86, 16, v82
	v_and_b32_e32 v87, 0xffff0000, v82
	v_lshlrev_b32_e32 v82, 16, v83
	v_and_b32_e32 v83, 0xffff0000, v83
	v_lshlrev_b32_e32 v84, 16, v85
	v_and_b32_e32 v85, 0xffff0000, v85
	v_pk_fma_f32 v[72:73], v[72:73], 0.5, v[90:91] op_sel_hi:[1,0,1]
	v_pk_fma_f32 v[78:79], v[78:79], 0.5, v[82:83] op_sel_hi:[1,0,1]
	v_pk_fma_f32 v[82:83], v[76:77], 0.5, v[86:87] op_sel_hi:[1,0,1]
	v_pk_fma_f32 v[86:87], v[74:75], 0.5, v[84:85] op_sel_hi:[1,0,1]
	v_cvt_pk_bf16_f32 v74, v82, v83
	v_cvt_pk_bf16_f32 v75, v78, v79
	v_cvt_pk_bf16_f32 v76, v72, v73
	v_mul_f32_e32 v73, v73, v73
	v_mul_f32_e32 v83, v83, v83
	v_mul_f32_e32 v79, v79, v79
	v_fmac_f32_e32 v73, v72, v72
	v_add_u32_e32 v72, 0x10000, v80
	v_fmac_f32_e32 v83, v82, v82
	v_fmac_f32_e32 v79, v78, v78
	v_add_u32_e32 v89, s17, v72
	v_cvt_pk_bf16_f32 v77, v86, v87
	v_add_f32_e32 v78, v83, v79
	ds_read_b128 v[82:85], v89
	v_add_f32_e32 v73, v73, v78
	v_mul_f32_e32 v78, v87, v87
	v_fmac_f32_e32 v78, v86, v86
	v_add_f32_e32 v73, v78, v73
	s_waitcnt lgkmcnt(0)
	v_lshlrev_b32_e32 v78, 16, v82
	v_and_b32_e32 v79, 0xffff0000, v82
	v_lshlrev_b32_e32 v82, 16, v83
	v_and_b32_e32 v83, 0xffff0000, v83
	v_lshlrev_b32_e32 v86, 16, v84
	v_and_b32_e32 v87, 0xffff0000, v84
	v_pk_fma_f32 v[70:71], v[70:71], 0.5, v[82:83] op_sel_hi:[1,0,1]
	v_pk_fma_f32 v[68:69], v[68:69], 0.5, v[78:79] op_sel_hi:[1,0,1]
	v_pk_fma_f32 v[82:83], v[64:65], 0.5, v[86:87] op_sel_hi:[1,0,1]
	v_mul_f32_e32 v64, v69, v69
	v_mul_f32_e32 v65, v71, v71
	v_fmac_f32_e32 v64, v68, v68
	v_fmac_f32_e32 v65, v70, v70
	v_lshlrev_b32_e32 v84, 16, v85
	v_and_b32_e32 v85, 0xffff0000, v85
	v_add_f32_e32 v64, v64, v65
	v_mul_f32_e32 v65, v83, v83
	v_pk_fma_f32 v[78:79], v[66:67], 0.5, v[84:85] op_sel_hi:[1,0,1]
	v_fmac_f32_e32 v65, v82, v82
	v_add_f32_e32 v64, v65, v64
	v_mul_f32_e32 v65, v79, v79
	v_fmac_f32_e32 v65, v78, v78
	v_add_f32_e32 v64, v65, v64
	v_add_f32_e32 v64, v73, v64
	v_mov_b32_e32 v65, v64
	s_nop 1
	v_permlane16_swap_b32 v65, v64
	ds_write_b128 v81, v[74:77]
	v_cvt_pk_bf16_f32 v66, v68, v69
	v_cvt_pk_bf16_f32 v67, v70, v71
	v_cvt_pk_bf16_f32 v68, v82, v83
	s_waitcnt lgkmcnt(0)
	v_add_f32_e32 v64, v64, v65
	v_mov_b32_e32 v65, v64
	s_nop 1
	v_permlane32_swap_b32 v65, v64
	v_cvt_pk_bf16_f32 v69, v78, v79
	ds_write_b128 v89, v[66:69]
	s_and_saveexec_b64 s[8:9], vcc
	s_cbranch_execz .LBB0_380
	v_lshl_add_u64 v[66:67], v[144:145], 2, s[14:15]
	s_waitcnt lgkmcnt(0)
	v_add_f32_e32 v64, v64, v65
	global_atomic_add_f32 v[66:67], v64, off offset:192
.LBB0_380:
	s_or_b64 exec, exec, s[8:9]
	s_bitset1_b32 s11, 14
	v_add_u32_e32 v73, s11, v146
	s_waitcnt lgkmcnt(0)
	ds_read_b128 v[64:67], v73
	s_waitcnt vmcnt(0) lgkmcnt(0)
	v_cndmask_b32_e64 v71, v67, v143, s[6:7]
	v_cndmask_b32_e64 v67, v65, v141, s[6:7]
	v_cndmask_b32_e64 v65, v64, v140, s[6:7]
	v_cndmask_b32_e64 v69, v66, v142, s[6:7]
	v_lshlrev_b32_e32 v64, 16, v65
	v_and_b32_e32 v65, 0xffff0000, v65
	v_lshlrev_b32_e32 v66, 16, v67
	v_and_b32_e32 v67, 0xffff0000, v67
	v_lshlrev_b32_e32 v68, 16, v69
	v_and_b32_e32 v69, 0xffff0000, v69
	v_pk_fma_f32 v[60:61], v[60:61], 0.5, v[64:65] op_sel_hi:[1,0,1]
	v_pk_fma_f32 v[62:63], v[62:63], 0.5, v[66:67] op_sel_hi:[1,0,1]
	v_pk_fma_f32 v[66:67], v[56:57], 0.5, v[68:69] op_sel_hi:[1,0,1]
	v_cvt_pk_bf16_f32 v56, v60, v61
	v_mul_f32_e32 v61, v61, v61
	v_fmac_f32_e32 v61, v60, v60
	v_mul_f32_e32 v60, v63, v63
	v_lshlrev_b32_e32 v70, 16, v71
	v_and_b32_e32 v71, 0xffff0000, v71
	v_fmac_f32_e32 v60, v62, v62
	v_add_u32_e32 v69, s11, v120
	v_pk_fma_f32 v[64:65], v[58:59], 0.5, v[70:71] op_sel_hi:[1,0,1]
	v_cvt_pk_bf16_f32 v57, v62, v63
	v_cvt_pk_bf16_f32 v58, v66, v67
	v_add_f32_e32 v68, v61, v60
	v_cvt_pk_bf16_f32 v59, v64, v65
	ds_read_b128 v[60:63], v69
	v_mul_f32_e32 v67, v67, v67
	v_fmac_f32_e32 v67, v66, v66
	v_mul_f32_e32 v65, v65, v65
	v_add_f32_e32 v66, v67, v68
	v_fmac_f32_e32 v65, v64, v64
	v_add_f32_e32 v68, v65, v66
	s_waitcnt lgkmcnt(0)
	v_lshlrev_b32_e32 v64, 16, v60
	v_and_b32_e32 v65, 0xffff0000, v60
	v_lshlrev_b32_e32 v60, 16, v61
	v_and_b32_e32 v61, 0xffff0000, v61
	v_lshlrev_b32_e32 v66, 16, v62
	v_and_b32_e32 v67, 0xffff0000, v62
	v_lshlrev_b32_e32 v62, 16, v63
	v_and_b32_e32 v63, 0xffff0000, v63
	v_pk_fma_f32 v[54:55], v[54:55], 0.5, v[60:61] op_sel_hi:[1,0,1]
	v_pk_fma_f32 v[52:53], v[52:53], 0.5, v[64:65] op_sel_hi:[1,0,1]
	v_pk_fma_f32 v[60:61], v[50:51], 0.5, v[62:63] op_sel_hi:[1,0,1]
	v_pk_fma_f32 v[62:63], v[48:49], 0.5, v[66:67] op_sel_hi:[1,0,1]
	v_mul_f32_e32 v48, v53, v53
	v_mul_f32_e32 v49, v55, v55
	v_fmac_f32_e32 v48, v52, v52
	v_fmac_f32_e32 v49, v54, v54
	v_add_f32_e32 v48, v48, v49
	v_mul_f32_e32 v49, v63, v63
	v_fmac_f32_e32 v49, v62, v62
	v_add_f32_e32 v48, v49, v48
	v_mul_f32_e32 v49, v61, v61
	v_fmac_f32_e32 v49, v60, v60
	v_add_f32_e32 v48, v49, v48
	v_add_f32_e32 v48, v68, v48
	v_mov_b32_e32 v49, v48
	s_nop 1
	v_permlane16_swap_b32 v49, v48
	ds_write_b128 v73, v[56:59]
	v_cvt_pk_bf16_f32 v50, v52, v53
	v_cvt_pk_bf16_f32 v51, v54, v55
	v_cvt_pk_bf16_f32 v52, v62, v63
	s_waitcnt lgkmcnt(1)
	v_add_f32_e32 v48, v48, v49
	v_mov_b32_e32 v49, v48
	s_nop 1
	v_permlane32_swap_b32 v49, v48
	v_cvt_pk_bf16_f32 v53, v60, v61
	ds_write_b128 v69, v[50:53]
	s_and_saveexec_b64 s[8:9], vcc
	s_cbranch_execz .LBB0_382
	v_lshl_add_u64 v[50:51], v[144:145], 2, s[14:15]
	s_waitcnt lgkmcnt(1)
	v_add_f32_e32 v48, v48, v49
	global_atomic_add_f32 v[50:51], v48, off offset:512
.LBB0_382:
	s_or_b64 exec, exec, s[8:9]
	v_add_u32_e32 v56, s11, v114
	s_waitcnt lgkmcnt(1)
	ds_read_b128 v[48:51], v56
	s_waitcnt lgkmcnt(0)
	v_cndmask_b32_e64 v55, v51, v139, s[6:7]
	v_cndmask_b32_e64 v51, v49, v137, s[6:7]
	v_cndmask_b32_e64 v49, v48, v136, s[6:7]
	v_cndmask_b32_e64 v53, v50, v138, s[6:7]
	v_lshlrev_b32_e32 v48, 16, v49
	v_and_b32_e32 v49, 0xffff0000, v49
	v_lshlrev_b32_e32 v50, 16, v51
	v_and_b32_e32 v51, 0xffff0000, v51
	v_lshlrev_b32_e32 v52, 16, v53
	v_and_b32_e32 v53, 0xffff0000, v53
	v_pk_fma_f32 v[44:45], v[44:45], 0.5, v[48:49] op_sel_hi:[1,0,1]
	v_pk_fma_f32 v[46:47], v[46:47], 0.5, v[50:51] op_sel_hi:[1,0,1]
	v_pk_fma_f32 v[50:51], v[40:41], 0.5, v[52:53] op_sel_hi:[1,0,1]
	v_cvt_pk_bf16_f32 v40, v44, v45
	v_mul_f32_e32 v45, v45, v45
	v_fmac_f32_e32 v45, v44, v44
	v_mul_f32_e32 v44, v47, v47
	v_lshlrev_b32_e32 v54, 16, v55
	v_and_b32_e32 v55, 0xffff0000, v55
	v_fmac_f32_e32 v44, v46, v46
	v_add_u32_e32 v53, s11, v104
	v_pk_fma_f32 v[48:49], v[42:43], 0.5, v[54:55] op_sel_hi:[1,0,1]
	v_cvt_pk_bf16_f32 v41, v46, v47
	v_cvt_pk_bf16_f32 v42, v50, v51
	v_add_f32_e32 v52, v45, v44
	v_cvt_pk_bf16_f32 v43, v48, v49
	ds_read_b128 v[44:47], v53
	v_mul_f32_e32 v51, v51, v51
	v_fmac_f32_e32 v51, v50, v50
	v_mul_f32_e32 v49, v49, v49
	v_add_f32_e32 v50, v51, v52
	v_fmac_f32_e32 v49, v48, v48
	v_add_f32_e32 v52, v49, v50
	s_waitcnt lgkmcnt(0)
	v_lshlrev_b32_e32 v48, 16, v44
	v_and_b32_e32 v49, 0xffff0000, v44
	v_lshlrev_b32_e32 v44, 16, v45
	v_and_b32_e32 v45, 0xffff0000, v45
	v_lshlrev_b32_e32 v50, 16, v46
	v_and_b32_e32 v51, 0xffff0000, v46
	v_lshlrev_b32_e32 v46, 16, v47
	v_and_b32_e32 v47, 0xffff0000, v47
	v_pk_fma_f32 v[38:39], v[38:39], 0.5, v[44:45] op_sel_hi:[1,0,1]
	v_pk_fma_f32 v[36:37], v[36:37], 0.5, v[48:49] op_sel_hi:[1,0,1]
	v_pk_fma_f32 v[44:45], v[34:35], 0.5, v[46:47] op_sel_hi:[1,0,1]
	v_pk_fma_f32 v[46:47], v[32:33], 0.5, v[50:51] op_sel_hi:[1,0,1]
	v_mul_f32_e32 v32, v37, v37
	v_mul_f32_e32 v33, v39, v39
	v_fmac_f32_e32 v32, v36, v36
	v_fmac_f32_e32 v33, v38, v38
	v_add_f32_e32 v32, v32, v33
	v_mul_f32_e32 v33, v47, v47
	v_fmac_f32_e32 v33, v46, v46
	v_add_f32_e32 v32, v33, v32
	v_mul_f32_e32 v33, v45, v45
	v_fmac_f32_e32 v33, v44, v44
	v_add_f32_e32 v32, v33, v32
	v_add_f32_e32 v32, v52, v32
	v_mov_b32_e32 v33, v32
	s_nop 1
	v_permlane16_swap_b32 v33, v32
	ds_write_b128 v56, v[40:43]
	v_cvt_pk_bf16_f32 v34, v36, v37
	v_cvt_pk_bf16_f32 v35, v38, v39
	v_cvt_pk_bf16_f32 v36, v46, v47
	s_waitcnt lgkmcnt(1)
	v_add_f32_e32 v32, v32, v33
	v_mov_b32_e32 v33, v32
	s_nop 1
	v_permlane32_swap_b32 v33, v32
	v_cvt_pk_bf16_f32 v37, v44, v45
	ds_write_b128 v53, v[34:37]
	s_and_saveexec_b64 s[8:9], vcc
	s_cbranch_execz .LBB0_384
	v_lshl_add_u64 v[34:35], v[144:145], 2, s[14:15]
	s_waitcnt lgkmcnt(1)
	v_add_f32_e32 v32, v32, v33
	global_atomic_add_f32 v[34:35], v32, off offset:576
.LBB0_384:
	s_or_b64 exec, exec, s[8:9]
	v_add_u32_e32 v40, s11, v96
	s_waitcnt lgkmcnt(1)
	ds_read_b128 v[32:35], v40
	s_waitcnt lgkmcnt(0)
	v_cndmask_b32_e64 v39, v35, v135, s[6:7]
	v_cndmask_b32_e64 v35, v33, v133, s[6:7]
	v_cndmask_b32_e64 v33, v32, v132, s[6:7]
	v_cndmask_b32_e64 v37, v34, v134, s[6:7]
	v_lshlrev_b32_e32 v32, 16, v33
	v_and_b32_e32 v33, 0xffff0000, v33
	v_lshlrev_b32_e32 v34, 16, v35
	v_and_b32_e32 v35, 0xffff0000, v35
	v_lshlrev_b32_e32 v36, 16, v37
	v_and_b32_e32 v37, 0xffff0000, v37
	v_pk_fma_f32 v[28:29], v[28:29], 0.5, v[32:33] op_sel_hi:[1,0,1]
	v_pk_fma_f32 v[30:31], v[30:31], 0.5, v[34:35] op_sel_hi:[1,0,1]
	v_pk_fma_f32 v[34:35], v[24:25], 0.5, v[36:37] op_sel_hi:[1,0,1]
	v_cvt_pk_bf16_f32 v24, v28, v29
	v_mul_f32_e32 v29, v29, v29
	v_fmac_f32_e32 v29, v28, v28
	v_mul_f32_e32 v28, v31, v31
	v_lshlrev_b32_e32 v38, 16, v39
	v_and_b32_e32 v39, 0xffff0000, v39
	v_fmac_f32_e32 v28, v30, v30
	v_add_u32_e32 v37, s11, v88
	v_pk_fma_f32 v[32:33], v[26:27], 0.5, v[38:39] op_sel_hi:[1,0,1]
	v_cvt_pk_bf16_f32 v25, v30, v31
	v_cvt_pk_bf16_f32 v26, v34, v35
	v_add_f32_e32 v36, v29, v28
	v_cvt_pk_bf16_f32 v27, v32, v33
	ds_read_b128 v[28:31], v37
	v_mul_f32_e32 v35, v35, v35
	v_fmac_f32_e32 v35, v34, v34
	v_mul_f32_e32 v33, v33, v33
	v_add_f32_e32 v34, v35, v36
	v_fmac_f32_e32 v33, v32, v32
	v_add_f32_e32 v36, v33, v34
	s_waitcnt lgkmcnt(0)
	v_lshlrev_b32_e32 v32, 16, v28
	v_and_b32_e32 v33, 0xffff0000, v28
	v_lshlrev_b32_e32 v28, 16, v29
	v_and_b32_e32 v29, 0xffff0000, v29
	v_lshlrev_b32_e32 v34, 16, v30
	v_and_b32_e32 v35, 0xffff0000, v30
	v_lshlrev_b32_e32 v30, 16, v31
	v_and_b32_e32 v31, 0xffff0000, v31
	v_pk_fma_f32 v[22:23], v[22:23], 0.5, v[28:29] op_sel_hi:[1,0,1]
	v_pk_fma_f32 v[20:21], v[20:21], 0.5, v[32:33] op_sel_hi:[1,0,1]
	v_pk_fma_f32 v[28:29], v[18:19], 0.5, v[30:31] op_sel_hi:[1,0,1]
	v_pk_fma_f32 v[30:31], v[16:17], 0.5, v[34:35] op_sel_hi:[1,0,1]
	v_mul_f32_e32 v16, v21, v21
	v_mul_f32_e32 v17, v23, v23
	v_fmac_f32_e32 v16, v20, v20
	v_fmac_f32_e32 v17, v22, v22
	v_add_f32_e32 v16, v16, v17
	v_mul_f32_e32 v17, v31, v31
	v_fmac_f32_e32 v17, v30, v30
	v_add_f32_e32 v16, v17, v16
	v_mul_f32_e32 v17, v29, v29
	v_fmac_f32_e32 v17, v28, v28
	v_add_f32_e32 v16, v17, v16
	v_add_f32_e32 v16, v36, v16
	v_mov_b32_e32 v17, v16
	s_nop 1
	v_permlane16_swap_b32 v17, v16
	ds_write_b128 v40, v[24:27]
	v_cvt_pk_bf16_f32 v18, v20, v21
	v_cvt_pk_bf16_f32 v19, v22, v23
	v_cvt_pk_bf16_f32 v20, v30, v31
	s_waitcnt lgkmcnt(1)
	v_add_f32_e32 v16, v16, v17
	v_mov_b32_e32 v17, v16
	s_nop 1
	v_permlane32_swap_b32 v17, v16
	v_cvt_pk_bf16_f32 v21, v28, v29
	ds_write_b128 v37, v[18:21]
	s_and_saveexec_b64 s[8:9], vcc
	s_cbranch_execz .LBB0_386
	v_lshl_add_u64 v[18:19], v[144:145], 2, s[14:15]
	s_waitcnt lgkmcnt(1)
	v_add_f32_e32 v16, v16, v17
	global_atomic_add_f32 v[18:19], v16, off offset:640
.LBB0_386:
	s_or_b64 exec, exec, s[8:9]
	v_add_u32_e32 v24, s11, v80
	s_waitcnt lgkmcnt(1)
	ds_read_b128 v[16:19], v24
	s_waitcnt lgkmcnt(0)
	v_cndmask_b32_e64 v23, v19, v131, s[6:7]
	v_cndmask_b32_e64 v19, v17, v129, s[6:7]
	v_cndmask_b32_e64 v17, v16, v128, s[6:7]
	v_cndmask_b32_e64 v21, v18, v130, s[6:7]
	v_lshlrev_b32_e32 v16, 16, v17
	v_and_b32_e32 v17, 0xffff0000, v17
	v_lshlrev_b32_e32 v18, 16, v19
	v_and_b32_e32 v19, 0xffff0000, v19
	v_lshlrev_b32_e32 v20, 16, v21
	v_and_b32_e32 v21, 0xffff0000, v21
	v_pk_fma_f32 v[12:13], v[12:13], 0.5, v[16:17] op_sel_hi:[1,0,1]
	v_pk_fma_f32 v[14:15], v[14:15], 0.5, v[18:19] op_sel_hi:[1,0,1]
	v_pk_fma_f32 v[18:19], v[8:9], 0.5, v[20:21] op_sel_hi:[1,0,1]
	v_cvt_pk_bf16_f32 v8, v12, v13
	v_mul_f32_e32 v13, v13, v13
	v_fmac_f32_e32 v13, v12, v12
	v_mul_f32_e32 v12, v15, v15
	v_lshlrev_b32_e32 v22, 16, v23
	v_and_b32_e32 v23, 0xffff0000, v23
	v_fmac_f32_e32 v12, v14, v14
	v_add_u32_e32 v21, s11, v72
	v_pk_fma_f32 v[16:17], v[10:11], 0.5, v[22:23] op_sel_hi:[1,0,1]
	v_cvt_pk_bf16_f32 v9, v14, v15
	v_cvt_pk_bf16_f32 v10, v18, v19
	v_add_f32_e32 v20, v13, v12
	v_cvt_pk_bf16_f32 v11, v16, v17
	ds_read_b128 v[12:15], v21
	v_mul_f32_e32 v19, v19, v19
	v_fmac_f32_e32 v19, v18, v18
	v_mul_f32_e32 v17, v17, v17
	v_add_f32_e32 v18, v19, v20
	v_fmac_f32_e32 v17, v16, v16
	v_add_f32_e32 v20, v17, v18
	s_waitcnt lgkmcnt(0)
	v_lshlrev_b32_e32 v16, 16, v12
	v_and_b32_e32 v17, 0xffff0000, v12
	v_lshlrev_b32_e32 v12, 16, v13
	v_and_b32_e32 v13, 0xffff0000, v13
	v_lshlrev_b32_e32 v18, 16, v14
	v_and_b32_e32 v19, 0xffff0000, v14
	v_lshlrev_b32_e32 v14, 16, v15
	v_and_b32_e32 v15, 0xffff0000, v15
	v_pk_fma_f32 v[6:7], v[6:7], 0.5, v[12:13] op_sel_hi:[1,0,1]
	v_pk_fma_f32 v[4:5], v[4:5], 0.5, v[16:17] op_sel_hi:[1,0,1]
	v_pk_fma_f32 v[12:13], v[2:3], 0.5, v[14:15] op_sel_hi:[1,0,1]
	v_pk_fma_f32 v[14:15], v[0:1], 0.5, v[18:19] op_sel_hi:[1,0,1]
	v_mul_f32_e32 v0, v5, v5
	v_mul_f32_e32 v1, v7, v7
	v_fmac_f32_e32 v0, v4, v4
	v_fmac_f32_e32 v1, v6, v6
	v_add_f32_e32 v0, v0, v1
	v_mul_f32_e32 v1, v15, v15
	v_fmac_f32_e32 v1, v14, v14
	v_add_f32_e32 v0, v1, v0
	v_mul_f32_e32 v1, v13, v13
	v_fmac_f32_e32 v1, v12, v12
	v_add_f32_e32 v0, v1, v0
	v_add_f32_e32 v0, v20, v0
	v_mov_b32_e32 v1, v0
	s_nop 1
	v_permlane16_swap_b32 v1, v0
	ds_write_b128 v24, v[8:11]
	v_cvt_pk_bf16_f32 v2, v4, v5
	v_cvt_pk_bf16_f32 v3, v6, v7
	v_cvt_pk_bf16_f32 v4, v14, v15
	s_waitcnt lgkmcnt(1)
	v_add_f32_e32 v0, v0, v1
	v_mov_b32_e32 v1, v0
	s_nop 1
	v_permlane32_swap_b32 v1, v0
	v_cvt_pk_bf16_f32 v5, v12, v13
	ds_write_b128 v21, v[2:5]
	s_and_saveexec_b64 s[6:7], vcc
	s_cbranch_execz .LBB0_388
	v_lshl_add_u64 v[2:3], v[144:145], 2, s[14:15]
	s_waitcnt lgkmcnt(1)
	v_add_f32_e32 v0, v0, v1
	global_atomic_add_f32 v[2:3], v0, off offset:704

.Latt_vw_go:
	v_add_u32_e32 v0, 0x3c00, v231
	ds_write_b128 v0, v[4:7]
	ds_write_b128 v0, v[8:11] offset:9216
	v_add_u32_e32 v0, 0x8400, v231
	ds_write_b128 v0, v[12:15]
	ds_write_b128 v0, v[16:19] offset:9216
	v_add_u32_e32 v0, 0xcc00, v231
	ds_write_b128 v0, v[20:23]
	ds_write_b128 v0, v[24:27] offset:9216
	v_add_u32_e32 v0, 0x11400, v231
	ds_write_b128 v0, v[28:31]
	ds_write_b128 v0, v[32:35] offset:9216
	v_add_u32_e32 v0, 0x15c00, v231
	ds_write_b128 v0, v[36:39]
	ds_write_b128 v0, v[40:43] offset:9216
	v_add_u32_e32 v0, 0x1a400, v231
	ds_write_b128 v0, v[44:47]
	ds_write_b128 v0, v[48:51] offset:9216
	v_add_u32_e32 v0, 0x1ec00, v231
	ds_write_b128 v0, v[52:55]
	ds_write_b128 v0, v[56:59] offset:9216
	v_mov_b32_e32 v251, 0xf149f2ca
	v_mov_b32_e32 v252, 0x3db504f3
	v_mov_b32_e32 v254, 0x3fb8aa3b
	v_add_u32_e32 v156, s67, v240
	v_add_u32_e32 v157, s67, v241
	v_add_u32_e32 v158, s67, v242
	v_add_u32_e32 v159, s67, v243
	v_add_u32_e32 v160, s67, v244
	v_add_u32_e32 v161, s67, v245
	v_add_u32_e32 v162, s67, v246
	v_add_u32_e32 v163, s67, v247
	v_mov_b32_e32 v248, 0xff61b1e6
	ds_read_b32 v164, v156 offset:0
	ds_read_b32 v165, v157 offset:0
	ds_read_b32 v166, v158 offset:0
	ds_read_b32 v167, v159 offset:0
	ds_read_b32 v168, v160 offset:0
	ds_read_b32 v169, v161 offset:0
	ds_read_b32 v170, v162 offset:0
	ds_read_b32 v171, v163 offset:0
	s_waitcnt lgkmcnt(0)
	ds_read_b32 v172, v156 offset:124
	ds_read_b32 v173, v157 offset:124
	ds_read_b32 v174, v158 offset:124
	ds_read_b32 v175, v159 offset:124
	ds_read_b32 v176, v160 offset:124
	ds_read_b32 v177, v161 offset:124
	ds_read_b32 v178, v162 offset:124
	ds_read_b32 v179, v163 offset:124
	v_pk_fma_f32 v[92:93], v[92:93], v[252:253], v[164:165] op_sel_hi:[1,0,1]
	v_pk_fma_f32 v[94:95], v[94:95], v[252:253], v[166:167] op_sel_hi:[1,0,1]
	v_pk_fma_f32 v[96:97], v[96:97], v[252:253], v[168:169] op_sel_hi:[1,0,1]
	v_pk_fma_f32 v[98:99], v[98:99], v[252:253], v[170:171] op_sel_hi:[1,0,1]
	v_cndmask_b32_e64 v92, v251, v92, s[4:5]
	v_cndmask_b32_e64 v93, v251, v93, s[6:7]
	v_cndmask_b32_e64 v94, v251, v94, s[8:9]
	v_cndmask_b32_e64 v95, v251, v95, s[10:11]
	v_cndmask_b32_e64 v96, v251, v96, s[12:13]
	v_cndmask_b32_e64 v97, v251, v97, s[14:15]
	v_cndmask_b32_e64 v98, v251, v98, s[16:17]
	v_cndmask_b32_e64 v99, v251, v99, s[18:19]
	v_max3_f32 v248, v248, v92, v93
	v_max3_f32 v248, v248, v94, v95
	v_max3_f32 v248, v248, v96, v97
	v_max3_f32 v248, v248, v98, v99
	s_waitcnt lgkmcnt(0)
	ds_read_b32 v164, v156 offset:248
	ds_read_b32 v165, v157 offset:248
	ds_read_b32 v166, v158 offset:248
	ds_read_b32 v167, v159 offset:248
	ds_read_b32 v168, v160 offset:248
	ds_read_b32 v169, v161 offset:248
	ds_read_b32 v170, v162 offset:248
	ds_read_b32 v171, v163 offset:248
	v_pk_fma_f32 v[100:101], v[100:101], v[252:253], v[172:173] op_sel_hi:[1,0,1]
	v_pk_fma_f32 v[102:103], v[102:103], v[252:253], v[174:175] op_sel_hi:[1,0,1]
	v_pk_fma_f32 v[104:105], v[104:105], v[252:253], v[176:177] op_sel_hi:[1,0,1]
	v_pk_fma_f32 v[106:107], v[106:107], v[252:253], v[178:179] op_sel_hi:[1,0,1]
	v_cndmask_b32_e64 v100, v251, v100, s[4:5]
	v_cndmask_b32_e64 v101, v251, v101, s[6:7]
	v_cndmask_b32_e64 v102, v251, v102, s[8:9]
	v_cndmask_b32_e64 v103, v251, v103, s[10:11]
	v_cndmask_b32_e64 v104, v251, v104, s[12:13]
	v_cndmask_b32_e64 v105, v251, v105, s[14:15]
	v_cndmask_b32_e64 v106, v251, v106, s[16:17]
	v_cndmask_b32_e64 v107, v251, v107, s[18:19]
	v_max3_f32 v248, v248, v100, v101
	v_max3_f32 v248, v248, v102, v103
	v_max3_f32 v248, v248, v104, v105
	v_max3_f32 v248, v248, v106, v107
	s_waitcnt lgkmcnt(0)
	ds_read_b32 v172, v156 offset:372
	ds_read_b32 v173, v157 offset:372
	ds_read_b32 v174, v158 offset:372
	ds_read_b32 v175, v159 offset:372
	ds_read_b32 v176, v160 offset:372
	ds_read_b32 v177, v161 offset:372
	ds_read_b32 v178, v162 offset:372
	ds_read_b32 v179, v163 offset:372
	v_pk_fma_f32 v[108:109], v[108:109], v[252:253], v[164:165] op_sel_hi:[1,0,1]
	v_pk_fma_f32 v[110:111], v[110:111], v[252:253], v[166:167] op_sel_hi:[1,0,1]
	v_pk_fma_f32 v[112:113], v[112:113], v[252:253], v[168:169] op_sel_hi:[1,0,1]
	v_pk_fma_f32 v[114:115], v[114:115], v[252:253], v[170:171] op_sel_hi:[1,0,1]
	v_cndmask_b32_e64 v108, v251, v108, s[4:5]
	v_cndmask_b32_e64 v109, v251, v109, s[6:7]
	v_cndmask_b32_e64 v110, v251, v110, s[8:9]
	v_cndmask_b32_e64 v111, v251, v111, s[10:11]
	v_cndmask_b32_e64 v112, v251, v112, s[12:13]
	v_cndmask_b32_e64 v113, v251, v113, s[14:15]
	v_cndmask_b32_e64 v114, v251, v114, s[16:17]
	v_cndmask_b32_e64 v115, v251, v115, s[18:19]
	v_max3_f32 v248, v248, v108, v109
	v_max3_f32 v248, v248, v110, v111
	v_max3_f32 v248, v248, v112, v113
	v_max3_f32 v248, v248, v114, v115
	s_waitcnt lgkmcnt(0)
	ds_read_b32 v164, v156 offset:496
	ds_read_b32 v165, v157 offset:496
	ds_read_b32 v166, v158 offset:496
	ds_read_b32 v167, v159 offset:496
	ds_read_b32 v168, v160 offset:496
	ds_read_b32 v169, v161 offset:496
	ds_read_b32 v170, v162 offset:496
	ds_read_b32 v171, v163 offset:496
	v_pk_fma_f32 v[116:117], v[116:117], v[252:253], v[172:173] op_sel_hi:[1,0,1]
	v_pk_fma_f32 v[118:119], v[118:119], v[252:253], v[174:175] op_sel_hi:[1,0,1]
	v_pk_fma_f32 v[120:121], v[120:121], v[252:253], v[176:177] op_sel_hi:[1,0,1]
	v_pk_fma_f32 v[122:123], v[122:123], v[252:253], v[178:179] op_sel_hi:[1,0,1]
	v_cndmask_b32_e64 v116, v251, v116, s[4:5]
	v_cndmask_b32_e64 v117, v251, v117, s[6:7]
	v_cndmask_b32_e64 v118, v251, v118, s[8:9]
	v_cndmask_b32_e64 v119, v251, v119, s[10:11]
	v_cndmask_b32_e64 v120, v251, v120, s[12:13]
	v_cndmask_b32_e64 v121, v251, v121, s[14:15]
	v_cndmask_b32_e64 v122, v251, v122, s[16:17]
	v_cndmask_b32_e64 v123, v251, v123, s[18:19]
	v_max3_f32 v248, v248, v116, v117
	v_max3_f32 v248, v248, v118, v119
	v_max3_f32 v248, v248, v120, v121
	v_max3_f32 v248, v248, v122, v123
	s_waitcnt lgkmcnt(0)
	ds_read_b32 v172, v156 offset:620
	ds_read_b32 v173, v157 offset:620
	ds_read_b32 v174, v158 offset:620
	ds_read_b32 v175, v159 offset:620
	ds_read_b32 v176, v160 offset:620
	ds_read_b32 v177, v161 offset:620
	ds_read_b32 v178, v162 offset:620
	ds_read_b32 v179, v163 offset:620
	v_pk_fma_f32 v[124:125], v[124:125], v[252:253], v[164:165] op_sel_hi:[1,0,1]
	v_pk_fma_f32 v[126:127], v[126:127], v[252:253], v[166:167] op_sel_hi:[1,0,1]
	v_pk_fma_f32 v[128:129], v[128:129], v[252:253], v[168:169] op_sel_hi:[1,0,1]
	v_pk_fma_f32 v[130:131], v[130:131], v[252:253], v[170:171] op_sel_hi:[1,0,1]
	v_cndmask_b32_e64 v124, v251, v124, s[4:5]
	v_cndmask_b32_e64 v125, v251, v125, s[6:7]
	v_cndmask_b32_e64 v126, v251, v126, s[8:9]
	v_cndmask_b32_e64 v127, v251, v127, s[10:11]
	v_cndmask_b32_e64 v128, v251, v128, s[12:13]
	v_cndmask_b32_e64 v129, v251, v129, s[14:15]
	v_cndmask_b32_e64 v130, v251, v130, s[16:17]
	v_cndmask_b32_e64 v131, v251, v131, s[18:19]
	v_max3_f32 v248, v248, v124, v125
	v_max3_f32 v248, v248, v126, v127
	v_max3_f32 v248, v248, v128, v129
	v_max3_f32 v248, v248, v130, v131
	s_waitcnt lgkmcnt(0)
	ds_read_b32 v164, v156 offset:744
	ds_read_b32 v165, v157 offset:744
	ds_read_b32 v166, v158 offset:744
	ds_read_b32 v167, v159 offset:744
	ds_read_b32 v168, v160 offset:744
	ds_read_b32 v169, v161 offset:744
	ds_read_b32 v170, v162 offset:744
	ds_read_b32 v171, v163 offset:744
	v_pk_fma_f32 v[132:133], v[132:133], v[252:253], v[172:173] op_sel_hi:[1,0,1]
	v_pk_fma_f32 v[134:135], v[134:135], v[252:253], v[174:175] op_sel_hi:[1,0,1]
	v_pk_fma_f32 v[136:137], v[136:137], v[252:253], v[176:177] op_sel_hi:[1,0,1]
	v_pk_fma_f32 v[138:139], v[138:139], v[252:253], v[178:179] op_sel_hi:[1,0,1]
	v_cndmask_b32_e64 v132, v251, v132, s[4:5]
	v_cndmask_b32_e64 v133, v251, v133, s[6:7]
	v_cndmask_b32_e64 v134, v251, v134, s[8:9]
	v_cndmask_b32_e64 v135, v251, v135, s[10:11]
	v_cndmask_b32_e64 v136, v251, v136, s[12:13]
	v_cndmask_b32_e64 v137, v251, v137, s[14:15]
	v_cndmask_b32_e64 v138, v251, v138, s[16:17]
	v_cndmask_b32_e64 v139, v251, v139, s[18:19]
	v_max3_f32 v248, v248, v132, v133
	v_max3_f32 v248, v248, v134, v135
	v_max3_f32 v248, v248, v136, v137
	v_max3_f32 v248, v248, v138, v139
	s_waitcnt lgkmcnt(0)
	ds_read_b32 v172, v156 offset:868
	ds_read_b32 v173, v157 offset:868
	ds_read_b32 v174, v158 offset:868
	ds_read_b32 v175, v159 offset:868
	ds_read_b32 v176, v160 offset:868
	ds_read_b32 v177, v161 offset:868
	ds_read_b32 v178, v162 offset:868
	ds_read_b32 v179, v163 offset:868
	v_pk_fma_f32 v[140:141], v[140:141], v[252:253], v[164:165] op_sel_hi:[1,0,1]
	v_pk_fma_f32 v[142:143], v[142:143], v[252:253], v[166:167] op_sel_hi:[1,0,1]
	v_pk_fma_f32 v[144:145], v[144:145], v[252:253], v[168:169] op_sel_hi:[1,0,1]
	v_pk_fma_f32 v[146:147], v[146:147], v[252:253], v[170:171] op_sel_hi:[1,0,1]
	v_cndmask_b32_e64 v140, v251, v140, s[4:5]
	v_cndmask_b32_e64 v141, v251, v141, s[6:7]
	v_cndmask_b32_e64 v142, v251, v142, s[8:9]
	v_cndmask_b32_e64 v143, v251, v143, s[10:11]
	v_cndmask_b32_e64 v144, v251, v144, s[12:13]
	v_cndmask_b32_e64 v145, v251, v145, s[14:15]
	v_cndmask_b32_e64 v146, v251, v146, s[16:17]
	v_cndmask_b32_e64 v147, v251, v147, s[18:19]
	v_max3_f32 v248, v248, v140, v141
	v_max3_f32 v248, v248, v142, v143
	v_max3_f32 v248, v248, v144, v145
	v_max3_f32 v248, v248, v146, v147
	s_waitcnt lgkmcnt(0)
	v_pk_fma_f32 v[148:149], v[148:149], v[252:253], v[172:173] op_sel_hi:[1,0,1]
	v_pk_fma_f32 v[150:151], v[150:151], v[252:253], v[174:175] op_sel_hi:[1,0,1]
	v_pk_fma_f32 v[152:153], v[152:153], v[252:253], v[176:177] op_sel_hi:[1,0,1]
	v_pk_fma_f32 v[154:155], v[154:155], v[252:253], v[178:179] op_sel_hi:[1,0,1]
	v_cndmask_b32_e64 v148, v251, v148, s[4:5]
	v_cndmask_b32_e64 v149, v251, v149, s[6:7]
	v_cndmask_b32_e64 v150, v251, v150, s[8:9]
	v_cndmask_b32_e64 v151, v251, v151, s[10:11]
	v_cndmask_b32_e64 v152, v251, v152, s[12:13]
	v_cndmask_b32_e64 v153, v251, v153, s[14:15]
	v_cndmask_b32_e64 v154, v251, v154, s[16:17]
	v_cndmask_b32_e64 v155, v251, v155, s[18:19]
	v_max3_f32 v248, v248, v148, v149
	v_max3_f32 v248, v248, v150, v151
	v_max3_f32 v248, v248, v152, v153
	v_max3_f32 v248, v248, v154, v155
	v_mov_b32_e32 v0, v248
	s_nop 1
	v_permlane16_swap_b32 v0, v248
	v_max_f32_e32 v248, v248, v0
	v_mov_b32_e32 v0, v248
	s_nop 1
	v_permlane32_swap_b32 v0, v248
	v_max_f32_e32 v248, v248, v0
	s_waitcnt lgkmcnt(0)
	v_mov_b32_e32 v2, 0
	v_mov_b32_e32 v3, 0
	v_pk_add_f32 v[92:93], v[92:93], v[248:249] op_sel_hi:[1,0] neg_lo:[0,1] neg_hi:[0,1]
	v_pk_add_f32 v[94:95], v[94:95], v[248:249] op_sel_hi:[1,0] neg_lo:[0,1] neg_hi:[0,1]
	v_pk_add_f32 v[96:97], v[96:97], v[248:249] op_sel_hi:[1,0] neg_lo:[0,1] neg_hi:[0,1]
	v_pk_add_f32 v[98:99], v[98:99], v[248:249] op_sel_hi:[1,0] neg_lo:[0,1] neg_hi:[0,1]
	v_pk_mul_f32 v[92:93], v[92:93], v[254:255] op_sel_hi:[1,0]
	v_pk_mul_f32 v[94:95], v[94:95], v[254:255] op_sel_hi:[1,0]
	v_pk_mul_f32 v[96:97], v[96:97], v[254:255] op_sel_hi:[1,0]
	v_pk_mul_f32 v[98:99], v[98:99], v[254:255] op_sel_hi:[1,0]
	v_exp_f32_e32 v92, v92
	v_exp_f32_e32 v93, v93
	v_exp_f32_e32 v94, v94
	v_exp_f32_e32 v95, v95
	v_exp_f32_e32 v96, v96
	v_exp_f32_e32 v97, v97
	v_exp_f32_e32 v98, v98
	v_exp_f32_e32 v99, v99
	s_nop 0
	v_pk_add_f32 v[2:3], v[2:3], v[92:93]
	v_pk_add_f32 v[2:3], v[2:3], v[94:95]
	v_pk_add_f32 v[2:3], v[2:3], v[96:97]
	v_pk_add_f32 v[2:3], v[2:3], v[98:99]
	s_barrier
	s_add_i32 s30, s20, s46
	s_cmpk_lt_i32 s30, 0x200
	s_cbranch_scc0 .Latt_nopf1
	s_and_b32 s69, s30, 7
	s_lshr_b32 s76, s30, 8
	s_lshl_b32 s69, s69, 1
	s_add_i32 s69, s69, s76
	s_lshl_b32 s69, s69, 12
	s_bfe_u32 s76, s30, 0x50003
	s_lshl_b32 s76, s76, 1
	s_add_i32 s77, s76, -4
	s_max_i32 s77, s77, 0
	s_min_i32 s77, s77, 56
	s_add_i32 s83, s76, -3
	s_max_i32 s83, s83, 0
	s_min_i32 s83, s83, 56
	s_add_i32 s83, s83, 8
	s_sub_i32 s83, s83, s77
	s_add_i32 s76, s76, s88
	s_lshl_b32 s77, s77, 6
	s_add_i32 s77, s77, s69
	s_lshl_b32 s77, s77, 8
	s_add_u32 s34, s50, s77
	s_addc_u32 s35, s51, 0
	s_add_u32 s34, s34, 0xe200000
	s_addc_u32 s35, s35, 0
	s_lshl_b32 s76, s76, 6
	s_add_i32 s76, s76, s69
	s_lshl_b32 s77, s92, 4
	s_add_i32 s76, s76, s77
	s_lshl_b32 s76, s76, 8
	s_add_u32 s36, s50, s76
	s_addc_u32 s37, s51, 0
	s_add_u32 s36, s36, 0xd200000
	s_addc_u32 s37, s37, 0
	global_load_dwordx4 v[76:79], v235, s[36:37] offset:0
	global_load_dwordx4 v[80:83], v235, s[36:37] offset:64
	global_load_dwordx4 v[84:87], v235, s[36:37] offset:128
	global_load_dwordx4 v[88:91], v235, s[36:37] offset:192
	global_load_dwordx4 v[4:7], v226, s[34:35]
	global_load_dwordx4 v[8:11], v227, s[34:35]
	s_add_u32 s34, s34, 0x4000
	s_addc_u32 s35, s35, 0
	global_load_dwordx4 v[12:15], v226, s[34:35]
	global_load_dwordx4 v[16:19], v227, s[34:35]
	s_add_u32 s34, s34, 0x4000
	s_addc_u32 s35, s35, 0
	global_load_dwordx4 v[20:23], v226, s[34:35]
	global_load_dwordx4 v[24:27], v227, s[34:35]
	s_add_u32 s34, s34, 0x4000
	s_addc_u32 s35, s35, 0
	global_load_dwordx4 v[28:31], v226, s[34:35]
	global_load_dwordx4 v[32:35], v227, s[34:35]
	s_add_u32 s34, s34, 0x4000
	s_addc_u32 s35, s35, 0
	global_load_dwordx4 v[36:39], v226, s[34:35]
	global_load_dwordx4 v[40:43], v227, s[34:35]
	s_add_u32 s34, s34, 0x4000
	s_addc_u32 s35, s35, 0
	global_load_dwordx4 v[44:47], v226, s[34:35]
	global_load_dwordx4 v[48:51], v227, s[34:35]
	s_add_u32 s34, s34, 0x4000
	s_addc_u32 s35, s35, 0
	global_load_dwordx4 v[52:55], v226, s[34:35]
	global_load_dwordx4 v[56:59], v227, s[34:35]
	s_add_u32 s34, s34, 0x4000
	s_addc_u32 s35, s35, 0

.Latt_p6b_skip:
	v_cvt_pk_bf16_f32 v220, v148, v149
	v_cvt_pk_bf16_f32 v221, v150, v151
	v_cvt_pk_bf16_f32 v222, v152, v153
	v_cvt_pk_bf16_f32 v223, v154, v155
	s_add_i32 s30, s27, 7
	s_add_i32 s31, s30, -7
	s_cmp_lt_i32 s30, 7
	s_cselect_b32 s30, s30, s31
	s_mul_i32 s30, s30, 0x4800
	s_add_i32 s30, s30, 0x3c00
	v_add_u32_e32 v0, s30, v233
	ds_read_b128 v[156:159], v0 offset:0
	ds_read_b128 v[160:163], v0 offset:2304
	ds_read_b128 v[164:167], v0 offset:4608
	ds_read_b128 v[168:171], v0 offset:6912
	ds_read_b128 v[172:175], v0 offset:9216
	ds_read_b128 v[176:179], v0 offset:11520
	ds_read_b128 v[180:183], v0 offset:13824
	ds_read_b128 v[184:187], v0 offset:16128
	s_waitcnt lgkmcnt(7)
	v_mfma_f32_16x16x32_bf16 v[188:191], v[156:159], v[220:223], v[188:191]
	s_waitcnt lgkmcnt(6)
	v_mfma_f32_16x16x32_bf16 v[192:195], v[160:163], v[220:223], v[192:195]
	s_waitcnt lgkmcnt(5)
	v_mfma_f32_16x16x32_bf16 v[196:199], v[164:167], v[220:223], v[196:199]
	s_waitcnt lgkmcnt(4)
	v_mfma_f32_16x16x32_bf16 v[200:203], v[168:171], v[220:223], v[200:203]
	s_waitcnt lgkmcnt(3)
	v_mfma_f32_16x16x32_bf16 v[204:207], v[172:175], v[220:223], v[204:207]
	s_waitcnt lgkmcnt(2)
	v_mfma_f32_16x16x32_bf16 v[208:211], v[176:179], v[220:223], v[208:211]
	s_waitcnt lgkmcnt(1)
	v_mfma_f32_16x16x32_bf16 v[212:215], v[180:183], v[220:223], v[212:215]
	s_waitcnt lgkmcnt(0)
	v_mfma_f32_16x16x32_bf16 v[216:219], v[184:187], v[220:223], v[216:219]
	v_add_f32_e32 v249, v2, v3
	v_mov_b32_e32 v0, v249
	s_nop 1
	v_permlane16_swap_b32 v0, v249
	v_add_f32_e32 v249, v249, v0
	v_mov_b32_e32 v0, v249
	s_nop 1
	v_permlane32_swap_b32 v0, v249
	v_add_f32_e32 v249, v249, v0
	v_div_scale_f32 v252, s[44:45], v249, v249, 1.0
	v_rcp_f32_e32 v253, v252
	v_div_scale_f32 v254, vcc, 1.0, v249, 1.0
	s_nop 0
	v_fma_f32 v255, -v252, v253, 1.0
	v_fmac_f32_e32 v253, v255, v253
	v_mul_f32_e32 v255, v254, v253
	v_fma_f32 v248, -v252, v255, v254
	v_fmac_f32_e32 v255, v248, v253
	v_fma_f32 v252, -v252, v255, v254
	v_div_fmas_f32 v252, v252, v253, v255
	v_div_fixup_f32 v252, v252, v249, 1.0
	s_nop 7
	v_pk_mul_f32 v[188:189], v[188:189], v[252:253] op_sel_hi:[1,0]
	v_pk_mul_f32 v[190:191], v[190:191], v[252:253] op_sel_hi:[1,0]
	v_pk_mul_f32 v[192:193], v[192:193], v[252:253] op_sel_hi:[1,0]
	v_pk_mul_f32 v[194:195], v[194:195], v[252:253] op_sel_hi:[1,0]
	v_pk_mul_f32 v[196:197], v[196:197], v[252:253] op_sel_hi:[1,0]
	v_pk_mul_f32 v[198:199], v[198:199], v[252:253] op_sel_hi:[1,0]
	v_pk_mul_f32 v[200:201], v[200:201], v[252:253] op_sel_hi:[1,0]
	v_pk_mul_f32 v[202:203], v[202:203], v[252:253] op_sel_hi:[1,0]
	v_pk_mul_f32 v[204:205], v[204:205], v[252:253] op_sel_hi:[1,0]
	v_pk_mul_f32 v[206:207], v[206:207], v[252:253] op_sel_hi:[1,0]
	v_pk_mul_f32 v[208:209], v[208:209], v[252:253] op_sel_hi:[1,0]
	v_pk_mul_f32 v[210:211], v[210:211], v[252:253] op_sel_hi:[1,0]
	v_pk_mul_f32 v[212:213], v[212:213], v[252:253] op_sel_hi:[1,0]
	v_pk_mul_f32 v[214:215], v[214:215], v[252:253] op_sel_hi:[1,0]
	v_pk_mul_f32 v[216:217], v[216:217], v[252:253] op_sel_hi:[1,0]
	v_pk_mul_f32 v[218:219], v[218:219], v[252:253] op_sel_hi:[1,0]
	v_pk_mul_f32 v[254:255], v[188:189], v[188:189]
	v_pk_fma_f32 v[254:255], v[190:191], v[190:191], v[254:255]
	v_pk_fma_f32 v[254:255], v[192:193], v[192:193], v[254:255]
	v_pk_fma_f32 v[254:255], v[194:195], v[194:195], v[254:255]
	v_pk_fma_f32 v[254:255], v[196:197], v[196:197], v[254:255]
	v_pk_fma_f32 v[254:255], v[198:199], v[198:199], v[254:255]
	v_pk_fma_f32 v[254:255], v[200:201], v[200:201], v[254:255]
	v_pk_fma_f32 v[254:255], v[202:203], v[202:203], v[254:255]
	v_pk_fma_f32 v[254:255], v[204:205], v[204:205], v[254:255]
	v_pk_fma_f32 v[254:255], v[206:207], v[206:207], v[254:255]
	v_pk_fma_f32 v[254:255], v[208:209], v[208:209], v[254:255]
	v_pk_fma_f32 v[254:255], v[210:211], v[210:211], v[254:255]
	v_pk_fma_f32 v[254:255], v[212:213], v[212:213], v[254:255]
	v_pk_fma_f32 v[254:255], v[214:215], v[214:215], v[254:255]
	v_pk_fma_f32 v[254:255], v[216:217], v[216:217], v[254:255]
	v_pk_fma_f32 v[254:255], v[218:219], v[218:219], v[254:255]
	v_add_f32_e32 v254, v254, v255
	v_mov_b32_e32 v253, v254
	s_nop 1
	v_permlane16_swap_b32 v253, v254
	v_add_f32_e32 v254, v254, v253
	v_mov_b32_e32 v253, v254
	s_nop 1
	v_permlane32_swap_b32 v253, v254
	v_add_f32_e32 v254, v254, v253
	v_mov_b32_e32 v253, 0x358637bd
	s_mov_b32 s30, 0x800000
	v_fmamk_f32 v254, v254, 0x3c000000, v253
	v_mul_f32_e32 v253, 0x4b800000, v254
	v_cmp_gt_f32_e32 vcc, s30, v254
	s_nop 1
	v_cndmask_b32_e32 v254, v254, v253, vcc
	v_rsq_f32_e32 v254, v254
	s_nop 0
	v_mul_f32_e32 v253, 0x45800000, v254
	v_cndmask_b32_e32 v254, v254, v253, vcc
	s_add_i32 s30, s20, s46
	s_cmpk_lt_i32 s30, 0x200
	s_cbranch_scc0 .Latt_nopf4
	s_waitcnt vmcnt(2)
	s_branch .Latt_gn_ok

.LBB0_963:
	v_readlane_b32 s4, v250, 7
	s_and_b32 s8, s4, 32
	v_add_u32_e32 v148, s8, v148
	v_ashrrev_i32_e32 v151, 5, v148
	v_lshlrev_b32_e32 v148, 10, v151
	s_add_i32 s8, s86, 0
	s_lshl_b32 s15, s92, 14
	v_add3_u32 v150, s8, v193, v148
	s_and_b32 s17, s15, 0x8000
	v_add_u32_e32 v160, s17, v150
	ds_read_b128 v[152:155], v160
	s_mov_b32 s18, 0xc3e00000
	v_mov_b32_e32 v148, 0
	s_waitcnt lgkmcnt(0)
	v_lshlrev_b32_e32 v156, 16, v152
	v_and_b32_e32 v157, 0xffff0000, v152
	v_lshlrev_b32_e32 v152, 16, v153
	v_and_b32_e32 v153, 0xffff0000, v153
	v_lshlrev_b32_e32 v158, 16, v154
	v_and_b32_e32 v159, 0xffff0000, v154
	v_lshlrev_b32_e32 v154, 16, v155
	v_and_b32_e32 v155, 0xffff0000, v155
	v_pk_add_f32 v[134:135], v[134:135], v[152:153]
	v_pk_add_f32 v[152:153], v[132:133], v[156:157]
	v_pk_add_f32 v[156:157], v[130:131], v[154:155]
	v_pk_add_f32 v[154:155], v[128:129], v[158:159]
	v_mul_f32_e32 v128, 0x41800000, v152
	v_mov_b32_e32 v129, 0x43e00000
	v_mul_f32_e32 v130, 0x41800000, v153
	v_med3_f32 v128, v128, s18, v129
	v_med3_f32 v131, v130, s18, v129
	v_mov_b32_e32 v130, 0
	v_cvt_pk_fp8_f32 v130, v128, v131
	v_mul_f32_e32 v128, 0x41800000, v134
	v_mul_f32_e32 v131, 0x41800000, v135
	v_med3_f32 v128, v128, s18, v129
	v_med3_f32 v131, v131, s18, v129
	v_cvt_pk_fp8_f32 v130, v128, v131 op_sel:[0,0,1]
	v_mul_f32_e32 v128, 0x41800000, v154
	v_mul_f32_e32 v131, 0x41800000, v155
	v_med3_f32 v128, v128, s18, v129
	v_med3_f32 v132, v131, s18, v129
	v_mov_b32_e32 v131, 0
	v_cvt_pk_fp8_f32 v131, v128, v132
	v_mul_f32_e32 v128, 0x41800000, v156
	v_mul_f32_e32 v132, 0x41800000, v157
	v_med3_f32 v128, v128, s18, v129
	v_med3_f32 v132, v132, s18, v129
	v_cvt_pk_fp8_f32 v131, v128, v132 op_sel:[0,0,1]
	v_lshlrev_b64 v[132:133], 11, v[146:147]
	v_lshl_add_u64 v[132:133], s[12:13], 0, v[132:133]
	v_lshl_add_u64 v[158:159], v[132:133], 0, v[144:145]
	global_store_dwordx2 v[158:159], v[130:131], off
	v_cvt_pk_bf16_f32 v130, v152, v153
	v_cvt_pk_bf16_f32 v131, v134, v135
	v_mul_f32_e32 v128, v153, v153
	v_mul_f32_e32 v135, v135, v135
	v_fmac_f32_e32 v128, v152, v152
	v_fmac_f32_e32 v135, v134, v134
	v_add_f32_e32 v134, v128, v135
	v_add_u32_e32 v128, 0x10000, v150
	v_mul_f32_e32 v135, v155, v155
	v_add_u32_e32 v161, s17, v128
	v_cvt_pk_bf16_f32 v132, v154, v155
	v_cvt_pk_bf16_f32 v133, v156, v157
	v_fmac_f32_e32 v135, v154, v154
	ds_read_b128 v[152:155], v161
	v_add_f32_e32 v134, v135, v134
	v_mul_f32_e32 v135, v157, v157
	v_fmac_f32_e32 v135, v156, v156
	v_add_f32_e32 v162, v135, v134
	s_waitcnt lgkmcnt(0)
	v_lshlrev_b32_e32 v134, 16, v152
	v_and_b32_e32 v135, 0xffff0000, v152
	v_lshlrev_b32_e32 v152, 16, v153
	v_and_b32_e32 v153, 0xffff0000, v153
	v_lshlrev_b32_e32 v156, 16, v154
	v_and_b32_e32 v157, 0xffff0000, v154
	v_pk_add_f32 v[120:121], v[120:121], v[134:135]
	v_pk_add_f32 v[122:123], v[122:123], v[152:153]
	v_pk_add_f32 v[152:153], v[116:117], v[156:157]
	v_mul_f32_e32 v116, 0x41800000, v120
	v_mul_f32_e32 v117, 0x41800000, v121
	v_med3_f32 v116, v116, s18, v129
	v_med3_f32 v117, v117, s18, v129
	v_cvt_pk_fp8_f32 v148, v116, v117
	v_mul_f32_e32 v116, 0x41800000, v122
	v_mul_f32_e32 v117, 0x41800000, v123
	v_med3_f32 v116, v116, s18, v129
	v_med3_f32 v117, v117, s18, v129
	v_cvt_pk_fp8_f32 v148, v116, v117 op_sel:[0,0,1]
	v_mul_f32_e32 v116, 0x41800000, v152
	v_mul_f32_e32 v117, 0x41800000, v153
	v_med3_f32 v116, v116, s18, v129
	v_med3_f32 v117, v117, s18, v129
	v_lshlrev_b32_e32 v154, 16, v155
	v_and_b32_e32 v155, 0xffff0000, v155
	v_cvt_pk_fp8_f32 v149, v116, v117
	v_pk_add_f32 v[134:135], v[118:119], v[154:155]
	ds_write_b128 v160, v[130:133]
	v_mul_f32_e32 v116, 0x41800000, v134
	v_mul_f32_e32 v117, 0x41800000, v135
	v_med3_f32 v116, v116, s18, v129
	v_med3_f32 v117, v117, s18, v129
	v_cvt_pk_fp8_f32 v149, v116, v117 op_sel:[0,0,1]
	v_mul_f32_e32 v116, v121, v121
	v_mul_f32_e32 v117, v123, v123
	v_fmac_f32_e32 v116, v120, v120
	v_fmac_f32_e32 v117, v122, v122
	v_add_f32_e32 v116, v116, v117
	v_mul_f32_e32 v117, v153, v153
	v_fmac_f32_e32 v117, v152, v152
	v_add_f32_e32 v116, v117, v116
	v_mul_f32_e32 v117, v135, v135
	v_fmac_f32_e32 v117, v134, v134
	v_add_f32_e32 v116, v117, v116
	v_mbcnt_hi_u32_b32 v117, -1, v225
	v_and_b32_e32 v119, 64, v117
	v_xor_b32_e32 v118, 16, v117
	v_add_u32_e32 v119, 64, v119
	v_cmp_lt_i32_e32 vcc, v118, v119
	v_add_f32_e32 v116, v162, v116
	global_store_dwordx2 v[158:159], v[148:149], off offset:128
	v_cndmask_b32_e32 v118, v117, v118, vcc
	v_lshlrev_b32_e32 v118, 2, v118
	v_mov_b32_e32 v154, v116
	s_nop 1
	v_permlane16_swap_b32 v154, v116
	v_cvt_pk_bf16_f32 v120, v120, v121
	v_xor_b32_e32 v121, 32, v117
	v_cmp_lt_i32_e64 s[8:9], v121, v119
	v_cmp_gt_u32_e32 vcc, 16, v189
	s_waitcnt lgkmcnt(0)
	v_add_f32_e32 v116, v116, v154
	v_cndmask_b32_e64 v117, v117, v121, s[8:9]
	v_lshlrev_b32_e32 v119, 2, v117
	v_mov_b32_e32 v117, v116
	s_nop 1
	v_permlane32_swap_b32 v117, v116
	v_cvt_pk_bf16_f32 v121, v122, v123
	v_cvt_pk_bf16_f32 v122, v152, v153
	v_cvt_pk_bf16_f32 v123, v134, v135
	ds_write_b128 v161, v[120:123]
	s_and_saveexec_b64 s[8:9], vcc
	s_cbranch_execz .LBB0_965
	v_lshl_add_u64 v[120:121], v[146:147], 2, s[10:11]
	s_waitcnt lgkmcnt(0)
	v_add_f32_e32 v116, v116, v117
	global_atomic_add_f32 v[120:121], v116, off
.LBB0_965:
	s_or_b64 exec, exec, s[8:9]
	s_or_b32 s8, s87, 16
	v_or_b32_e32 v116, s8, v192
	s_waitcnt lgkmcnt(0)
	v_lshlrev_b32_e32 v117, 6, v116
	v_lshlrev_b32_e32 v116, 2, v116
	s_lshr_b32 s8, s8, 3
	v_and_b32_e32 v117, 0x3c0, v117
	v_and_b32_e32 v116, 32, v116
	v_add_lshl_u32 v120, v151, s8, 10
	v_bitop3_b32 v116, v117, v116, v191 bitop3:0x36
	v_add3_u32 v120, 0, v116, v120
	v_add_u32_e32 v121, s17, v120
	ds_read_b128 v[130:133], v121
	v_or_b32_e32 v116, 16, v146
	v_ashrrev_i32_e32 v117, 31, v116
	s_waitcnt lgkmcnt(0)
	v_lshlrev_b32_e32 v122, 16, v130
	v_and_b32_e32 v123, 0xffff0000, v130
	v_lshlrev_b32_e32 v134, 16, v132
	v_and_b32_e32 v135, 0xffff0000, v132
	v_lshlrev_b32_e32 v132, 16, v133
	v_and_b32_e32 v133, 0xffff0000, v133
	v_pk_add_f32 v[122:123], v[112:113], v[122:123]
	v_pk_add_f32 v[148:149], v[110:111], v[132:133]
	v_mul_f32_e32 v110, 0x41800000, v122
	v_med3_f32 v111, v110, s18, v129
	v_mul_f32_e32 v110, 0x41800000, v123
	v_med3_f32 v112, v110, s18, v129
	v_mov_b32_e32 v110, 0
	v_lshlrev_b32_e32 v130, 16, v131
	v_and_b32_e32 v131, 0xffff0000, v131
	v_cvt_pk_fp8_f32 v110, v111, v112
	v_pk_add_f32 v[114:115], v[114:115], v[130:131]
	v_pk_add_f32 v[108:109], v[108:109], v[134:135]
	v_mul_f32_e32 v111, 0x41800000, v114
	v_mul_f32_e32 v112, 0x41800000, v115
	v_med3_f32 v111, v111, s18, v129
	v_med3_f32 v112, v112, s18, v129
	v_cvt_pk_fp8_f32 v110, v111, v112 op_sel:[0,0,1]
	v_mul_f32_e32 v111, 0x41800000, v108
	v_med3_f32 v112, v111, s18, v129
	v_mul_f32_e32 v111, 0x41800000, v109
	v_med3_f32 v113, v111, s18, v129
	v_mov_b32_e32 v111, 0
	v_cvt_pk_fp8_f32 v111, v112, v113
	v_mul_f32_e32 v112, 0x41800000, v148
	v_mul_f32_e32 v113, 0x41800000, v149
	v_med3_f32 v112, v112, s18, v129
	v_med3_f32 v113, v113, s18, v129
	v_cvt_pk_fp8_f32 v111, v112, v113 op_sel:[0,0,1]
	v_lshlrev_b64 v[112:113], 11, v[116:117]
	v_lshl_add_u64 v[112:113], s[12:13], 0, v[112:113]
	v_lshl_add_u64 v[134:135], v[112:113], 0, v[144:145]
	global_store_dwordx2 v[134:135], v[110:111], off
	v_cvt_pk_bf16_f32 v110, v122, v123
	v_cvt_pk_bf16_f32 v111, v114, v115
	v_cvt_pk_bf16_f32 v112, v108, v109
	v_mul_f32_e32 v109, v109, v109
	v_fmac_f32_e32 v109, v108, v108
	v_add_u32_e32 v108, 0x10000, v120
	v_add_u32_e32 v147, s17, v108
	v_cvt_pk_bf16_f32 v113, v148, v149
	v_mul_f32_e32 v123, v123, v123
	v_mul_f32_e32 v115, v115, v115
	ds_read_b128 v[130:133], v147
	v_fmac_f32_e32 v123, v122, v122
	v_fmac_f32_e32 v115, v114, v114
	v_add_f32_e32 v114, v123, v115
	v_add_f32_e32 v109, v109, v114
	v_mul_f32_e32 v114, v149, v149
	v_fmac_f32_e32 v114, v148, v148
	v_add_f32_e32 v109, v114, v109
	s_waitcnt lgkmcnt(0)
	v_lshlrev_b32_e32 v114, 16, v130
	v_and_b32_e32 v115, 0xffff0000, v130
	v_lshlrev_b32_e32 v122, 16, v131
	v_and_b32_e32 v123, 0xffff0000, v131
	v_lshlrev_b32_e32 v130, 16, v132
	v_and_b32_e32 v131, 0xffff0000, v132
	v_pk_add_f32 v[100:101], v[100:101], v[114:115]
	v_lshlrev_b32_e32 v132, 16, v133
	v_and_b32_e32 v133, 0xffff0000, v133
	v_pk_add_f32 v[102:103], v[102:103], v[122:123]
	v_pk_add_f32 v[122:123], v[96:97], v[130:131]
	v_mul_f32_e32 v96, 0x41800000, v100
	v_mul_f32_e32 v97, 0x41800000, v101
	v_pk_add_f32 v[114:115], v[98:99], v[132:133]
	v_med3_f32 v96, v96, s18, v129
	v_med3_f32 v97, v97, s18, v129
	v_mov_b32_e32 v98, 0
	v_cvt_pk_fp8_f32 v98, v96, v97
	v_mul_f32_e32 v96, 0x41800000, v102
	v_mul_f32_e32 v97, 0x41800000, v103
	v_med3_f32 v96, v96, s18, v129
	v_med3_f32 v97, v97, s18, v129
	v_cvt_pk_fp8_f32 v98, v96, v97 op_sel:[0,0,1]
	v_mul_f32_e32 v96, 0x41800000, v122
	v_mul_f32_e32 v97, 0x41800000, v123
	v_med3_f32 v96, v96, s18, v129
	v_med3_f32 v97, v97, s18, v129
	v_mov_b32_e32 v99, 0
	v_cvt_pk_fp8_f32 v99, v96, v97
	v_mul_f32_e32 v96, 0x41800000, v114
	v_mul_f32_e32 v97, 0x41800000, v115
	v_med3_f32 v96, v96, s18, v129
	v_med3_f32 v97, v97, s18, v129
	v_cvt_pk_fp8_f32 v99, v96, v97 op_sel:[0,0,1]
	v_mul_f32_e32 v96, v101, v101
	v_mul_f32_e32 v97, v103, v103
	v_fmac_f32_e32 v96, v100, v100
	v_fmac_f32_e32 v97, v102, v102
	v_add_f32_e32 v96, v96, v97
	v_mul_f32_e32 v97, v123, v123
	v_fmac_f32_e32 v97, v122, v122
	v_add_f32_e32 v96, v97, v96
	v_mul_f32_e32 v97, v115, v115
	v_fmac_f32_e32 v97, v114, v114
	v_add_f32_e32 v96, v97, v96
	v_add_f32_e32 v96, v109, v96
	v_mov_b32_e32 v109, v96
	s_nop 1
	v_permlane16_swap_b32 v109, v96
	global_store_dwordx2 v[134:135], v[98:99], off offset:128
	v_mov_b32_e32 v97, 0
	ds_write_b128 v121, v[110:113]
	v_cvt_pk_bf16_f32 v100, v100, v101
	s_waitcnt lgkmcnt(0)
	v_add_f32_e32 v96, v96, v109
	v_mov_b32_e32 v98, v96
	s_nop 1
	v_permlane32_swap_b32 v98, v96
	v_cvt_pk_bf16_f32 v101, v102, v103
	v_cvt_pk_bf16_f32 v102, v122, v123
	v_cvt_pk_bf16_f32 v103, v114, v115
	ds_write_b128 v147, v[100:103]
	s_and_saveexec_b64 s[8:9], vcc
	s_cbranch_execz .LBB0_967
	v_lshl_add_u64 v[100:101], v[116:117], 2, s[10:11]
	s_waitcnt lgkmcnt(0)
	v_add_f32_e32 v96, v96, v98
	global_atomic_add_f32 v[100:101], v96, off
.LBB0_967:
	s_or_b64 exec, exec, s[8:9]
	s_or_b32 s8, s87, 32
	v_or_b32_e32 v96, s8, v192
	s_waitcnt lgkmcnt(0)
	v_lshlrev_b32_e32 v98, 6, v96
	v_lshlrev_b32_e32 v96, 2, v96
	s_lshr_b32 s8, s8, 3
	v_and_b32_e32 v98, 0x3c0, v98
	v_and_b32_e32 v96, 32, v96
	v_add_lshl_u32 v99, v151, s8, 10
	v_bitop3_b32 v96, v98, v96, v191 bitop3:0x36
	v_add3_u32 v100, 0, v96, v99
	v_add_u32_e32 v101, s17, v100
	ds_read_b128 v[110:113], v101
	v_or_b32_e32 v98, 32, v146
	v_ashrrev_i32_e32 v99, 31, v98
	v_mov_b32_e32 v96, 0
	s_waitcnt lgkmcnt(0)
	v_lshlrev_b32_e32 v102, 16, v110
	v_and_b32_e32 v103, 0xffff0000, v110
	v_lshlrev_b32_e32 v110, 16, v111
	v_and_b32_e32 v111, 0xffff0000, v111
	v_lshlrev_b32_e32 v114, 16, v112
	v_and_b32_e32 v115, 0xffff0000, v112
	v_lshlrev_b32_e32 v112, 16, v113
	v_and_b32_e32 v113, 0xffff0000, v113
	v_pk_add_f32 v[102:103], v[92:93], v[102:103]
	v_pk_add_f32 v[94:95], v[94:95], v[110:111]
	v_pk_add_f32 v[116:117], v[90:91], v[112:113]
	v_pk_add_f32 v[110:111], v[88:89], v[114:115]
	v_mul_f32_e32 v88, 0x41800000, v102
	v_mov_b32_e32 v89, 0x43e00000
	v_mul_f32_e32 v90, 0x41800000, v103
	v_med3_f32 v88, v88, s18, v89
	v_med3_f32 v91, v90, s18, v89
	v_mov_b32_e32 v90, 0
	v_cvt_pk_fp8_f32 v90, v88, v91
	v_mul_f32_e32 v88, 0x41800000, v94
	v_mul_f32_e32 v91, 0x41800000, v95
	v_med3_f32 v88, v88, s18, v89
	v_med3_f32 v91, v91, s18, v89
	v_cvt_pk_fp8_f32 v90, v88, v91 op_sel:[0,0,1]
	v_mul_f32_e32 v88, 0x41800000, v110
	v_mul_f32_e32 v91, 0x41800000, v111
	v_med3_f32 v88, v88, s18, v89
	v_med3_f32 v92, v91, s18, v89
	v_mov_b32_e32 v91, 0
	v_cvt_pk_fp8_f32 v91, v88, v92
	v_mul_f32_e32 v88, 0x41800000, v116
	v_mul_f32_e32 v92, 0x41800000, v117
	v_med3_f32 v88, v88, s18, v89
	v_med3_f32 v92, v92, s18, v89
	v_cvt_pk_fp8_f32 v91, v88, v92 op_sel:[0,0,1]
	v_lshlrev_b64 v[92:93], 11, v[98:99]
	v_lshl_add_u64 v[92:93], s[12:13], 0, v[92:93]
	v_lshl_add_u64 v[114:115], v[92:93], 0, v[144:145]
	global_store_dwordx2 v[114:115], v[90:91], off
	v_cvt_pk_bf16_f32 v90, v102, v103
	v_cvt_pk_bf16_f32 v91, v94, v95
	v_mul_f32_e32 v88, v103, v103
	v_mul_f32_e32 v95, v95, v95
	v_fmac_f32_e32 v88, v102, v102
	v_fmac_f32_e32 v95, v94, v94
	v_add_f32_e32 v94, v88, v95
	v_add_u32_e32 v88, 0x10000, v100
	v_mul_f32_e32 v95, v111, v111
	v_add_u32_e32 v109, s17, v88
	v_cvt_pk_bf16_f32 v92, v110, v111
	v_cvt_pk_bf16_f32 v93, v116, v117
	v_fmac_f32_e32 v95, v110, v110
	ds_read_b128 v[110:113], v109
	v_add_f32_e32 v94, v95, v94
	v_mul_f32_e32 v95, v117, v117
	v_fmac_f32_e32 v95, v116, v116
	v_add_f32_e32 v116, v95, v94
	s_waitcnt lgkmcnt(0)
	v_lshlrev_b32_e32 v94, 16, v110
	v_and_b32_e32 v95, 0xffff0000, v110
	v_lshlrev_b32_e32 v102, 16, v111
	v_and_b32_e32 v103, 0xffff0000, v111
	v_lshlrev_b32_e32 v110, 16, v112
	v_and_b32_e32 v111, 0xffff0000, v112
	v_pk_add_f32 v[84:85], v[84:85], v[94:95]
	v_pk_add_f32 v[86:87], v[86:87], v[102:103]
	v_pk_add_f32 v[102:103], v[80:81], v[110:111]
	v_mul_f32_e32 v80, 0x41800000, v84
	v_mul_f32_e32 v81, 0x41800000, v85
	v_med3_f32 v80, v80, s18, v89
	v_med3_f32 v81, v81, s18, v89
	v_cvt_pk_fp8_f32 v96, v80, v81
	v_mul_f32_e32 v80, 0x41800000, v86
	v_mul_f32_e32 v81, 0x41800000, v87
	v_med3_f32 v80, v80, s18, v89
	v_med3_f32 v81, v81, s18, v89
	v_cvt_pk_fp8_f32 v96, v80, v81 op_sel:[0,0,1]
	v_mul_f32_e32 v80, 0x41800000, v102
	v_mul_f32_e32 v81, 0x41800000, v103
	v_med3_f32 v80, v80, s18, v89
	v_med3_f32 v81, v81, s18, v89
	v_lshlrev_b32_e32 v112, 16, v113
	v_and_b32_e32 v113, 0xffff0000, v113
	v_cvt_pk_fp8_f32 v97, v80, v81
	v_pk_add_f32 v[94:95], v[82:83], v[112:113]
	ds_write_b128 v101, v[90:93]
	v_mul_f32_e32 v80, 0x41800000, v94
	v_mul_f32_e32 v81, 0x41800000, v95
	v_med3_f32 v80, v80, s18, v89
	v_med3_f32 v81, v81, s18, v89
	v_cvt_pk_fp8_f32 v97, v80, v81 op_sel:[0,0,1]
	v_mul_f32_e32 v80, v85, v85
	v_mul_f32_e32 v81, v87, v87
	v_fmac_f32_e32 v80, v84, v84
	v_fmac_f32_e32 v81, v86, v86
	v_add_f32_e32 v80, v80, v81
	v_mul_f32_e32 v81, v103, v103
	v_fmac_f32_e32 v81, v102, v102
	v_add_f32_e32 v80, v81, v80
	v_mul_f32_e32 v81, v95, v95
	v_fmac_f32_e32 v81, v94, v94
	v_add_f32_e32 v80, v81, v80
	v_add_f32_e32 v80, v116, v80
	v_mov_b32_e32 v81, v80
	s_nop 1
	v_permlane16_swap_b32 v81, v80
	global_store_dwordx2 v[114:115], v[96:97], off offset:128
	v_cvt_pk_bf16_f32 v82, v84, v85
	v_cvt_pk_bf16_f32 v83, v86, v87
	v_cvt_pk_bf16_f32 v84, v102, v103
	s_waitcnt lgkmcnt(0)
	v_add_f32_e32 v80, v80, v81
	v_mov_b32_e32 v81, v80
	s_nop 1
	v_permlane32_swap_b32 v81, v80
	v_cvt_pk_bf16_f32 v85, v94, v95
	ds_write_b128 v109, v[82:85]
	s_and_saveexec_b64 s[8:9], vcc
	s_cbranch_execz .LBB0_969
	v_lshl_add_u64 v[82:83], v[98:99], 2, s[10:11]
	s_waitcnt lgkmcnt(0)
	v_add_f32_e32 v80, v80, v81
	global_atomic_add_f32 v[82:83], v80, off
.LBB0_969:
	s_or_b64 exec, exec, s[8:9]
	s_or_b32 s8, s87, 48
	v_or_b32_e32 v80, s8, v192
	s_waitcnt lgkmcnt(0)
	v_lshlrev_b32_e32 v81, 6, v80
	v_lshlrev_b32_e32 v80, 2, v80
	s_lshr_b32 s8, s8, 3
	v_and_b32_e32 v81, 0x3c0, v81
	v_and_b32_e32 v80, 32, v80
	v_add_lshl_u32 v82, v151, s8, 10
	v_bitop3_b32 v80, v81, v80, v191 bitop3:0x36
	v_add3_u32 v82, 0, v80, v82
	v_add_u32_e32 v83, s17, v82
	ds_read_b128 v[84:87], v83
	v_or_b32_e32 v80, 48, v146
	v_ashrrev_i32_e32 v81, 31, v80
	s_waitcnt lgkmcnt(0)
	v_lshlrev_b32_e32 v90, 16, v84
	v_and_b32_e32 v91, 0xffff0000, v84
	v_lshlrev_b32_e32 v84, 16, v85
	v_and_b32_e32 v85, 0xffff0000, v85
	v_lshlrev_b32_e32 v92, 16, v86
	v_and_b32_e32 v93, 0xffff0000, v86
	v_lshlrev_b32_e32 v86, 16, v87
	v_and_b32_e32 v87, 0xffff0000, v87
	v_pk_add_f32 v[78:79], v[78:79], v[84:85]
	v_pk_add_f32 v[84:85], v[76:77], v[90:91]
	v_pk_add_f32 v[90:91], v[74:75], v[86:87]
	v_mul_f32_e32 v74, 0x41800000, v84
	v_med3_f32 v75, v74, s18, v89
	v_mul_f32_e32 v74, 0x41800000, v85
	v_med3_f32 v76, v74, s18, v89
	v_mov_b32_e32 v74, 0
	v_cvt_pk_fp8_f32 v74, v75, v76
	v_mul_f32_e32 v75, 0x41800000, v78
	v_mul_f32_e32 v76, 0x41800000, v79
	v_pk_add_f32 v[72:73], v[72:73], v[92:93]
	v_med3_f32 v75, v75, s18, v89
	v_med3_f32 v76, v76, s18, v89
	v_cvt_pk_fp8_f32 v74, v75, v76 op_sel:[0,0,1]
	v_mul_f32_e32 v75, 0x41800000, v72
	v_med3_f32 v76, v75, s18, v89
	v_mul_f32_e32 v75, 0x41800000, v73
	v_med3_f32 v77, v75, s18, v89
	v_mov_b32_e32 v75, 0
	v_cvt_pk_fp8_f32 v75, v76, v77
	v_mul_f32_e32 v76, 0x41800000, v90
	v_mul_f32_e32 v77, 0x41800000, v91
	v_med3_f32 v76, v76, s18, v89
	v_med3_f32 v77, v77, s18, v89
	v_cvt_pk_fp8_f32 v75, v76, v77 op_sel:[0,0,1]
	v_lshlrev_b64 v[76:77], 11, v[80:81]
	v_lshl_add_u64 v[76:77], s[12:13], 0, v[76:77]
	v_lshl_add_u64 v[92:93], v[76:77], 0, v[144:145]
	global_store_dwordx2 v[92:93], v[74:75], off
	v_cvt_pk_bf16_f32 v74, v84, v85
	v_cvt_pk_bf16_f32 v75, v78, v79
	v_cvt_pk_bf16_f32 v76, v72, v73
	v_mul_f32_e32 v73, v73, v73
	v_mul_f32_e32 v85, v85, v85
	v_mul_f32_e32 v79, v79, v79
	v_fmac_f32_e32 v73, v72, v72
	v_add_u32_e32 v72, 0x10000, v82
	v_fmac_f32_e32 v85, v84, v84
	v_fmac_f32_e32 v79, v78, v78
	v_add_u32_e32 v94, s17, v72
	v_cvt_pk_bf16_f32 v77, v90, v91
	v_add_f32_e32 v78, v85, v79
	ds_read_b128 v[84:87], v94
	v_add_f32_e32 v73, v73, v78
	v_mul_f32_e32 v78, v91, v91
	v_fmac_f32_e32 v78, v90, v90
	v_add_f32_e32 v73, v78, v73
	s_waitcnt lgkmcnt(0)
	v_lshlrev_b32_e32 v78, 16, v84
	v_and_b32_e32 v79, 0xffff0000, v84
	v_lshlrev_b32_e32 v84, 16, v85
	v_and_b32_e32 v85, 0xffff0000, v85
	v_lshlrev_b32_e32 v90, 16, v86
	v_and_b32_e32 v91, 0xffff0000, v86
	v_pk_add_f32 v[68:69], v[68:69], v[78:79]
	v_lshlrev_b32_e32 v86, 16, v87
	v_and_b32_e32 v87, 0xffff0000, v87
	v_pk_add_f32 v[70:71], v[70:71], v[84:85]
	v_pk_add_f32 v[84:85], v[64:65], v[90:91]
	v_mul_f32_e32 v64, 0x41800000, v68
	v_mul_f32_e32 v65, 0x41800000, v69
	v_pk_add_f32 v[78:79], v[66:67], v[86:87]
	v_med3_f32 v64, v64, s18, v89
	v_med3_f32 v65, v65, s18, v89
	v_mov_b32_e32 v66, 0
	v_cvt_pk_fp8_f32 v66, v64, v65
	v_mul_f32_e32 v64, 0x41800000, v70
	v_mul_f32_e32 v65, 0x41800000, v71
	v_med3_f32 v64, v64, s18, v89
	v_med3_f32 v65, v65, s18, v89
	v_cvt_pk_fp8_f32 v66, v64, v65 op_sel:[0,0,1]
	v_mul_f32_e32 v64, 0x41800000, v84
	v_mul_f32_e32 v65, 0x41800000, v85
	v_med3_f32 v64, v64, s18, v89
	v_med3_f32 v65, v65, s18, v89
	v_mov_b32_e32 v67, 0
	v_cvt_pk_fp8_f32 v67, v64, v65
	v_mul_f32_e32 v64, 0x41800000, v78
	v_mul_f32_e32 v65, 0x41800000, v79
	v_med3_f32 v64, v64, s18, v89
	v_med3_f32 v65, v65, s18, v89
	v_cvt_pk_fp8_f32 v67, v64, v65 op_sel:[0,0,1]
	v_mul_f32_e32 v64, v69, v69
	v_mul_f32_e32 v65, v71, v71
	v_fmac_f32_e32 v64, v68, v68
	v_fmac_f32_e32 v65, v70, v70
	v_add_f32_e32 v64, v64, v65
	v_mul_f32_e32 v65, v85, v85
	v_fmac_f32_e32 v65, v84, v84
	v_add_f32_e32 v64, v65, v64
	v_mul_f32_e32 v65, v79, v79
	v_fmac_f32_e32 v65, v78, v78
	v_add_f32_e32 v64, v65, v64
	v_add_f32_e32 v64, v73, v64
	v_mov_b32_e32 v73, v64
	s_nop 1
	v_permlane16_swap_b32 v73, v64
	global_store_dwordx2 v[92:93], v[66:67], off offset:128
	v_mov_b32_e32 v65, 0
	ds_write_b128 v83, v[74:77]
	v_cvt_pk_bf16_f32 v68, v68, v69
	s_waitcnt lgkmcnt(0)
	v_add_f32_e32 v64, v64, v73
	v_mov_b32_e32 v66, v64
	s_nop 1
	v_permlane32_swap_b32 v66, v64
	v_cvt_pk_bf16_f32 v69, v70, v71
	v_cvt_pk_bf16_f32 v70, v84, v85
	v_cvt_pk_bf16_f32 v71, v78, v79
	ds_write_b128 v94, v[68:71]
	s_and_saveexec_b64 s[8:9], vcc
	s_cbranch_execz .LBB0_971
	v_lshl_add_u64 v[68:69], v[80:81], 2, s[10:11]
	s_waitcnt lgkmcnt(0)
	v_add_f32_e32 v64, v64, v66
	global_atomic_add_f32 v[68:69], v64, off
.LBB0_971:
	s_or_b64 exec, exec, s[8:9]
	s_bitset1_b32 s15, 14
	v_add_u32_e32 v73, s15, v150
	ds_read_b128 v[68:71], v73
	s_mov_b32 s17, 0xc3e00000
	s_waitcnt lgkmcnt(0)
	v_add_u32_e32 v66, 0x80, v146
	v_ashrrev_i32_e32 v67, 31, v66
	v_add_u32_e32 v78, s15, v128
	s_waitcnt vmcnt(0)
	v_cndmask_b32_e64 v64, v71, v143, s[6:7]
	v_cndmask_b32_e64 v71, v69, v141, s[6:7]
	v_cndmask_b32_e64 v69, v68, v140, s[6:7]
	v_cndmask_b32_e64 v75, v70, v142, s[6:7]
	v_lshlrev_b32_e32 v68, 16, v69
	v_and_b32_e32 v69, 0xffff0000, v69
	v_lshlrev_b32_e32 v70, 16, v71
	v_and_b32_e32 v71, 0xffff0000, v71
	v_lshlrev_b32_e32 v74, 16, v75
	v_and_b32_e32 v75, 0xffff0000, v75
	v_lshlrev_b32_e32 v76, 16, v64
	v_and_b32_e32 v77, 0xffff0000, v64
	v_pk_add_f32 v[68:69], v[60:61], v[68:69]
	v_pk_add_f32 v[62:63], v[62:63], v[70:71]
	v_pk_add_f32 v[76:77], v[58:59], v[76:77]
	v_pk_add_f32 v[70:71], v[56:57], v[74:75]
	v_mul_f32_e32 v57, 0x41800000, v68
	v_mov_b32_e32 v56, 0x43e00000
	v_mul_f32_e32 v58, 0x41800000, v69
	v_med3_f32 v57, v57, s17, v56
	v_med3_f32 v59, v58, s17, v56
	v_mov_b32_e32 v58, 0
	v_cvt_pk_fp8_f32 v58, v57, v59
	v_mul_f32_e32 v57, 0x41800000, v62
	v_mul_f32_e32 v59, 0x41800000, v63
	v_med3_f32 v57, v57, s17, v56
	v_med3_f32 v59, v59, s17, v56
	v_cvt_pk_fp8_f32 v58, v57, v59 op_sel:[0,0,1]
	v_mul_f32_e32 v57, 0x41800000, v70
	v_mul_f32_e32 v59, 0x41800000, v71
	v_med3_f32 v57, v57, s17, v56
	v_med3_f32 v60, v59, s17, v56
	v_mov_b32_e32 v59, 0
	v_cvt_pk_fp8_f32 v59, v57, v60
	v_mul_f32_e32 v57, 0x41800000, v76
	v_mul_f32_e32 v60, 0x41800000, v77
	v_med3_f32 v57, v57, s17, v56
	v_med3_f32 v60, v60, s17, v56
	v_cvt_pk_fp8_f32 v59, v57, v60 op_sel:[0,0,1]
	v_lshlrev_b64 v[60:61], 11, v[66:67]
	v_lshl_add_u64 v[60:61], s[12:13], 0, v[60:61]
	v_lshl_add_u64 v[74:75], v[60:61], 0, v[144:145]
	global_store_dwordx2 v[74:75], v[58:59], off
	v_cvt_pk_bf16_f32 v58, v68, v69
	v_cvt_pk_bf16_f32 v59, v62, v63
	v_mul_f32_e32 v63, v63, v63
	v_mul_f32_e32 v57, v69, v69
	v_fmac_f32_e32 v63, v62, v62
	v_mul_f32_e32 v62, v71, v71
	v_cvt_pk_bf16_f32 v60, v70, v71
	v_cvt_pk_bf16_f32 v61, v76, v77
	v_fmac_f32_e32 v57, v68, v68
	v_fmac_f32_e32 v62, v70, v70
	ds_read_b128 v[68:71], v78
	v_add_f32_e32 v57, v57, v63
	v_add_f32_e32 v57, v62, v57
	v_mul_f32_e32 v62, v77, v77
	v_fmac_f32_e32 v62, v76, v76
	v_add_f32_e32 v57, v62, v57
	s_waitcnt lgkmcnt(0)
	v_lshlrev_b32_e32 v62, 16, v68
	v_and_b32_e32 v63, 0xffff0000, v68
	v_lshlrev_b32_e32 v68, 16, v69
	v_and_b32_e32 v69, 0xffff0000, v69
	v_lshlrev_b32_e32 v76, 16, v70
	v_and_b32_e32 v77, 0xffff0000, v70
	v_pk_add_f32 v[52:53], v[52:53], v[62:63]
	v_pk_add_f32 v[54:55], v[54:55], v[68:69]
	v_pk_add_f32 v[68:69], v[48:49], v[76:77]
	v_mul_f32_e32 v48, 0x41800000, v52
	v_mul_f32_e32 v49, 0x41800000, v53
	v_med3_f32 v48, v48, s17, v56
	v_med3_f32 v49, v49, s17, v56
	v_mov_b32_e32 v64, 0
	v_cvt_pk_fp8_f32 v64, v48, v49
	v_mul_f32_e32 v48, 0x41800000, v54
	v_mul_f32_e32 v49, 0x41800000, v55
	v_med3_f32 v48, v48, s17, v56
	v_med3_f32 v49, v49, s17, v56
	v_cvt_pk_fp8_f32 v64, v48, v49 op_sel:[0,0,1]
	v_mul_f32_e32 v48, 0x41800000, v68
	v_mul_f32_e32 v49, 0x41800000, v69
	v_med3_f32 v48, v48, s17, v56
	v_med3_f32 v49, v49, s17, v56
	v_lshlrev_b32_e32 v70, 16, v71
	v_and_b32_e32 v71, 0xffff0000, v71
	v_cvt_pk_fp8_f32 v65, v48, v49
	v_pk_add_f32 v[62:63], v[50:51], v[70:71]
	ds_write_b128 v73, v[58:61]
	v_mul_f32_e32 v48, 0x41800000, v62
	v_mul_f32_e32 v49, 0x41800000, v63
	v_med3_f32 v48, v48, s17, v56
	v_med3_f32 v49, v49, s17, v56
	v_cvt_pk_fp8_f32 v65, v48, v49 op_sel:[0,0,1]
	v_mul_f32_e32 v48, v53, v53
	v_mul_f32_e32 v49, v55, v55
	v_fmac_f32_e32 v48, v52, v52
	v_fmac_f32_e32 v49, v54, v54
	v_add_f32_e32 v48, v48, v49
	v_mul_f32_e32 v49, v69, v69
	v_fmac_f32_e32 v49, v68, v68
	v_add_f32_e32 v48, v49, v48
	v_mul_f32_e32 v49, v63, v63
	v_fmac_f32_e32 v49, v62, v62
	v_add_f32_e32 v48, v49, v48
	v_add_f32_e32 v48, v57, v48
	v_mov_b32_e32 v49, v48
	s_nop 1
	v_permlane16_swap_b32 v49, v48
	global_store_dwordx2 v[74:75], v[64:65], off offset:128
	v_cvt_pk_bf16_f32 v50, v52, v53
	v_cvt_pk_bf16_f32 v51, v54, v55
	v_cvt_pk_bf16_f32 v52, v68, v69
	s_waitcnt lgkmcnt(0)
	v_add_f32_e32 v48, v48, v49
	v_mov_b32_e32 v49, v48
	s_nop 1
	v_permlane32_swap_b32 v49, v48
	v_cvt_pk_bf16_f32 v53, v62, v63
	ds_write_b128 v78, v[50:53]
	s_and_saveexec_b64 s[8:9], vcc
	s_cbranch_execz .LBB0_973
	v_lshl_add_u64 v[50:51], v[66:67], 2, s[10:11]
	s_waitcnt lgkmcnt(1)
	v_add_f32_e32 v48, v48, v49
	global_atomic_add_f32 v[50:51], v48, off
.LBB0_973:
	s_or_b64 exec, exec, s[8:9]
	v_add_u32_e32 v57, s15, v120
	ds_read_b128 v[50:53], v57
	v_add_u32_e32 v48, 0x90, v146
	s_waitcnt lgkmcnt(2)
	v_ashrrev_i32_e32 v49, 31, v48
	s_waitcnt lgkmcnt(0)
	v_cndmask_b32_e64 v59, v53, v139, s[6:7]
	v_cndmask_b32_e64 v53, v51, v137, s[6:7]
	v_cndmask_b32_e64 v51, v50, v136, s[6:7]
	v_cndmask_b32_e64 v55, v52, v138, s[6:7]
	v_lshlrev_b32_e32 v50, 16, v51
	v_and_b32_e32 v51, 0xffff0000, v51
	v_lshlrev_b32_e32 v52, 16, v53
	v_and_b32_e32 v53, 0xffff0000, v53
	v_lshlrev_b32_e32 v54, 16, v55
	v_and_b32_e32 v55, 0xffff0000, v55
	v_pk_add_f32 v[44:45], v[44:45], v[50:51]
	v_pk_add_f32 v[46:47], v[46:47], v[52:53]
	v_pk_add_f32 v[52:53], v[40:41], v[54:55]
	v_mul_f32_e32 v40, 0x41800000, v44
	v_lshlrev_b32_e32 v58, 16, v59
	v_and_b32_e32 v59, 0xffff0000, v59
	v_med3_f32 v41, v40, s17, v56
	v_mul_f32_e32 v40, 0x41800000, v45
	v_pk_add_f32 v[50:51], v[42:43], v[58:59]
	v_med3_f32 v42, v40, s17, v56
	v_mov_b32_e32 v40, 0
	v_cvt_pk_fp8_f32 v40, v41, v42
	v_mul_f32_e32 v41, 0x41800000, v46
	v_mul_f32_e32 v42, 0x41800000, v47
	v_med3_f32 v41, v41, s17, v56
	v_med3_f32 v42, v42, s17, v56
	v_cvt_pk_fp8_f32 v40, v41, v42 op_sel:[0,0,1]
	v_mul_f32_e32 v41, 0x41800000, v52
	v_med3_f32 v42, v41, s17, v56
	v_mul_f32_e32 v41, 0x41800000, v53
	v_med3_f32 v43, v41, s17, v56
	v_mov_b32_e32 v41, 0
	v_cvt_pk_fp8_f32 v41, v42, v43
	v_mul_f32_e32 v42, 0x41800000, v50
	v_mul_f32_e32 v43, 0x41800000, v51
	v_med3_f32 v42, v42, s17, v56
	v_med3_f32 v43, v43, s17, v56
	v_cvt_pk_fp8_f32 v41, v42, v43 op_sel:[0,0,1]
	v_lshlrev_b64 v[42:43], 11, v[48:49]
	v_lshl_add_u64 v[42:43], s[12:13], 0, v[42:43]
	v_lshl_add_u64 v[54:55], v[42:43], 0, v[144:145]
	global_store_dwordx2 v[54:55], v[40:41], off
	v_cvt_pk_bf16_f32 v40, v44, v45
	v_mul_f32_e32 v45, v45, v45
	v_fmac_f32_e32 v45, v44, v44
	v_mul_f32_e32 v44, v47, v47
	v_fmac_f32_e32 v44, v46, v46
	v_add_u32_e32 v59, s15, v108
	v_cvt_pk_bf16_f32 v41, v46, v47
	v_cvt_pk_bf16_f32 v42, v52, v53
	v_cvt_pk_bf16_f32 v43, v50, v51
	v_add_f32_e32 v58, v45, v44
	ds_read_b128 v[44:47], v59
	v_mul_f32_e32 v53, v53, v53
	v_fmac_f32_e32 v53, v52, v52
	v_mul_f32_e32 v51, v51, v51
	v_add_f32_e32 v52, v53, v58
	v_fmac_f32_e32 v51, v50, v50
	v_add_f32_e32 v58, v51, v52
	s_waitcnt lgkmcnt(0)
	v_lshlrev_b32_e32 v50, 16, v44
	v_and_b32_e32 v51, 0xffff0000, v44
	v_lshlrev_b32_e32 v44, 16, v45
	v_and_b32_e32 v45, 0xffff0000, v45
	v_lshlrev_b32_e32 v52, 16, v46
	v_and_b32_e32 v53, 0xffff0000, v46
	v_lshlrev_b32_e32 v46, 16, v47
	v_and_b32_e32 v47, 0xffff0000, v47
	v_pk_add_f32 v[36:37], v[36:37], v[50:51]
	v_pk_add_f32 v[38:39], v[38:39], v[44:45]
	v_pk_add_f32 v[44:45], v[34:35], v[46:47]
	v_pk_add_f32 v[46:47], v[32:33], v[52:53]
	v_mul_f32_e32 v32, 0x41800000, v36
	v_mul_f32_e32 v33, 0x41800000, v37
	v_med3_f32 v32, v32, s17, v56
	v_med3_f32 v33, v33, s17, v56
	v_mov_b32_e32 v34, 0
	v_cvt_pk_fp8_f32 v34, v32, v33
	v_mul_f32_e32 v32, 0x41800000, v38
	v_mul_f32_e32 v33, 0x41800000, v39
	v_med3_f32 v32, v32, s17, v56
	v_med3_f32 v33, v33, s17, v56
	v_cvt_pk_fp8_f32 v34, v32, v33 op_sel:[0,0,1]
	v_mul_f32_e32 v32, 0x41800000, v46
	v_mul_f32_e32 v33, 0x41800000, v47
	v_med3_f32 v32, v32, s17, v56
	v_med3_f32 v33, v33, s17, v56
	v_mov_b32_e32 v35, 0
	v_cvt_pk_fp8_f32 v35, v32, v33
	v_mul_f32_e32 v32, 0x41800000, v44
	v_mul_f32_e32 v33, 0x41800000, v45
	v_med3_f32 v32, v32, s17, v56
	v_med3_f32 v33, v33, s17, v56
	v_cvt_pk_fp8_f32 v35, v32, v33 op_sel:[0,0,1]
	v_mul_f32_e32 v32, v37, v37
	v_mul_f32_e32 v33, v39, v39
	v_fmac_f32_e32 v32, v36, v36
	v_fmac_f32_e32 v33, v38, v38
	v_add_f32_e32 v32, v32, v33
	v_mul_f32_e32 v33, v47, v47
	v_fmac_f32_e32 v33, v46, v46
	v_add_f32_e32 v32, v33, v32
	v_mul_f32_e32 v33, v45, v45
	v_fmac_f32_e32 v33, v44, v44
	v_add_f32_e32 v32, v33, v32
	v_add_f32_e32 v32, v58, v32
	v_mov_b32_e32 v50, v32
	s_nop 1
	v_permlane16_swap_b32 v50, v32
	global_store_dwordx2 v[54:55], v[34:35], off offset:128
	v_mov_b32_e32 v33, 0
	ds_write_b128 v57, v[40:43]
	v_cvt_pk_bf16_f32 v36, v36, v37
	s_waitcnt lgkmcnt(1)
	v_add_f32_e32 v32, v32, v50
	v_mov_b32_e32 v34, v32
	s_nop 1
	v_permlane32_swap_b32 v34, v32
	v_cvt_pk_bf16_f32 v37, v38, v39
	v_cvt_pk_bf16_f32 v38, v46, v47
	v_cvt_pk_bf16_f32 v39, v44, v45
	ds_write_b128 v59, v[36:39]
	s_and_saveexec_b64 s[8:9], vcc
	s_cbranch_execz .LBB0_975
	v_lshl_add_u64 v[36:37], v[48:49], 2, s[10:11]
	s_waitcnt lgkmcnt(1)
	v_add_f32_e32 v32, v32, v34
	global_atomic_add_f32 v[36:37], v32, off
.LBB0_975:
	s_or_b64 exec, exec, s[8:9]
	v_add_u32_e32 v44, s15, v100
	ds_read_b128 v[36:39], v44
	s_waitcnt lgkmcnt(2)
	v_add_u32_e32 v34, 0xa0, v146
	v_ashrrev_i32_e32 v35, 31, v34
	v_add_u32_e32 v45, s15, v88
	s_waitcnt lgkmcnt(0)
	v_cndmask_b32_e64 v32, v39, v127, s[6:7]
	v_cndmask_b32_e64 v39, v37, v125, s[6:7]
	v_cndmask_b32_e64 v37, v36, v124, s[6:7]
	v_cndmask_b32_e64 v41, v38, v126, s[6:7]
	v_lshlrev_b32_e32 v36, 16, v37
	v_and_b32_e32 v37, 0xffff0000, v37
	v_lshlrev_b32_e32 v38, 16, v39
	v_and_b32_e32 v39, 0xffff0000, v39
	v_lshlrev_b32_e32 v40, 16, v41
	v_and_b32_e32 v41, 0xffff0000, v41
	v_lshlrev_b32_e32 v42, 16, v32
	v_and_b32_e32 v43, 0xffff0000, v32
	v_pk_add_f32 v[36:37], v[28:29], v[36:37]
	v_pk_add_f32 v[30:31], v[30:31], v[38:39]
	v_pk_add_f32 v[42:43], v[26:27], v[42:43]
	v_pk_add_f32 v[38:39], v[24:25], v[40:41]
	v_mul_f32_e32 v25, 0x41800000, v36
	v_mov_b32_e32 v24, 0x43e00000
	v_mul_f32_e32 v26, 0x41800000, v37
	v_med3_f32 v25, v25, s17, v24
	v_med3_f32 v27, v26, s17, v24
	v_mov_b32_e32 v26, 0
	v_cvt_pk_fp8_f32 v26, v25, v27
	v_mul_f32_e32 v25, 0x41800000, v30
	v_mul_f32_e32 v27, 0x41800000, v31
	v_med3_f32 v25, v25, s17, v24
	v_med3_f32 v27, v27, s17, v24
	v_cvt_pk_fp8_f32 v26, v25, v27 op_sel:[0,0,1]
	v_mul_f32_e32 v25, 0x41800000, v38
	v_mul_f32_e32 v27, 0x41800000, v39
	v_med3_f32 v25, v25, s17, v24
	v_med3_f32 v28, v27, s17, v24
	v_mov_b32_e32 v27, 0
	v_cvt_pk_fp8_f32 v27, v25, v28
	v_mul_f32_e32 v25, 0x41800000, v42
	v_mul_f32_e32 v28, 0x41800000, v43
	v_med3_f32 v25, v25, s17, v24
	v_med3_f32 v28, v28, s17, v24
	v_cvt_pk_fp8_f32 v27, v25, v28 op_sel:[0,0,1]
	v_lshlrev_b64 v[28:29], 11, v[34:35]
	v_lshl_add_u64 v[28:29], s[12:13], 0, v[28:29]
	v_lshl_add_u64 v[40:41], v[28:29], 0, v[144:145]
	global_store_dwordx2 v[40:41], v[26:27], off
	v_cvt_pk_bf16_f32 v26, v36, v37
	v_cvt_pk_bf16_f32 v27, v30, v31
	v_mul_f32_e32 v31, v31, v31
	v_mul_f32_e32 v25, v37, v37
	v_fmac_f32_e32 v31, v30, v30
	v_mul_f32_e32 v30, v39, v39
	v_cvt_pk_bf16_f32 v28, v38, v39
	v_cvt_pk_bf16_f32 v29, v42, v43
	v_fmac_f32_e32 v25, v36, v36
	v_fmac_f32_e32 v30, v38, v38
	ds_read_b128 v[36:39], v45
	v_add_f32_e32 v25, v25, v31
	v_add_f32_e32 v25, v30, v25
	v_mul_f32_e32 v30, v43, v43
	v_fmac_f32_e32 v30, v42, v42
	v_add_f32_e32 v25, v30, v25
	s_waitcnt lgkmcnt(0)
	v_lshlrev_b32_e32 v30, 16, v36
	v_and_b32_e32 v31, 0xffff0000, v36
	v_lshlrev_b32_e32 v36, 16, v37
	v_and_b32_e32 v37, 0xffff0000, v37
	v_lshlrev_b32_e32 v42, 16, v38
	v_and_b32_e32 v43, 0xffff0000, v38
	v_pk_add_f32 v[20:21], v[20:21], v[30:31]
	v_pk_add_f32 v[22:23], v[22:23], v[36:37]
	v_pk_add_f32 v[36:37], v[16:17], v[42:43]
	v_mul_f32_e32 v16, 0x41800000, v20
	v_mul_f32_e32 v17, 0x41800000, v21
	v_med3_f32 v16, v16, s17, v24
	v_med3_f32 v17, v17, s17, v24
	v_mov_b32_e32 v32, 0
	v_cvt_pk_fp8_f32 v32, v16, v17
	v_mul_f32_e32 v16, 0x41800000, v22
	v_mul_f32_e32 v17, 0x41800000, v23
	v_med3_f32 v16, v16, s17, v24
	v_med3_f32 v17, v17, s17, v24
	v_cvt_pk_fp8_f32 v32, v16, v17 op_sel:[0,0,1]
	v_mul_f32_e32 v16, 0x41800000, v36
	v_mul_f32_e32 v17, 0x41800000, v37
	v_med3_f32 v16, v16, s17, v24
	v_med3_f32 v17, v17, s17, v24
	v_lshlrev_b32_e32 v38, 16, v39
	v_and_b32_e32 v39, 0xffff0000, v39
	v_cvt_pk_fp8_f32 v33, v16, v17
	v_pk_add_f32 v[30:31], v[18:19], v[38:39]
	ds_write_b128 v44, v[26:29]
	v_mul_f32_e32 v16, 0x41800000, v30
	v_mul_f32_e32 v17, 0x41800000, v31
	v_med3_f32 v16, v16, s17, v24
	v_med3_f32 v17, v17, s17, v24
	v_cvt_pk_fp8_f32 v33, v16, v17 op_sel:[0,0,1]
	v_mul_f32_e32 v16, v21, v21
	v_mul_f32_e32 v17, v23, v23
	v_fmac_f32_e32 v16, v20, v20
	v_fmac_f32_e32 v17, v22, v22
	v_add_f32_e32 v16, v16, v17
	v_mul_f32_e32 v17, v37, v37
	v_fmac_f32_e32 v17, v36, v36
	v_add_f32_e32 v16, v17, v16
	v_mul_f32_e32 v17, v31, v31
	v_fmac_f32_e32 v17, v30, v30
	v_add_f32_e32 v16, v17, v16
	v_add_f32_e32 v16, v25, v16
	v_mov_b32_e32 v17, v16
	s_nop 1
	v_permlane16_swap_b32 v17, v16
	global_store_dwordx2 v[40:41], v[32:33], off offset:128
	v_cvt_pk_bf16_f32 v18, v20, v21
	v_cvt_pk_bf16_f32 v19, v22, v23
	v_cvt_pk_bf16_f32 v20, v36, v37
	s_waitcnt lgkmcnt(0)
	v_add_f32_e32 v16, v16, v17
	v_mov_b32_e32 v17, v16
	s_nop 1
	v_permlane32_swap_b32 v17, v16
	v_cvt_pk_bf16_f32 v21, v30, v31
	ds_write_b128 v45, v[18:21]
	s_and_saveexec_b64 s[8:9], vcc
	s_cbranch_execz .LBB0_977
	v_lshl_add_u64 v[18:19], v[34:35], 2, s[10:11]
	s_waitcnt lgkmcnt(1)
	v_add_f32_e32 v16, v16, v17
	global_atomic_add_f32 v[18:19], v16, off
.LBB0_977:
	s_or_b64 exec, exec, s[8:9]
	v_add_u32_e32 v25, s15, v82
	ds_read_b128 v[18:21], v25
	v_add_u32_e32 v16, 0xb0, v146
	s_waitcnt lgkmcnt(2)
	v_ashrrev_i32_e32 v17, 31, v16
	s_waitcnt lgkmcnt(0)
	v_cndmask_b32_e64 v27, v21, v107, s[6:7]
	v_cndmask_b32_e64 v21, v19, v105, s[6:7]
	v_cndmask_b32_e64 v19, v18, v104, s[6:7]
	v_cndmask_b32_e64 v23, v20, v106, s[6:7]
	v_lshlrev_b32_e32 v18, 16, v19
	v_and_b32_e32 v19, 0xffff0000, v19
	v_lshlrev_b32_e32 v20, 16, v21
	v_and_b32_e32 v21, 0xffff0000, v21
	v_lshlrev_b32_e32 v22, 16, v23
	v_and_b32_e32 v23, 0xffff0000, v23
	v_pk_add_f32 v[12:13], v[12:13], v[18:19]
	v_pk_add_f32 v[14:15], v[14:15], v[20:21]
	v_pk_add_f32 v[20:21], v[8:9], v[22:23]
	v_mul_f32_e32 v8, 0x41800000, v12
	v_lshlrev_b32_e32 v26, 16, v27
	v_and_b32_e32 v27, 0xffff0000, v27
	v_med3_f32 v9, v8, s17, v24
	v_mul_f32_e32 v8, 0x41800000, v13
	v_pk_add_f32 v[18:19], v[10:11], v[26:27]
	v_med3_f32 v10, v8, s17, v24
	v_mov_b32_e32 v8, 0
	v_cvt_pk_fp8_f32 v8, v9, v10
	v_mul_f32_e32 v9, 0x41800000, v14
	v_mul_f32_e32 v10, 0x41800000, v15
	v_med3_f32 v9, v9, s17, v24
	v_med3_f32 v10, v10, s17, v24
	v_cvt_pk_fp8_f32 v8, v9, v10 op_sel:[0,0,1]
	v_mul_f32_e32 v9, 0x41800000, v20
	v_med3_f32 v10, v9, s17, v24
	v_mul_f32_e32 v9, 0x41800000, v21
	v_med3_f32 v11, v9, s17, v24
	v_mov_b32_e32 v9, 0
	v_cvt_pk_fp8_f32 v9, v10, v11
	v_mul_f32_e32 v10, 0x41800000, v18
	v_mul_f32_e32 v11, 0x41800000, v19
	v_med3_f32 v10, v10, s17, v24
	v_med3_f32 v11, v11, s17, v24
	v_cvt_pk_fp8_f32 v9, v10, v11 op_sel:[0,0,1]
	v_lshlrev_b64 v[10:11], 11, v[16:17]
	v_lshl_add_u64 v[10:11], s[12:13], 0, v[10:11]
	v_lshl_add_u64 v[22:23], v[10:11], 0, v[144:145]
	global_store_dwordx2 v[22:23], v[8:9], off
	v_cvt_pk_bf16_f32 v8, v12, v13
	v_mul_f32_e32 v13, v13, v13
	v_fmac_f32_e32 v13, v12, v12
	v_mul_f32_e32 v12, v15, v15
	v_fmac_f32_e32 v12, v14, v14
	v_add_u32_e32 v27, s15, v72
	v_cvt_pk_bf16_f32 v9, v14, v15
	v_cvt_pk_bf16_f32 v10, v20, v21
	v_cvt_pk_bf16_f32 v11, v18, v19
	v_add_f32_e32 v26, v13, v12
	ds_read_b128 v[12:15], v27
	v_mul_f32_e32 v21, v21, v21
	v_fmac_f32_e32 v21, v20, v20
	v_mul_f32_e32 v19, v19, v19
	v_add_f32_e32 v20, v21, v26
	v_fmac_f32_e32 v19, v18, v18
	v_add_f32_e32 v26, v19, v20
	s_waitcnt lgkmcnt(0)
	v_lshlrev_b32_e32 v18, 16, v12
	v_and_b32_e32 v19, 0xffff0000, v12
	v_lshlrev_b32_e32 v12, 16, v13
	v_and_b32_e32 v13, 0xffff0000, v13
	v_lshlrev_b32_e32 v20, 16, v14
	v_and_b32_e32 v21, 0xffff0000, v14
	v_lshlrev_b32_e32 v14, 16, v15
	v_and_b32_e32 v15, 0xffff0000, v15
	v_pk_add_f32 v[4:5], v[4:5], v[18:19]
	v_pk_add_f32 v[6:7], v[6:7], v[12:13]
	v_pk_add_f32 v[12:13], v[2:3], v[14:15]
	v_pk_add_f32 v[14:15], v[0:1], v[20:21]
	v_mul_f32_e32 v0, 0x41800000, v4
	v_mul_f32_e32 v1, 0x41800000, v5
	v_med3_f32 v0, v0, s17, v24
	v_med3_f32 v1, v1, s17, v24
	v_mov_b32_e32 v2, 0
	v_cvt_pk_fp8_f32 v2, v0, v1
	v_mul_f32_e32 v0, 0x41800000, v6
	v_mul_f32_e32 v1, 0x41800000, v7
	v_med3_f32 v0, v0, s17, v24
	v_med3_f32 v1, v1, s17, v24
	v_cvt_pk_fp8_f32 v2, v0, v1 op_sel:[0,0,1]
	v_mul_f32_e32 v0, 0x41800000, v14
	v_mul_f32_e32 v1, 0x41800000, v15
	v_med3_f32 v0, v0, s17, v24
	v_med3_f32 v1, v1, s17, v24
	v_mov_b32_e32 v3, 0
	v_cvt_pk_fp8_f32 v3, v0, v1
	v_mul_f32_e32 v0, 0x41800000, v12
	v_mul_f32_e32 v1, 0x41800000, v13
	v_med3_f32 v0, v0, s17, v24
	v_med3_f32 v1, v1, s17, v24
	v_cvt_pk_fp8_f32 v3, v0, v1 op_sel:[0,0,1]
	v_mul_f32_e32 v0, v5, v5
	v_mul_f32_e32 v1, v7, v7
	v_fmac_f32_e32 v0, v4, v4
	v_fmac_f32_e32 v1, v6, v6
	v_add_f32_e32 v0, v0, v1
	v_mul_f32_e32 v1, v15, v15
	v_fmac_f32_e32 v1, v14, v14
	v_add_f32_e32 v0, v1, v0
	v_mul_f32_e32 v1, v13, v13
	v_fmac_f32_e32 v1, v12, v12
	v_add_f32_e32 v0, v1, v0
	v_add_f32_e32 v0, v26, v0
	v_mov_b32_e32 v18, v0
	s_nop 1
	v_permlane16_swap_b32 v18, v0
	global_store_dwordx2 v[22:23], v[2:3], off offset:128
	v_mov_b32_e32 v1, 0
	ds_write_b128 v25, v[8:11]
	v_cvt_pk_bf16_f32 v4, v4, v5
	s_waitcnt lgkmcnt(1)
	v_add_f32_e32 v0, v0, v18
	v_mov_b32_e32 v2, v0
	s_nop 1
	v_permlane32_swap_b32 v2, v0
	v_cvt_pk_bf16_f32 v5, v6, v7
	v_cvt_pk_bf16_f32 v6, v14, v15
	v_cvt_pk_bf16_f32 v7, v12, v13
	ds_write_b128 v27, v[4:7]
	s_and_saveexec_b64 s[6:7], vcc
	s_cbranch_execz .LBB0_979
	v_lshl_add_u64 v[4:5], v[16:17], 2, s[10:11]
	s_waitcnt lgkmcnt(1)
	v_add_f32_e32 v0, v0, v2
	global_atomic_add_f32 v[4:5], v0, off

.LBB0_1269:
	v_readlane_b32 s4, v250, 7
	s_and_b32 s8, s4, 32
	v_add_u32_e32 v18, s8, v18
	v_ashrrev_i32_e32 v26, 5, v18
	v_lshlrev_b32_e32 v18, 10, v26
	s_add_i32 s8, s86, 0
	s_lshl_b32 s11, s92, 14
	v_add3_u32 v21, s8, v191, v18
	s_and_b32 s15, s11, 0x8000
	v_add_u32_e32 v27, s15, v21
	ds_read_b128 v[22:25], v27
	s_mov_b32 s16, 0x38800000
	v_add_u32_e32 v20, 0x10000, v21
	s_waitcnt lgkmcnt(0)
	v_lshlrev_b32_e32 v18, 16, v22
	v_and_b32_e32 v19, 0xffff0000, v22
	v_lshlrev_b32_e32 v22, 16, v23
	v_and_b32_e32 v23, 0xffff0000, v23
	v_pk_fma_f32 v[18:19], v[156:157], s[16:17], v[18:19] op_sel_hi:[1,0,1]
	v_pk_fma_f32 v[30:31], v[158:159], s[16:17], v[22:23] op_sel_hi:[1,0,1]
	v_cvt_pk_bf16_f32 v22, v18, v19
	v_mul_f32_e32 v19, v19, v19
	v_lshlrev_b32_e32 v28, 16, v24
	v_and_b32_e32 v29, 0xffff0000, v24
	v_fmac_f32_e32 v19, v18, v18
	v_mul_f32_e32 v18, v31, v31
	v_pk_fma_f32 v[28:29], v[152:153], s[16:17], v[28:29] op_sel_hi:[1,0,1]
	v_fmac_f32_e32 v18, v30, v30
	v_lshlrev_b32_e32 v24, 16, v25
	v_and_b32_e32 v25, 0xffff0000, v25
	v_add_f32_e32 v18, v19, v18
	v_mul_f32_e32 v19, v29, v29
	v_add_u32_e32 v156, s15, v20
	v_pk_fma_f32 v[154:155], v[154:155], s[16:17], v[24:25] op_sel_hi:[1,0,1]
	v_cvt_pk_bf16_f32 v23, v30, v31
	v_cvt_pk_bf16_f32 v24, v28, v29
	v_fmac_f32_e32 v19, v28, v28
	v_cvt_pk_bf16_f32 v25, v154, v155
	ds_read_b128 v[28:31], v156
	v_add_f32_e32 v18, v19, v18
	v_mul_f32_e32 v19, v155, v155
	v_fmac_f32_e32 v19, v154, v154
	v_add_f32_e32 v154, v19, v18
	s_waitcnt lgkmcnt(0)
	v_lshlrev_b32_e32 v18, 16, v28
	v_and_b32_e32 v19, 0xffff0000, v28
	v_lshlrev_b32_e32 v28, 16, v29
	v_and_b32_e32 v29, 0xffff0000, v29
	v_pk_fma_f32 v[150:151], v[150:151], s[16:17], v[28:29] op_sel_hi:[1,0,1]
	v_pk_fma_f32 v[28:29], v[148:149], s[16:17], v[18:19] op_sel_hi:[1,0,1]
	v_lshlrev_b32_e32 v152, 16, v30
	v_and_b32_e32 v153, 0xffff0000, v30
	v_lshlrev_b32_e32 v30, 16, v31
	v_and_b32_e32 v31, 0xffff0000, v31
	v_mul_f32_e32 v18, v29, v29
	v_mul_f32_e32 v19, v151, v151
	v_pk_fma_f32 v[146:147], v[146:147], s[16:17], v[30:31] op_sel_hi:[1,0,1]
	v_pk_fma_f32 v[30:31], v[144:145], s[16:17], v[152:153] op_sel_hi:[1,0,1]
	v_fmac_f32_e32 v18, v28, v28
	v_fmac_f32_e32 v19, v150, v150
	v_add_f32_e32 v18, v18, v19
	v_mul_f32_e32 v19, v31, v31
	v_fmac_f32_e32 v19, v30, v30
	v_add_f32_e32 v18, v19, v18
	v_mul_f32_e32 v19, v147, v147
	v_fmac_f32_e32 v19, v146, v146
	v_mbcnt_hi_u32_b32 v144, -1, v225
	v_add_f32_e32 v18, v19, v18
	v_and_b32_e32 v145, 64, v144
	v_add_f32_e32 v19, v154, v18
	v_xor_b32_e32 v18, 16, v144
	v_add_u32_e32 v145, 64, v145
	v_cmp_lt_i32_e32 vcc, v18, v145
	ds_write_b128 v27, v[22:25]
	v_cvt_pk_bf16_f32 v28, v28, v29
	v_cvt_pk_bf16_f32 v29, v150, v151
	v_cvt_pk_bf16_f32 v30, v30, v31
	v_cvt_pk_bf16_f32 v31, v146, v147
	s_nop 0
	v_cndmask_b32_e32 v18, v144, v18, vcc
	v_lshlrev_b32_e32 v18, 2, v18
	v_mov_b32_e32 v148, v19
	s_nop 1
	v_permlane16_swap_b32 v148, v19
	v_cmp_gt_u32_e32 vcc, 16, v186
	ds_write_b128 v156, v[28:31]
	s_waitcnt lgkmcnt(0)
	v_add_f32_e32 v22, v19, v148
	v_xor_b32_e32 v19, 32, v144
	v_cmp_lt_i32_e64 s[8:9], v19, v145
	s_nop 1
	v_cndmask_b32_e64 v19, v144, v19, s[8:9]
	v_lshlrev_b32_e32 v19, 2, v19
	v_mov_b32_e32 v23, v22
	s_nop 1
	v_permlane32_swap_b32 v23, v22
	s_and_saveexec_b64 s[8:9], vcc
	v_readlane_b32 s68, v250, 9
	v_readlane_b32 s69, v250, 10
	s_cbranch_execz .LBB0_1271
	v_lshl_add_u64 v[24:25], v[16:17], 2, s[12:13]
	s_waitcnt lgkmcnt(0)
	v_add_f32_e32 v22, v22, v23
	global_atomic_add_f32 v[24:25], v22, off
.LBB0_1271:
	s_or_b64 exec, exec, s[8:9]
	s_or_b32 s8, s87, 16
	v_or_b32_e32 v22, s8, v189
	s_waitcnt lgkmcnt(0)
	v_lshlrev_b32_e32 v23, 6, v22
	v_lshlrev_b32_e32 v22, 2, v22
	s_lshr_b32 s8, s8, 3
	v_and_b32_e32 v23, 0x3c0, v23
	v_and_b32_e32 v22, 32, v22
	v_add_lshl_u32 v24, v26, s8, 10
	v_bitop3_b32 v22, v23, v22, v188 bitop3:0x36
	v_add3_u32 v23, 0, v22, v24
	v_add_u32_e32 v27, s15, v23
	ds_read_b128 v[28:31], v27
	s_waitcnt lgkmcnt(0)
	v_lshlrev_b32_e32 v24, 16, v28
	v_and_b32_e32 v25, 0xffff0000, v28
	v_lshlrev_b32_e32 v28, 16, v29
	v_and_b32_e32 v29, 0xffff0000, v29
	v_pk_fma_f32 v[24:25], v[140:141], s[16:17], v[24:25] op_sel_hi:[1,0,1]
	v_pk_fma_f32 v[142:143], v[142:143], s[16:17], v[28:29] op_sel_hi:[1,0,1]
	v_mul_f32_e32 v22, v25, v25
	v_cvt_pk_bf16_f32 v28, v24, v25
	v_fmac_f32_e32 v22, v24, v24
	v_mul_f32_e32 v24, v143, v143
	v_lshlrev_b32_e32 v144, 16, v30
	v_and_b32_e32 v145, 0xffff0000, v30
	v_fmac_f32_e32 v24, v142, v142
	v_pk_fma_f32 v[136:137], v[136:137], s[16:17], v[144:145] op_sel_hi:[1,0,1]
	v_add_f32_e32 v24, v22, v24
	v_add_u32_e32 v22, 0x10000, v23
	v_lshlrev_b32_e32 v30, 16, v31
	v_and_b32_e32 v31, 0xffff0000, v31
	v_cvt_pk_bf16_f32 v29, v142, v143
	v_mul_f32_e32 v25, v137, v137
	v_add_u32_e32 v142, s15, v22
	v_pk_fma_f32 v[140:141], v[138:139], s[16:17], v[30:31] op_sel_hi:[1,0,1]
	v_cvt_pk_bf16_f32 v30, v136, v137
	v_fmac_f32_e32 v25, v136, v136
	v_cvt_pk_bf16_f32 v31, v140, v141
	ds_read_b128 v[136:139], v142
	v_add_f32_e32 v24, v25, v24
	v_mul_f32_e32 v25, v141, v141
	v_fmac_f32_e32 v25, v140, v140
	v_add_f32_e32 v143, v25, v24
	s_waitcnt lgkmcnt(0)
	v_lshlrev_b32_e32 v24, 16, v136
	v_and_b32_e32 v25, 0xffff0000, v136
	v_lshlrev_b32_e32 v136, 16, v137
	v_and_b32_e32 v137, 0xffff0000, v137
	v_pk_fma_f32 v[134:135], v[134:135], s[16:17], v[136:137] op_sel_hi:[1,0,1]
	v_pk_fma_f32 v[24:25], v[132:133], s[16:17], v[24:25] op_sel_hi:[1,0,1]
	v_lshlrev_b32_e32 v140, 16, v138
	v_and_b32_e32 v141, 0xffff0000, v138
	v_mul_f32_e32 v132, v25, v25
	v_mul_f32_e32 v133, v135, v135
	v_pk_fma_f32 v[128:129], v[128:129], s[16:17], v[140:141] op_sel_hi:[1,0,1]
	v_fmac_f32_e32 v132, v24, v24
	v_fmac_f32_e32 v133, v134, v134
	v_lshlrev_b32_e32 v138, 16, v139
	v_and_b32_e32 v139, 0xffff0000, v139
	v_add_f32_e32 v132, v132, v133
	v_mul_f32_e32 v133, v129, v129
	v_pk_fma_f32 v[130:131], v[130:131], s[16:17], v[138:139] op_sel_hi:[1,0,1]
	v_fmac_f32_e32 v133, v128, v128
	v_add_f32_e32 v132, v133, v132
	v_mul_f32_e32 v133, v131, v131
	v_fmac_f32_e32 v133, v130, v130
	v_add_f32_e32 v132, v133, v132
	v_add_f32_e32 v132, v143, v132
	v_mov_b32_e32 v133, v132
	s_nop 1
	v_permlane16_swap_b32 v133, v132
	ds_write_b128 v27, v[28:31]
	v_cvt_pk_bf16_f32 v28, v24, v25
	v_cvt_pk_bf16_f32 v29, v134, v135
	v_cvt_pk_bf16_f32 v30, v128, v129
	s_waitcnt lgkmcnt(0)
	v_add_f32_e32 v24, v132, v133
	v_mov_b32_e32 v25, v24
	s_nop 1
	v_permlane32_swap_b32 v25, v24
	v_cvt_pk_bf16_f32 v31, v130, v131
	ds_write_b128 v142, v[28:31]
	s_and_saveexec_b64 s[8:9], vcc
	s_cbranch_execz .LBB0_1273
	v_lshl_add_u64 v[28:29], v[16:17], 2, s[12:13]
	s_waitcnt lgkmcnt(0)
	v_add_f32_e32 v24, v24, v25
	global_atomic_add_f32 v[28:29], v24, off offset:64
.LBB0_1273:
	s_or_b64 exec, exec, s[8:9]
	s_or_b32 s8, s87, 32
	v_or_b32_e32 v24, s8, v189
	s_waitcnt lgkmcnt(0)
	v_lshlrev_b32_e32 v25, 6, v24
	v_lshlrev_b32_e32 v24, 2, v24
	s_lshr_b32 s8, s8, 3
	v_and_b32_e32 v25, 0x3c0, v25
	v_and_b32_e32 v24, 32, v24
	v_add_lshl_u32 v27, v26, s8, 10
	v_bitop3_b32 v24, v25, v24, v188 bitop3:0x36
	v_add3_u32 v25, 0, v24, v27
	v_add_u32_e32 v27, s15, v25
	ds_read_b128 v[28:31], v27
	s_mov_b32 s8, 0x38800000
	s_waitcnt lgkmcnt(0)
	v_lshlrev_b32_e32 v128, 16, v28
	v_and_b32_e32 v129, 0xffff0000, v28
	v_lshlrev_b32_e32 v28, 16, v29
	v_and_b32_e32 v29, 0xffff0000, v29
	v_lshlrev_b32_e32 v130, 16, v30
	v_and_b32_e32 v131, 0xffff0000, v30
	v_lshlrev_b32_e32 v30, 16, v31
	v_and_b32_e32 v31, 0xffff0000, v31
	v_pk_fma_f32 v[126:127], v[126:127], s[8:9], v[28:29] op_sel_hi:[1,0,1]
	v_pk_fma_f32 v[124:125], v[124:125], s[8:9], v[128:129] op_sel_hi:[1,0,1]
	v_pk_fma_f32 v[128:129], v[122:123], s[8:9], v[30:31] op_sel_hi:[1,0,1]
	v_mul_f32_e32 v24, v125, v125
	v_mul_f32_e32 v122, v127, v127
	v_fmac_f32_e32 v24, v124, v124
	v_fmac_f32_e32 v122, v126, v126
	v_pk_fma_f32 v[120:121], v[120:121], s[8:9], v[130:131] op_sel_hi:[1,0,1]
	v_cvt_pk_bf16_f32 v28, v124, v125
	v_add_f32_e32 v124, v24, v122
	v_add_u32_e32 v24, 0x10000, v25
	v_mul_f32_e32 v125, v121, v121
	v_add_u32_e32 v130, s15, v24
	v_cvt_pk_bf16_f32 v29, v126, v127
	v_cvt_pk_bf16_f32 v30, v120, v121
	v_cvt_pk_bf16_f32 v31, v128, v129
	v_fmac_f32_e32 v125, v120, v120
	ds_read_b128 v[120:123], v130
	v_add_f32_e32 v124, v125, v124
	v_mul_f32_e32 v125, v129, v129
	v_fmac_f32_e32 v125, v128, v128
	v_add_f32_e32 v128, v125, v124
	s_waitcnt lgkmcnt(0)
	v_lshlrev_b32_e32 v124, 16, v120
	v_and_b32_e32 v125, 0xffff0000, v120
	v_lshlrev_b32_e32 v120, 16, v121
	v_and_b32_e32 v121, 0xffff0000, v121
	v_lshlrev_b32_e32 v126, 16, v122
	v_and_b32_e32 v127, 0xffff0000, v122
	v_lshlrev_b32_e32 v122, 16, v123
	v_and_b32_e32 v123, 0xffff0000, v123
	v_pk_fma_f32 v[118:119], v[118:119], s[8:9], v[120:121] op_sel_hi:[1,0,1]
	v_pk_fma_f32 v[116:117], v[116:117], s[8:9], v[124:125] op_sel_hi:[1,0,1]
	v_pk_fma_f32 v[120:121], v[114:115], s[8:9], v[122:123] op_sel_hi:[1,0,1]
	v_pk_fma_f32 v[114:115], v[112:113], s[8:9], v[126:127] op_sel_hi:[1,0,1]
	v_mul_f32_e32 v112, v117, v117
	v_mul_f32_e32 v113, v119, v119
	v_fmac_f32_e32 v112, v116, v116
	v_fmac_f32_e32 v113, v118, v118
	v_add_f32_e32 v112, v112, v113
	v_mul_f32_e32 v113, v115, v115
	v_fmac_f32_e32 v113, v114, v114
	v_add_f32_e32 v112, v113, v112
	v_mul_f32_e32 v113, v121, v121
	v_fmac_f32_e32 v113, v120, v120
	v_add_f32_e32 v112, v113, v112
	v_add_f32_e32 v113, v128, v112
	v_mov_b32_e32 v122, v113
	s_nop 1
	v_permlane16_swap_b32 v122, v113
	ds_write_b128 v27, v[28:31]
	v_cvt_pk_bf16_f32 v112, v116, v117
	s_waitcnt lgkmcnt(0)
	v_add_f32_e32 v27, v113, v122
	v_mov_b32_e32 v28, v27
	s_nop 1
	v_permlane32_swap_b32 v28, v27
	v_cvt_pk_bf16_f32 v113, v118, v119
	v_cvt_pk_bf16_f32 v114, v114, v115
	v_cvt_pk_bf16_f32 v115, v120, v121
	ds_write_b128 v130, v[112:115]
	s_and_saveexec_b64 s[16:17], vcc
	s_cbranch_execz .LBB0_1275
	v_lshl_add_u64 v[30:31], v[16:17], 2, s[12:13]
	s_waitcnt lgkmcnt(0)
	v_add_f32_e32 v27, v27, v28
	global_atomic_add_f32 v[30:31], v27, off offset:128
.LBB0_1275:
	s_or_b64 exec, exec, s[16:17]
	s_or_b32 s9, s87, 48
	v_or_b32_e32 v27, s9, v189
	s_waitcnt lgkmcnt(0)
	v_lshlrev_b32_e32 v28, 6, v27
	v_lshlrev_b32_e32 v27, 2, v27
	s_lshr_b32 s9, s9, 3
	v_and_b32_e32 v28, 0x3c0, v28
	v_and_b32_e32 v27, 32, v27
	v_add_lshl_u32 v26, v26, s9, 10
	v_bitop3_b32 v27, v28, v27, v188 bitop3:0x36
	v_add3_u32 v27, 0, v27, v26
	v_add_u32_e32 v116, s15, v27
	ds_read_b128 v[28:31], v116
	s_waitcnt lgkmcnt(0)
	v_lshlrev_b32_e32 v112, 16, v28
	v_and_b32_e32 v113, 0xffff0000, v28
	v_lshlrev_b32_e32 v28, 16, v29
	v_and_b32_e32 v29, 0xffff0000, v29
	v_lshlrev_b32_e32 v114, 16, v30
	v_and_b32_e32 v115, 0xffff0000, v30
	v_lshlrev_b32_e32 v30, 16, v31
	v_and_b32_e32 v31, 0xffff0000, v31
	v_pk_fma_f32 v[110:111], v[110:111], s[8:9], v[28:29] op_sel_hi:[1,0,1]
	v_pk_fma_f32 v[108:109], v[108:109], s[8:9], v[112:113] op_sel_hi:[1,0,1]
	v_pk_fma_f32 v[112:113], v[106:107], s[8:9], v[30:31] op_sel_hi:[1,0,1]
	v_mul_f32_e32 v26, v109, v109
	v_mul_f32_e32 v106, v111, v111
	v_fmac_f32_e32 v26, v108, v108
	v_fmac_f32_e32 v106, v110, v110
	v_pk_fma_f32 v[104:105], v[104:105], s[8:9], v[114:115] op_sel_hi:[1,0,1]
	v_cvt_pk_bf16_f32 v28, v108, v109
	v_add_f32_e32 v108, v26, v106
	v_add_u32_e32 v26, 0x10000, v27
	v_mul_f32_e32 v109, v105, v105
	v_add_u32_e32 v114, s15, v26
	v_cvt_pk_bf16_f32 v29, v110, v111
	v_cvt_pk_bf16_f32 v30, v104, v105
	v_cvt_pk_bf16_f32 v31, v112, v113
	v_fmac_f32_e32 v109, v104, v104
	ds_read_b128 v[104:107], v114
	v_add_f32_e32 v108, v109, v108
	v_mul_f32_e32 v109, v113, v113
	v_fmac_f32_e32 v109, v112, v112
	v_add_f32_e32 v112, v109, v108
	s_waitcnt lgkmcnt(0)
	v_lshlrev_b32_e32 v108, 16, v104
	v_and_b32_e32 v109, 0xffff0000, v104
	v_lshlrev_b32_e32 v104, 16, v105
	v_and_b32_e32 v105, 0xffff0000, v105
	v_lshlrev_b32_e32 v110, 16, v106
	v_and_b32_e32 v111, 0xffff0000, v106
	v_lshlrev_b32_e32 v106, 16, v107
	v_and_b32_e32 v107, 0xffff0000, v107
	v_pk_fma_f32 v[102:103], v[102:103], s[8:9], v[104:105] op_sel_hi:[1,0,1]
	v_pk_fma_f32 v[100:101], v[100:101], s[8:9], v[108:109] op_sel_hi:[1,0,1]
	v_pk_fma_f32 v[104:105], v[98:99], s[8:9], v[106:107] op_sel_hi:[1,0,1]
	v_pk_fma_f32 v[98:99], v[96:97], s[8:9], v[110:111] op_sel_hi:[1,0,1]
	v_mul_f32_e32 v96, v101, v101
	v_mul_f32_e32 v97, v103, v103
	v_fmac_f32_e32 v96, v100, v100
	v_fmac_f32_e32 v97, v102, v102
	v_add_f32_e32 v96, v96, v97
	v_mul_f32_e32 v97, v99, v99
	v_fmac_f32_e32 v97, v98, v98
	v_add_f32_e32 v96, v97, v96
	v_mul_f32_e32 v97, v105, v105
	v_fmac_f32_e32 v97, v104, v104
	v_add_f32_e32 v96, v97, v96
	v_add_f32_e32 v97, v112, v96
	v_mov_b32_e32 v106, v97
	s_nop 1
	v_permlane16_swap_b32 v106, v97
	ds_write_b128 v116, v[28:31]
	v_cvt_pk_bf16_f32 v96, v100, v101
	s_waitcnt lgkmcnt(0)
	v_add_f32_e32 v28, v97, v106
	v_mov_b32_e32 v29, v28
	s_nop 1
	v_permlane32_swap_b32 v29, v28
	v_cvt_pk_bf16_f32 v97, v102, v103
	v_cvt_pk_bf16_f32 v98, v98, v99
	v_cvt_pk_bf16_f32 v99, v104, v105
	ds_write_b128 v114, v[96:99]
	s_and_saveexec_b64 s[8:9], vcc
	s_cbranch_execz .LBB0_1277
	v_lshl_add_u64 v[30:31], v[16:17], 2, s[12:13]
	s_waitcnt lgkmcnt(0)
	v_add_f32_e32 v28, v28, v29
	global_atomic_add_f32 v[30:31], v28, off offset:192
.LBB0_1277:
	s_or_b64 exec, exec, s[8:9]
	s_bitset1_b32 s11, 14
	v_add_u32_e32 v96, s11, v21
	s_waitcnt lgkmcnt(0)
	ds_read_b128 v[28:31], v96
	s_mov_b32 s8, 0x38800000
	s_waitcnt vmcnt(0) lgkmcnt(0)
	v_cndmask_b32_e64 v21, v31, v15, s[6:7]
	v_cndmask_b32_e64 v15, v29, v13, s[6:7]
	v_cndmask_b32_e64 v13, v28, v12, s[6:7]
	v_cndmask_b32_e64 v30, v30, v14, s[6:7]
	v_lshlrev_b32_e32 v12, 16, v13
	v_and_b32_e32 v13, 0xffff0000, v13
	v_lshlrev_b32_e32 v14, 16, v15
	v_and_b32_e32 v15, 0xffff0000, v15
	v_lshlrev_b32_e32 v28, 16, v30
	v_and_b32_e32 v29, 0xffff0000, v30
	v_lshlrev_b32_e32 v30, 16, v21
	v_and_b32_e32 v31, 0xffff0000, v21
	v_pk_fma_f32 v[94:95], v[94:95], s[8:9], v[14:15] op_sel_hi:[1,0,1]
	v_pk_fma_f32 v[92:93], v[92:93], s[8:9], v[12:13] op_sel_hi:[1,0,1]
	v_pk_fma_f32 v[90:91], v[90:91], s[8:9], v[30:31] op_sel_hi:[1,0,1]
	v_pk_fma_f32 v[28:29], v[88:89], s[8:9], v[28:29] op_sel_hi:[1,0,1]
	v_mul_f32_e32 v21, v93, v93
	v_mul_f32_e32 v30, v95, v95
	v_cvt_pk_bf16_f32 v12, v92, v93
	v_fmac_f32_e32 v21, v92, v92
	v_fmac_f32_e32 v30, v94, v94
	v_mul_f32_e32 v88, v29, v29
	v_add_u32_e32 v92, s11, v20
	v_cvt_pk_bf16_f32 v13, v94, v95
	v_cvt_pk_bf16_f32 v14, v28, v29
	v_cvt_pk_bf16_f32 v15, v90, v91
	v_add_f32_e32 v21, v21, v30
	v_fmac_f32_e32 v88, v28, v28
	ds_read_b128 v[28:31], v92
	v_add_f32_e32 v20, v88, v21
	v_mul_f32_e32 v21, v91, v91
	v_fmac_f32_e32 v21, v90, v90
	v_add_f32_e32 v90, v21, v20
	s_waitcnt lgkmcnt(0)
	v_lshlrev_b32_e32 v20, 16, v28
	v_and_b32_e32 v21, 0xffff0000, v28
	v_lshlrev_b32_e32 v28, 16, v29
	v_and_b32_e32 v29, 0xffff0000, v29
	v_pk_fma_f32 v[86:87], v[86:87], s[8:9], v[28:29] op_sel_hi:[1,0,1]
	v_pk_fma_f32 v[20:21], v[84:85], s[8:9], v[20:21] op_sel_hi:[1,0,1]
	v_lshlrev_b32_e32 v88, 16, v30
	v_and_b32_e32 v89, 0xffff0000, v30
	v_lshlrev_b32_e32 v30, 16, v31
	v_and_b32_e32 v31, 0xffff0000, v31
	v_mul_f32_e32 v28, v21, v21
	v_mul_f32_e32 v29, v87, v87
	v_pk_fma_f32 v[82:83], v[82:83], s[8:9], v[30:31] op_sel_hi:[1,0,1]
	v_pk_fma_f32 v[30:31], v[80:81], s[8:9], v[88:89] op_sel_hi:[1,0,1]
	v_fmac_f32_e32 v28, v20, v20
	v_fmac_f32_e32 v29, v86, v86
	v_add_f32_e32 v28, v28, v29
	v_mul_f32_e32 v29, v31, v31
	v_fmac_f32_e32 v29, v30, v30
	v_add_f32_e32 v28, v29, v28
	v_mul_f32_e32 v29, v83, v83
	v_fmac_f32_e32 v29, v82, v82
	v_add_f32_e32 v28, v29, v28
	v_add_f32_e32 v29, v90, v28
	v_mov_b32_e32 v80, v29
	s_nop 1
	v_permlane16_swap_b32 v80, v29
	ds_write_b128 v96, v[12:15]
	v_cvt_pk_bf16_f32 v28, v20, v21
	s_waitcnt lgkmcnt(1)
	v_add_f32_e32 v12, v29, v80
	v_mov_b32_e32 v13, v12
	s_nop 1
	v_permlane32_swap_b32 v13, v12
	v_cvt_pk_bf16_f32 v29, v86, v87
	v_cvt_pk_bf16_f32 v30, v30, v31
	v_cvt_pk_bf16_f32 v31, v82, v83
	ds_write_b128 v92, v[28:31]
	s_and_saveexec_b64 s[16:17], vcc
	s_cbranch_execz .LBB0_1279
	v_lshl_add_u64 v[14:15], v[16:17], 2, s[12:13]
	s_waitcnt lgkmcnt(1)
	v_add_f32_e32 v12, v12, v13
	global_atomic_add_f32 v[14:15], v12, off offset:512
.LBB0_1279:
	s_or_b64 exec, exec, s[16:17]
	v_add_u32_e32 v80, s11, v23
	s_waitcnt lgkmcnt(1)
	ds_read_b128 v[12:15], v80
	s_waitcnt lgkmcnt(0)
	v_cndmask_b32_e64 v15, v15, v11, s[6:7]
	v_cndmask_b32_e64 v11, v13, v9, s[6:7]
	v_cndmask_b32_e64 v9, v12, v8, s[6:7]
	v_cndmask_b32_e64 v14, v14, v10, s[6:7]
	v_lshlrev_b32_e32 v8, 16, v9
	v_and_b32_e32 v9, 0xffff0000, v9
	v_lshlrev_b32_e32 v10, 16, v11
	v_and_b32_e32 v11, 0xffff0000, v11
	v_lshlrev_b32_e32 v12, 16, v14
	v_and_b32_e32 v13, 0xffff0000, v14
	v_lshlrev_b32_e32 v14, 16, v15
	v_and_b32_e32 v15, 0xffff0000, v15
	v_pk_fma_f32 v[20:21], v[78:79], s[8:9], v[10:11] op_sel_hi:[1,0,1]
	v_pk_fma_f32 v[28:29], v[76:77], s[8:9], v[8:9] op_sel_hi:[1,0,1]
	v_pk_fma_f32 v[30:31], v[74:75], s[8:9], v[14:15] op_sel_hi:[1,0,1]
	v_pk_fma_f32 v[12:13], v[72:73], s[8:9], v[12:13] op_sel_hi:[1,0,1]
	v_mul_f32_e32 v14, v29, v29
	v_mul_f32_e32 v15, v21, v21
	v_cvt_pk_bf16_f32 v8, v28, v29
	v_cvt_pk_bf16_f32 v9, v20, v21
	v_fmac_f32_e32 v14, v28, v28
	v_fmac_f32_e32 v15, v20, v20
	v_mul_f32_e32 v21, v13, v13
	v_add_u32_e32 v28, s11, v22
	v_cvt_pk_bf16_f32 v10, v12, v13
	v_cvt_pk_bf16_f32 v11, v30, v31
	v_add_f32_e32 v20, v14, v15
	v_fmac_f32_e32 v21, v12, v12
	ds_read_b128 v[12:15], v28
	v_add_f32_e32 v20, v21, v20
	v_mul_f32_e32 v21, v31, v31
	v_fmac_f32_e32 v21, v30, v30
	v_add_f32_e32 v29, v21, v20
	s_waitcnt lgkmcnt(0)
	v_lshlrev_b32_e32 v20, 16, v12
	v_and_b32_e32 v21, 0xffff0000, v12
	v_lshlrev_b32_e32 v12, 16, v13
	v_and_b32_e32 v13, 0xffff0000, v13
	v_pk_fma_f32 v[12:13], v[70:71], s[8:9], v[12:13] op_sel_hi:[1,0,1]
	v_pk_fma_f32 v[20:21], v[68:69], s[8:9], v[20:21] op_sel_hi:[1,0,1]
	v_lshlrev_b32_e32 v22, 16, v14
	v_and_b32_e32 v23, 0xffff0000, v14
	v_mul_f32_e32 v30, v21, v21
	v_mul_f32_e32 v31, v13, v13
	v_pk_fma_f32 v[22:23], v[64:65], s[8:9], v[22:23] op_sel_hi:[1,0,1]
	v_fmac_f32_e32 v30, v20, v20
	v_fmac_f32_e32 v31, v12, v12
	v_lshlrev_b32_e32 v14, 16, v15
	v_and_b32_e32 v15, 0xffff0000, v15
	v_add_f32_e32 v30, v30, v31
	v_mul_f32_e32 v31, v23, v23
	v_pk_fma_f32 v[14:15], v[66:67], s[8:9], v[14:15] op_sel_hi:[1,0,1]
	v_fmac_f32_e32 v31, v22, v22
	v_add_f32_e32 v30, v31, v30
	v_mul_f32_e32 v31, v15, v15
	v_fmac_f32_e32 v31, v14, v14
	v_add_f32_e32 v30, v31, v30
	v_add_f32_e32 v29, v29, v30
	v_mov_b32_e32 v30, v29
	s_nop 1
	v_permlane16_swap_b32 v30, v29
	ds_write_b128 v80, v[8:11]
	v_cvt_pk_bf16_f32 v10, v20, v21
	v_cvt_pk_bf16_f32 v11, v12, v13
	v_cvt_pk_bf16_f32 v12, v22, v23
	s_waitcnt lgkmcnt(1)
	v_add_f32_e32 v8, v29, v30
	v_mov_b32_e32 v9, v8
	s_nop 1
	v_permlane32_swap_b32 v9, v8
	v_cvt_pk_bf16_f32 v13, v14, v15
	ds_write_b128 v28, v[10:13]
	s_and_saveexec_b64 s[8:9], vcc
	s_cbranch_execz .LBB0_1281
	v_lshl_add_u64 v[10:11], v[16:17], 2, s[12:13]
	s_waitcnt lgkmcnt(1)
	v_add_f32_e32 v8, v8, v9
	global_atomic_add_f32 v[10:11], v8, off offset:576
.LBB0_1281:
	s_or_b64 exec, exec, s[8:9]
	v_add_u32_e32 v22, s11, v25
	s_waitcnt lgkmcnt(1)
	ds_read_b128 v[8:11], v22
	s_mov_b32 s8, 0x38800000
	v_add_u32_e32 v23, s11, v24
	s_waitcnt lgkmcnt(0)
	v_cndmask_b32_e64 v11, v11, v7, s[6:7]
	v_cndmask_b32_e64 v7, v9, v5, s[6:7]
	v_cndmask_b32_e64 v5, v8, v4, s[6:7]
	v_cndmask_b32_e64 v10, v10, v6, s[6:7]
	v_lshlrev_b32_e32 v4, 16, v5
	v_and_b32_e32 v5, 0xffff0000, v5
	v_lshlrev_b32_e32 v6, 16, v7
	v_and_b32_e32 v7, 0xffff0000, v7
	v_lshlrev_b32_e32 v8, 16, v10
	v_and_b32_e32 v9, 0xffff0000, v10
	v_lshlrev_b32_e32 v10, 16, v11
	v_and_b32_e32 v11, 0xffff0000, v11
	v_pk_fma_f32 v[12:13], v[62:63], s[8:9], v[6:7] op_sel_hi:[1,0,1]
	v_pk_fma_f32 v[14:15], v[60:61], s[8:9], v[4:5] op_sel_hi:[1,0,1]
	v_pk_fma_f32 v[20:21], v[58:59], s[8:9], v[10:11] op_sel_hi:[1,0,1]
	v_pk_fma_f32 v[8:9], v[56:57], s[8:9], v[8:9] op_sel_hi:[1,0,1]
	v_mul_f32_e32 v10, v15, v15
	v_mul_f32_e32 v11, v13, v13
	v_cvt_pk_bf16_f32 v4, v14, v15
	v_cvt_pk_bf16_f32 v5, v12, v13
	v_fmac_f32_e32 v10, v14, v14
	v_fmac_f32_e32 v11, v12, v12
	v_mul_f32_e32 v13, v9, v9
	v_cvt_pk_bf16_f32 v6, v8, v9
	v_cvt_pk_bf16_f32 v7, v20, v21
	v_add_f32_e32 v12, v10, v11
	v_fmac_f32_e32 v13, v8, v8
	ds_read_b128 v[8:11], v23
	v_add_f32_e32 v12, v13, v12
	v_mul_f32_e32 v13, v21, v21
	v_fmac_f32_e32 v13, v20, v20
	v_add_f32_e32 v20, v13, v12
	s_waitcnt lgkmcnt(0)
	v_lshlrev_b32_e32 v12, 16, v8
	v_and_b32_e32 v13, 0xffff0000, v8
	v_lshlrev_b32_e32 v8, 16, v9
	v_and_b32_e32 v9, 0xffff0000, v9
	v_pk_fma_f32 v[8:9], v[54:55], s[8:9], v[8:9] op_sel_hi:[1,0,1]
	v_pk_fma_f32 v[12:13], v[52:53], s[8:9], v[12:13] op_sel_hi:[1,0,1]
	v_lshlrev_b32_e32 v14, 16, v10
	v_and_b32_e32 v15, 0xffff0000, v10
	v_mul_f32_e32 v21, v13, v13
	v_mul_f32_e32 v24, v9, v9
	v_pk_fma_f32 v[14:15], v[48:49], s[8:9], v[14:15] op_sel_hi:[1,0,1]
	v_fmac_f32_e32 v21, v12, v12
	v_fmac_f32_e32 v24, v8, v8
	v_lshlrev_b32_e32 v10, 16, v11
	v_and_b32_e32 v11, 0xffff0000, v11
	v_add_f32_e32 v21, v21, v24
	v_mul_f32_e32 v24, v15, v15
	v_pk_fma_f32 v[10:11], v[50:51], s[8:9], v[10:11] op_sel_hi:[1,0,1]
	v_fmac_f32_e32 v24, v14, v14
	v_add_f32_e32 v21, v24, v21
	v_mul_f32_e32 v24, v11, v11
	v_fmac_f32_e32 v24, v10, v10
	v_add_f32_e32 v21, v24, v21
	v_add_f32_e32 v20, v20, v21
	v_mov_b32_e32 v21, v20
	s_nop 1
	v_permlane16_swap_b32 v21, v20
	ds_write_b128 v22, v[4:7]
	v_cvt_pk_bf16_f32 v6, v12, v13
	v_cvt_pk_bf16_f32 v7, v8, v9
	v_cvt_pk_bf16_f32 v8, v14, v15
	s_waitcnt lgkmcnt(1)
	v_add_f32_e32 v4, v20, v21
	v_mov_b32_e32 v5, v4
	s_nop 1
	v_permlane32_swap_b32 v5, v4
	v_cvt_pk_bf16_f32 v9, v10, v11
	ds_write_b128 v23, v[6:9]
	s_and_saveexec_b64 s[16:17], vcc
	s_cbranch_execz .LBB0_1283
	v_lshl_add_u64 v[6:7], v[16:17], 2, s[12:13]
	s_waitcnt lgkmcnt(1)
	v_add_f32_e32 v4, v4, v5
	global_atomic_add_f32 v[6:7], v4, off offset:640
.LBB0_1283:
	s_or_b64 exec, exec, s[16:17]
	v_add_u32_e32 v14, s11, v27
	s_waitcnt lgkmcnt(1)
	ds_read_b128 v[4:7], v14
	v_add_u32_e32 v15, s11, v26
	s_waitcnt lgkmcnt(0)
	v_cndmask_b32_e64 v7, v7, v3, s[6:7]
	v_cndmask_b32_e64 v3, v5, v1, s[6:7]
	v_cndmask_b32_e64 v1, v4, v0, s[6:7]
	v_cndmask_b32_e64 v6, v6, v2, s[6:7]
	v_lshlrev_b32_e32 v0, 16, v1
	v_and_b32_e32 v1, 0xffff0000, v1
	v_lshlrev_b32_e32 v2, 16, v3
	v_and_b32_e32 v3, 0xffff0000, v3
	v_lshlrev_b32_e32 v4, 16, v6
	v_and_b32_e32 v5, 0xffff0000, v6
	v_lshlrev_b32_e32 v6, 16, v7
	v_and_b32_e32 v7, 0xffff0000, v7
	v_pk_fma_f32 v[8:9], v[46:47], s[8:9], v[2:3] op_sel_hi:[1,0,1]
	v_pk_fma_f32 v[10:11], v[44:45], s[8:9], v[0:1] op_sel_hi:[1,0,1]
	v_pk_fma_f32 v[12:13], v[42:43], s[8:9], v[6:7] op_sel_hi:[1,0,1]
	v_pk_fma_f32 v[4:5], v[40:41], s[8:9], v[4:5] op_sel_hi:[1,0,1]
	v_mul_f32_e32 v6, v11, v11
	v_mul_f32_e32 v7, v9, v9
	v_cvt_pk_bf16_f32 v0, v10, v11
	v_cvt_pk_bf16_f32 v1, v8, v9
	v_fmac_f32_e32 v6, v10, v10
	v_fmac_f32_e32 v7, v8, v8
	v_mul_f32_e32 v9, v5, v5
	v_cvt_pk_bf16_f32 v2, v4, v5
	v_cvt_pk_bf16_f32 v3, v12, v13
	v_add_f32_e32 v8, v6, v7
	v_fmac_f32_e32 v9, v4, v4
	ds_read_b128 v[4:7], v15
	v_add_f32_e32 v8, v9, v8
	v_mul_f32_e32 v9, v13, v13
	v_fmac_f32_e32 v9, v12, v12
	v_add_f32_e32 v12, v9, v8
	s_waitcnt lgkmcnt(0)
	v_lshlrev_b32_e32 v8, 16, v4
	v_and_b32_e32 v9, 0xffff0000, v4
	v_lshlrev_b32_e32 v4, 16, v5
	v_and_b32_e32 v5, 0xffff0000, v5
	v_pk_fma_f32 v[4:5], v[38:39], s[8:9], v[4:5] op_sel_hi:[1,0,1]
	v_pk_fma_f32 v[8:9], v[36:37], s[8:9], v[8:9] op_sel_hi:[1,0,1]
	v_lshlrev_b32_e32 v10, 16, v6
	v_and_b32_e32 v11, 0xffff0000, v6
	v_mul_f32_e32 v13, v9, v9
	v_mul_f32_e32 v20, v5, v5
	v_pk_fma_f32 v[10:11], v[32:33], s[8:9], v[10:11] op_sel_hi:[1,0,1]
	v_fmac_f32_e32 v13, v8, v8
	v_fmac_f32_e32 v20, v4, v4
	v_lshlrev_b32_e32 v6, 16, v7
	v_and_b32_e32 v7, 0xffff0000, v7
	v_add_f32_e32 v13, v13, v20
	v_mul_f32_e32 v20, v11, v11
	v_pk_fma_f32 v[6:7], v[34:35], s[8:9], v[6:7] op_sel_hi:[1,0,1]
	v_fmac_f32_e32 v20, v10, v10
	v_add_f32_e32 v13, v20, v13
	v_mul_f32_e32 v20, v7, v7
	v_fmac_f32_e32 v20, v6, v6
	v_add_f32_e32 v13, v20, v13
	v_add_f32_e32 v12, v12, v13
	v_mov_b32_e32 v13, v12
	s_nop 1
	v_permlane16_swap_b32 v13, v12
	ds_write_b128 v14, v[0:3]
	v_cvt_pk_bf16_f32 v2, v8, v9
	v_cvt_pk_bf16_f32 v3, v4, v5
	v_cvt_pk_bf16_f32 v4, v10, v11
	s_waitcnt lgkmcnt(1)
	v_add_f32_e32 v0, v12, v13
	v_mov_b32_e32 v1, v0
	s_nop 1
	v_permlane32_swap_b32 v1, v0
	v_cvt_pk_bf16_f32 v5, v6, v7
	ds_write_b128 v15, v[2:5]
	s_and_saveexec_b64 s[6:7], vcc
	s_cbranch_execz .LBB0_1285
	v_lshl_add_u64 v[2:3], v[16:17], 2, s[12:13]
	s_waitcnt lgkmcnt(1)
	v_add_f32_e32 v0, v0, v1
	global_atomic_add_f32 v[2:3], v0, off offset:704

.LBB0_1359:
	v_lshl_add_u32 v152, s8, 8, v188
	v_ashrrev_i32_e32 v153, 31, v152
	v_lshl_add_u64 v[154:155], v[152:153], 2, s[12:13]
	global_load_dword v168, v[154:155], off
	v_lshl_add_u32 v144, s30, 8, v190
	v_ashrrev_i32_e32 v145, 31, v144
	v_lshlrev_b64 v[146:147], 11, v[152:153]
	v_lshl_add_u64 v[146:147], v[146:147], 0, v[144:145]
	v_lshlrev_b64 v[156:157], 1, v[146:147]
	v_lshl_add_u64 v[160:161], s[52:53], 0, v[156:157]
	v_lshl_add_u64 v[164:165], s[58:59], 0, v[156:157]
	global_load_dwordx4 v[148:151], v[160:161], off
	global_load_dwordx4 v[156:159], v[164:165], off
	v_and_b32_e32 v163, 64, v194
	v_xor_b32_e32 v162, 16, v194
	v_add_u32_e32 v178, 64, v163
	v_cmp_lt_i32_e32 vcc, v162, v178
	s_waitcnt vmcnt(0)
	v_fmamk_f32 v168, v168, 0x3a000000, v195
	v_cndmask_b32_e32 v162, v194, v162, vcc
	v_lshlrev_b32_e32 v196, 2, v162
	global_load_dwordx4 v[160:163], v[160:161], off offset:256
	s_nop 0
	global_load_dwordx4 v[164:167], v[164:165], off offset:256
	v_mul_f32_e32 v169, 0x4b800000, v168
	v_cmp_gt_f32_e32 vcc, s61, v168
	v_lshlrev_b32_e32 v172, 16, v150
	s_nop 0
	v_cndmask_b32_e32 v168, v168, v169, vcc
	v_rsq_f32_e32 v176, v168
	v_lshlrev_b32_e32 v168, 16, v148
	v_and_b32_e32 v169, 0xffff0000, v148
	v_lshlrev_b32_e32 v170, 16, v156
	v_mul_f32_e32 v177, 0x45800000, v176
	v_cndmask_b32_e32 v179, v176, v177, vcc
	v_mul_f32_e32 v124, v124, v179
	v_mul_f32_e32 v120, v120, v179
	v_mul_f32_e32 v125, v125, v179
	v_mul_f32_e32 v121, v121, v179
	v_mul_f32_e32 v126, v126, v179
	v_mul_f32_e32 v122, v122, v179
	v_mul_f32_e32 v127, v127, v179
	v_mul_f32_e32 v123, v123, v179
	v_mul_f32_e32 v116, v116, v179
	v_mul_f32_e32 v124, 0xbfb8aa3b, v124
	v_mul_f32_e32 v120, 0xbfb8aa3b, v120
	v_mul_f32_e32 v125, 0xbfb8aa3b, v125
	v_mul_f32_e32 v121, 0xbfb8aa3b, v121
	v_mul_f32_e32 v126, 0xbfb8aa3b, v126
	v_mul_f32_e32 v122, 0xbfb8aa3b, v122
	v_mul_f32_e32 v127, 0xbfb8aa3b, v127
	v_mul_f32_e32 v123, 0xbfb8aa3b, v123
	v_mul_f32_e32 v116, 0xbfb8aa3b, v116
	v_exp_f32_e32 v124, v124
	v_exp_f32_e32 v120, v120
	v_exp_f32_e32 v125, v125
	v_exp_f32_e32 v121, v121
	v_exp_f32_e32 v126, v126
	v_exp_f32_e32 v122, v122
	v_exp_f32_e32 v127, v127
	v_exp_f32_e32 v123, v123
	v_exp_f32_e32 v116, v116
	v_mul_f32_e32 v117, v117, v179
	v_mul_f32_e32 v117, 0xbfb8aa3b, v117
	v_mul_f32_e32 v112, v112, v179
	v_exp_f32_e32 v177, v117
	v_add_f32_e32 v117, 1.0, v124
	v_add_f32_e32 v120, 1.0, v120
	v_add_f32_e32 v124, 1.0, v125
	v_add_f32_e32 v121, 1.0, v121
	v_add_f32_e32 v125, 1.0, v126
	v_add_f32_e32 v122, 1.0, v122
	v_add_f32_e32 v127, 1.0, v127
	v_add_f32_e32 v123, 1.0, v123
	v_mul_f32_e32 v113, v113, v179
	v_mul_f32_e32 v112, 0xbfb8aa3b, v112
	v_add_f32_e32 v176, 1.0, v116
	v_rcp_f32_e32 v116, v117
	v_rcp_f32_e32 v120, v120
	v_rcp_f32_e32 v117, v124
	v_rcp_f32_e32 v121, v121
	v_rcp_f32_e32 v124, v125
	v_rcp_f32_e32 v126, v122
	v_rcp_f32_e32 v125, v127
	v_rcp_f32_e32 v127, v123
	v_mul_f32_e32 v113, 0xbfb8aa3b, v113
	v_exp_f32_e32 v112, v112
	v_exp_f32_e32 v113, v113
	v_and_b32_e32 v171, 0xffff0000, v156
	v_and_b32_e32 v173, 0xffff0000, v150
	v_lshlrev_b32_e32 v174, 16, v158
	v_and_b32_e32 v175, 0xffff0000, v158
	v_lshlrev_b32_e32 v150, 16, v151
	v_and_b32_e32 v151, 0xffff0000, v151
	v_lshlrev_b32_e32 v158, 16, v159
	v_and_b32_e32 v159, 0xffff0000, v159
	v_pk_fma_f32 v[122:123], v[116:117], v[170:171], v[168:169]
	v_pk_fma_f32 v[116:117], v[120:121], v[174:175], v[172:173]
	v_pk_fma_f32 v[120:121], v[126:127], v[158:159], v[150:151]
	v_add_f32_e32 v126, 1.0, v177
	v_add_f32_e32 v112, 1.0, v112
	v_rcp_f32_e32 v176, v176
	v_rcp_f32_e32 v177, v126
	v_add_f32_e32 v113, 1.0, v113
	v_rcp_f32_e32 v112, v112
	v_rcp_f32_e32 v113, v113
	v_lshlrev_b32_e32 v148, 16, v149
	v_and_b32_e32 v149, 0xffff0000, v149
	v_lshlrev_b32_e32 v156, 16, v157
	v_and_b32_e32 v157, 0xffff0000, v157
	v_pk_fma_f32 v[124:125], v[124:125], v[156:157], v[148:149]
	s_waitcnt vmcnt(1)
	v_lshlrev_b32_e32 v126, 16, v160
	v_and_b32_e32 v127, 0xffff0000, v160
	s_waitcnt vmcnt(0)
	v_lshlrev_b32_e32 v148, 16, v164
	v_and_b32_e32 v149, 0xffff0000, v164
	v_pk_fma_f32 v[126:127], v[176:177], v[148:149], v[126:127]
	v_lshlrev_b32_e32 v148, 16, v162
	v_and_b32_e32 v149, 0xffff0000, v162
	v_lshlrev_b32_e32 v170, 16, v166
	v_and_b32_e32 v171, 0xffff0000, v166
	v_pk_fma_f32 v[148:149], v[112:113], v[170:171], v[148:149]
	v_mul_f32_e32 v113, v114, v179
	v_mul_f32_e32 v118, v118, v179
	v_mul_f32_e32 v113, 0xbfb8aa3b, v113
	v_mul_f32_e32 v114, v119, v179
	v_mul_f32_e32 v118, 0xbfb8aa3b, v118
	v_exp_f32_e32 v113, v113
	v_mul_f32_e32 v114, 0xbfb8aa3b, v114
	v_exp_f32_e32 v118, v118
	v_exp_f32_e32 v114, v114
	v_add_f32_e32 v113, 1.0, v113
	v_lshlrev_b32_e32 v160, 16, v161
	v_add_f32_e32 v112, 1.0, v118
	v_rcp_f32_e32 v118, v113
	v_add_f32_e32 v113, 1.0, v114
	v_mul_f32_e32 v114, v115, v179
	v_mul_f32_e32 v114, 0xbfb8aa3b, v114
	v_rcp_f32_e32 v112, v112
	v_rcp_f32_e32 v113, v113
	v_exp_f32_e32 v119, v114
	v_and_b32_e32 v161, 0xffff0000, v161
	v_lshlrev_b32_e32 v114, 16, v165
	v_and_b32_e32 v115, 0xffff0000, v165
	v_pk_fma_f32 v[114:115], v[112:113], v[114:115], v[160:161]
	v_add_f32_e32 v112, 1.0, v119
	v_rcp_f32_e32 v119, v112
	v_lshlrev_b32_e32 v112, 16, v163
	v_and_b32_e32 v113, 0xffff0000, v163
	v_lshlrev_b32_e32 v160, 16, v167
	v_and_b32_e32 v161, 0xffff0000, v167
	v_pk_fma_f32 v[118:119], v[118:119], v[160:161], v[112:113]
	v_pk_mul_f32 v[112:113], v[126:127], v[126:127]
	v_pk_mul_f32 v[160:161], v[114:115], v[114:115]
	v_pk_mul_f32 v[162:163], v[148:149], v[148:149]
	v_add_f32_e32 v160, v160, v161
	v_add_f32_e32 v112, v112, v113
	v_pk_mul_f32 v[164:165], v[118:119], v[118:119]
	v_add_f32_e32 v112, v112, v160
	v_add_f32_e32 v113, v162, v163
	v_pk_mul_f32 v[150:151], v[122:123], v[122:123]
	v_pk_mul_f32 v[156:157], v[124:125], v[124:125]
	v_add_f32_e32 v112, v113, v112
	v_add_f32_e32 v113, v164, v165
	v_pk_mul_f32 v[158:159], v[116:117], v[116:117]
	v_add_f32_e32 v112, v113, v112
	v_add_f32_e32 v113, v156, v157
	v_add_f32_e32 v150, v150, v151
	v_pk_mul_f32 v[168:169], v[120:121], v[120:121]
	v_add_f32_e32 v113, v150, v113
	v_add_f32_e32 v150, v158, v159
	v_add_f32_e32 v113, v150, v113
	v_add_f32_e32 v150, v168, v169
	v_add_f32_e32 v113, v150, v113
	v_add_f32_e32 v112, v113, v112
	v_mov_b32_e32 v113, v112
	s_nop 1
	v_permlane16_swap_b32 v113, v112
	v_xor_b32_e32 v150, 32, v194
	v_cmp_lt_i32_e32 vcc, v150, v178
	s_nop 1
	v_cndmask_b32_e32 v150, v194, v150, vcc
	v_lshlrev_b32_e32 v197, 2, v150
	s_waitcnt lgkmcnt(0)
	v_add_f32_e32 v150, v112, v113
	v_mov_b32_e32 v151, v150
	s_nop 1
	v_permlane32_swap_b32 v151, v150
	v_lshl_add_u64 v[112:113], v[152:153], 2, s[16:17]
	s_and_saveexec_b64 s[30:31], s[0:1]
	s_cbranch_execz .LBB0_1361
	s_waitcnt lgkmcnt(0)
	v_add_f32_e32 v150, v150, v151
	global_atomic_add_f32 v[112:113], v150, off
.LBB0_1361:
	s_or_b64 exec, exec, s[30:31]
	v_or_b32_e32 v156, 16, v152
	v_ashrrev_i32_e32 v157, 31, v156
	s_waitcnt lgkmcnt(0)
	v_lshl_add_u64 v[150:151], v[156:157], 2, s[12:13]
	global_load_dword v153, v[150:151], off
	v_lshlrev_b64 v[150:151], 11, v[156:157]
	v_lshl_add_u64 v[150:151], v[150:151], 0, v[144:145]
	v_lshlrev_b64 v[162:163], 1, v[150:151]
	v_lshl_add_u64 v[166:167], s[52:53], 0, v[162:163]
	v_lshl_add_u64 v[170:171], s[58:59], 0, v[162:163]
	global_load_dwordx4 v[158:161], v[166:167], off
	global_load_dwordx4 v[162:165], v[170:171], off
	s_nop 0
	global_load_dwordx4 v[166:169], v[166:167], off offset:256
	s_nop 0
	global_load_dwordx4 v[170:173], v[170:171], off offset:256
	s_waitcnt vmcnt(4)
	v_fmamk_f32 v153, v153, 0x3a000000, v195
	v_mul_f32_e32 v174, 0x4b800000, v153
	v_cmp_gt_f32_e32 vcc, s61, v153
	s_waitcnt vmcnt(2)
	v_lshlrev_b32_e32 v176, 16, v162
	v_cndmask_b32_e32 v153, v153, v174, vcc
	v_rsq_f32_e32 v153, v153
	s_waitcnt vmcnt(1)
	v_lshlrev_b32_e32 v182, 16, v166
	v_and_b32_e32 v183, 0xffff0000, v166
	v_lshlrev_b32_e32 v174, 16, v158
	v_mul_f32_e32 v166, 0x45800000, v153
	v_cndmask_b32_e32 v153, v153, v166, vcc
	v_mul_f32_e32 v108, v108, v153
	v_mul_f32_e32 v104, v104, v153
	v_mul_f32_e32 v109, v109, v153
	v_mul_f32_e32 v105, v105, v153
	v_mul_f32_e32 v110, v110, v153
	v_mul_f32_e32 v106, v106, v153
	v_mul_f32_e32 v111, v111, v153
	v_mul_f32_e32 v107, v107, v153
	v_mul_f32_e32 v100, v100, v153
	v_mul_f32_e32 v101, v101, v153
	v_mul_f32_e32 v108, 0xbfb8aa3b, v108
	v_mul_f32_e32 v104, 0xbfb8aa3b, v104
	v_mul_f32_e32 v109, 0xbfb8aa3b, v109
	v_mul_f32_e32 v105, 0xbfb8aa3b, v105
	v_mul_f32_e32 v110, 0xbfb8aa3b, v110
	v_mul_f32_e32 v106, 0xbfb8aa3b, v106
	v_mul_f32_e32 v111, 0xbfb8aa3b, v111
	v_mul_f32_e32 v107, 0xbfb8aa3b, v107
	v_mul_f32_e32 v100, 0xbfb8aa3b, v100
	v_mul_f32_e32 v101, 0xbfb8aa3b, v101
	v_exp_f32_e32 v108, v108
	v_exp_f32_e32 v104, v104
	v_exp_f32_e32 v109, v109
	v_exp_f32_e32 v105, v105
	v_exp_f32_e32 v110, v110
	v_exp_f32_e32 v106, v106
	v_exp_f32_e32 v111, v111
	v_exp_f32_e32 v107, v107
	v_exp_f32_e32 v100, v100
	v_exp_f32_e32 v101, v101
	v_mul_f32_e32 v97, v97, v153
	v_mul_f32_e32 v98, v98, v153
	v_mul_f32_e32 v96, v96, v153
	v_mul_f32_e32 v97, 0xbfb8aa3b, v97
	v_mul_f32_e32 v98, 0xbfb8aa3b, v98
	v_mul_f32_e32 v103, v103, v153
	v_mul_f32_e32 v96, 0xbfb8aa3b, v96
	v_exp_f32_e32 v166, v97
	v_add_f32_e32 v97, 1.0, v108
	v_add_f32_e32 v104, 1.0, v104
	v_add_f32_e32 v108, 1.0, v109
	v_add_f32_e32 v105, 1.0, v105
	v_add_f32_e32 v109, 1.0, v110
	v_add_f32_e32 v106, 1.0, v106
	v_add_f32_e32 v111, 1.0, v111
	v_add_f32_e32 v107, 1.0, v107
	v_exp_f32_e32 v98, v98
	v_mul_f32_e32 v103, 0xbfb8aa3b, v103
	v_exp_f32_e32 v96, v96
	v_add_f32_e32 v185, 1.0, v100
	v_add_f32_e32 v199, 1.0, v101
	v_rcp_f32_e32 v100, v104
	v_rcp_f32_e32 v101, v105
	v_rcp_f32_e32 v104, v109
	v_rcp_f32_e32 v110, v106
	v_rcp_f32_e32 v105, v111
	v_rcp_f32_e32 v111, v107
	v_mul_f32_e32 v102, v102, v153
	v_exp_f32_e32 v103, v103
	v_mul_f32_e32 v102, 0xbfb8aa3b, v102
	v_exp_f32_e32 v102, v102
	v_and_b32_e32 v175, 0xffff0000, v158
	v_and_b32_e32 v177, 0xffff0000, v162
	v_lshlrev_b32_e32 v178, 16, v160
	v_and_b32_e32 v179, 0xffff0000, v160
	v_lshlrev_b32_e32 v180, 16, v164
	v_and_b32_e32 v181, 0xffff0000, v164
	v_lshlrev_b32_e32 v158, 16, v159
	v_and_b32_e32 v159, 0xffff0000, v159
	v_lshlrev_b32_e32 v162, 16, v163
	v_and_b32_e32 v163, 0xffff0000, v163
	v_lshlrev_b32_e32 v160, 16, v161
	v_and_b32_e32 v161, 0xffff0000, v161
	v_lshlrev_b32_e32 v164, 16, v165
	v_and_b32_e32 v165, 0xffff0000, v165
	v_add_f32_e32 v98, 1.0, v98
	v_add_f32_e32 v187, 1.0, v96
	v_rcp_f32_e32 v96, v97
	v_rcp_f32_e32 v97, v108
	v_pk_fma_f32 v[108:109], v[104:105], v[162:163], v[158:159]
	v_pk_fma_f32 v[104:105], v[110:111], v[164:165], v[160:161]
	v_add_f32_e32 v110, 1.0, v166
	v_rcp_f32_e32 v166, v98
	v_add_f32_e32 v98, 1.0, v103
	v_rcp_f32_e32 v103, v98
	v_mul_f32_e32 v98, v99, v153
	v_rcp_f32_e32 v198, v187
	v_rcp_f32_e32 v187, v199
	v_rcp_f32_e32 v199, v110
	v_add_f32_e32 v102, 1.0, v102
	v_mul_f32_e32 v98, 0xbfb8aa3b, v98
	v_rcp_f32_e32 v102, v102
	v_exp_f32_e32 v153, v98
	v_pk_fma_f32 v[106:107], v[96:97], v[176:177], v[174:175]
	v_lshlrev_b32_e32 v110, 16, v168
	v_and_b32_e32 v111, 0xffff0000, v168
	s_waitcnt vmcnt(0)
	v_lshlrev_b32_e32 v174, 16, v172
	v_and_b32_e32 v175, 0xffff0000, v172
	v_pk_fma_f32 v[110:111], v[198:199], v[174:175], v[110:111]
	v_lshlrev_b32_e32 v174, 16, v167
	v_and_b32_e32 v175, 0xffff0000, v167
	v_lshlrev_b32_e32 v98, 16, v171
	v_and_b32_e32 v99, 0xffff0000, v171
	v_rcp_f32_e32 v186, v185
	v_pk_fma_f32 v[98:99], v[102:103], v[98:99], v[174:175]
	v_add_f32_e32 v102, 1.0, v153
	v_rcp_f32_e32 v167, v102
	v_lshlrev_b32_e32 v184, 16, v170
	v_and_b32_e32 v185, 0xffff0000, v170
	v_pk_fma_f32 v[96:97], v[186:187], v[184:185], v[182:183]
	v_lshlrev_b32_e32 v102, 16, v169
	v_and_b32_e32 v103, 0xffff0000, v169
	v_lshlrev_b32_e32 v168, 16, v173
	v_and_b32_e32 v169, 0xffff0000, v173
	v_pk_fma_f32 v[100:101], v[100:101], v[180:181], v[178:179]
	v_pk_mul_f32 v[158:159], v[106:107], v[106:107]
	v_pk_mul_f32 v[160:161], v[108:109], v[108:109]
	v_pk_fma_f32 v[102:103], v[166:167], v[168:169], v[102:103]
	v_pk_mul_f32 v[166:167], v[96:97], v[96:97]
	v_pk_mul_f32 v[168:169], v[98:99], v[98:99]
	v_pk_mul_f32 v[162:163], v[100:101], v[100:101]
	v_pk_mul_f32 v[170:171], v[110:111], v[110:111]
	v_add_f32_e32 v153, v168, v169
	v_add_f32_e32 v166, v166, v167
	v_add_f32_e32 v160, v160, v161
	v_add_f32_e32 v158, v158, v159
	v_pk_mul_f32 v[164:165], v[104:105], v[104:105]
	v_pk_mul_f32 v[172:173], v[102:103], v[102:103]
	v_add_f32_e32 v153, v166, v153
	v_add_f32_e32 v166, v170, v171
	v_add_f32_e32 v158, v158, v160
	v_add_f32_e32 v159, v162, v163
	v_add_f32_e32 v153, v166, v153
	v_add_f32_e32 v166, v172, v173
	v_add_f32_e32 v158, v159, v158
	v_add_f32_e32 v159, v164, v165
	v_add_f32_e32 v153, v166, v153
	v_add_f32_e32 v158, v159, v158
	v_add_f32_e32 v153, v158, v153
	v_mov_b32_e32 v158, v153
	s_nop 1
	v_permlane16_swap_b32 v158, v153
	s_waitcnt lgkmcnt(0)
	v_add_f32_e32 v153, v153, v158
	v_mov_b32_e32 v160, v153
	s_nop 1
	v_permlane32_swap_b32 v160, v153
	v_lshl_add_u64 v[158:159], v[156:157], 2, s[16:17]
	s_and_saveexec_b64 s[30:31], s[0:1]
	s_cbranch_execz .LBB0_1363
	s_waitcnt lgkmcnt(0)
	v_add_f32_e32 v153, v153, v160
	global_atomic_add_f32 v[158:159], v153, off
.LBB0_1363:
	s_or_b64 exec, exec, s[30:31]
	s_waitcnt lgkmcnt(0)
	v_or_b32_e32 v160, 32, v152
	v_ashrrev_i32_e32 v161, 31, v160
	v_lshl_add_u64 v[156:157], v[160:161], 2, s[12:13]
	global_load_dword v153, v[156:157], off
	v_lshlrev_b64 v[156:157], 11, v[160:161]
	v_lshl_add_u64 v[156:157], v[156:157], 0, v[144:145]
	v_lshlrev_b64 v[166:167], 1, v[156:157]
	v_lshl_add_u64 v[170:171], s[52:53], 0, v[166:167]
	v_lshl_add_u64 v[174:175], s[58:59], 0, v[166:167]
	global_load_dwordx4 v[162:165], v[170:171], off
	global_load_dwordx4 v[166:169], v[174:175], off
	s_nop 0
	global_load_dwordx4 v[170:173], v[170:171], off offset:256
	s_nop 0
	global_load_dwordx4 v[174:177], v[174:175], off offset:256
	s_waitcnt vmcnt(4)
	v_fmamk_f32 v153, v153, 0x3a000000, v195
	v_mul_f32_e32 v178, 0x4b800000, v153
	v_cmp_gt_f32_e32 vcc, s61, v153
	s_waitcnt vmcnt(2)
	v_lshlrev_b32_e32 v180, 16, v166
	v_cndmask_b32_e32 v153, v153, v178, vcc
	v_rsq_f32_e32 v153, v153
	s_waitcnt vmcnt(1)
	v_lshlrev_b32_e32 v186, 16, v170
	v_and_b32_e32 v187, 0xffff0000, v170
	v_lshlrev_b32_e32 v178, 16, v162
	v_mul_f32_e32 v170, 0x45800000, v153
	v_cndmask_b32_e32 v153, v153, v170, vcc
	v_mul_f32_e32 v92, v92, v153
	v_mul_f32_e32 v88, v88, v153
	v_mul_f32_e32 v93, v93, v153
	v_mul_f32_e32 v89, v89, v153
	v_mul_f32_e32 v94, v94, v153
	v_mul_f32_e32 v90, v90, v153
	v_mul_f32_e32 v95, v95, v153
	v_mul_f32_e32 v91, v91, v153
	v_mul_f32_e32 v84, v84, v153
	v_mul_f32_e32 v85, v85, v153
	v_mul_f32_e32 v92, 0xbfb8aa3b, v92
	v_mul_f32_e32 v88, 0xbfb8aa3b, v88
	v_mul_f32_e32 v93, 0xbfb8aa3b, v93
	v_mul_f32_e32 v89, 0xbfb8aa3b, v89
	v_mul_f32_e32 v94, 0xbfb8aa3b, v94
	v_mul_f32_e32 v90, 0xbfb8aa3b, v90
	v_mul_f32_e32 v95, 0xbfb8aa3b, v95
	v_mul_f32_e32 v91, 0xbfb8aa3b, v91
	v_mul_f32_e32 v84, 0xbfb8aa3b, v84
	v_mul_f32_e32 v85, 0xbfb8aa3b, v85
	v_exp_f32_e32 v92, v92
	v_exp_f32_e32 v88, v88
	v_exp_f32_e32 v93, v93
	v_exp_f32_e32 v89, v89
	v_exp_f32_e32 v94, v94
	v_exp_f32_e32 v90, v90
	v_exp_f32_e32 v95, v95
	v_exp_f32_e32 v91, v91
	v_exp_f32_e32 v84, v84
	v_exp_f32_e32 v85, v85
	v_mul_f32_e32 v81, v81, v153
	v_mul_f32_e32 v82, v82, v153
	v_mul_f32_e32 v80, v80, v153
	v_mul_f32_e32 v81, 0xbfb8aa3b, v81
	v_mul_f32_e32 v82, 0xbfb8aa3b, v82
	v_mul_f32_e32 v87, v87, v153
	v_mul_f32_e32 v80, 0xbfb8aa3b, v80
	v_exp_f32_e32 v170, v81
	v_add_f32_e32 v81, 1.0, v92
	v_add_f32_e32 v88, 1.0, v88
	v_add_f32_e32 v92, 1.0, v93
	v_add_f32_e32 v89, 1.0, v89
	v_add_f32_e32 v93, 1.0, v94
	v_add_f32_e32 v90, 1.0, v90
	v_add_f32_e32 v95, 1.0, v95
	v_add_f32_e32 v91, 1.0, v91
	v_exp_f32_e32 v82, v82
	v_mul_f32_e32 v87, 0xbfb8aa3b, v87
	v_exp_f32_e32 v80, v80
	v_add_f32_e32 v199, 1.0, v84
	v_add_f32_e32 v203, 1.0, v85
	v_rcp_f32_e32 v84, v88
	v_rcp_f32_e32 v85, v89
	v_rcp_f32_e32 v88, v93
	v_rcp_f32_e32 v94, v90
	v_rcp_f32_e32 v89, v95
	v_rcp_f32_e32 v95, v91
	v_mul_f32_e32 v86, v86, v153
	v_exp_f32_e32 v87, v87
	v_mul_f32_e32 v86, 0xbfb8aa3b, v86
	v_exp_f32_e32 v86, v86
	v_and_b32_e32 v179, 0xffff0000, v162
	v_and_b32_e32 v181, 0xffff0000, v166
	v_lshlrev_b32_e32 v182, 16, v164
	v_and_b32_e32 v183, 0xffff0000, v164
	v_lshlrev_b32_e32 v184, 16, v168
	v_and_b32_e32 v185, 0xffff0000, v168
	v_lshlrev_b32_e32 v162, 16, v163
	v_and_b32_e32 v163, 0xffff0000, v163
	v_lshlrev_b32_e32 v166, 16, v167
	v_and_b32_e32 v167, 0xffff0000, v167
	v_lshlrev_b32_e32 v164, 16, v165
	v_and_b32_e32 v165, 0xffff0000, v165
	v_lshlrev_b32_e32 v168, 16, v169
	v_and_b32_e32 v169, 0xffff0000, v169
	v_add_f32_e32 v82, 1.0, v82
	v_add_f32_e32 v201, 1.0, v80
	v_rcp_f32_e32 v80, v81
	v_rcp_f32_e32 v81, v92
	v_pk_fma_f32 v[92:93], v[88:89], v[166:167], v[162:163]
	v_pk_fma_f32 v[88:89], v[94:95], v[168:169], v[164:165]
	v_add_f32_e32 v94, 1.0, v170
	v_rcp_f32_e32 v170, v82
	v_add_f32_e32 v82, 1.0, v87
	v_rcp_f32_e32 v87, v82
	v_mul_f32_e32 v82, v83, v153
	v_rcp_f32_e32 v202, v201
	v_rcp_f32_e32 v201, v203
	v_rcp_f32_e32 v203, v94
	v_add_f32_e32 v86, 1.0, v86
	v_mul_f32_e32 v82, 0xbfb8aa3b, v82
	v_rcp_f32_e32 v86, v86
	v_exp_f32_e32 v153, v82
	v_pk_fma_f32 v[90:91], v[80:81], v[180:181], v[178:179]
	v_lshlrev_b32_e32 v94, 16, v172
	v_and_b32_e32 v95, 0xffff0000, v172
	s_waitcnt vmcnt(0)
	v_lshlrev_b32_e32 v178, 16, v176
	v_and_b32_e32 v179, 0xffff0000, v176
	v_pk_fma_f32 v[94:95], v[202:203], v[178:179], v[94:95]
	v_lshlrev_b32_e32 v178, 16, v171
	v_and_b32_e32 v179, 0xffff0000, v171
	v_lshlrev_b32_e32 v82, 16, v175
	v_and_b32_e32 v83, 0xffff0000, v175
	v_rcp_f32_e32 v200, v199
	v_pk_fma_f32 v[82:83], v[86:87], v[82:83], v[178:179]
	v_add_f32_e32 v86, 1.0, v153
	v_rcp_f32_e32 v171, v86
	v_lshlrev_b32_e32 v198, 16, v174
	v_and_b32_e32 v199, 0xffff0000, v174
	v_pk_fma_f32 v[80:81], v[200:201], v[198:199], v[186:187]
	v_lshlrev_b32_e32 v86, 16, v173
	v_and_b32_e32 v87, 0xffff0000, v173
	v_lshlrev_b32_e32 v172, 16, v177
	v_and_b32_e32 v173, 0xffff0000, v177
	v_pk_fma_f32 v[84:85], v[84:85], v[184:185], v[182:183]
	v_pk_mul_f32 v[162:163], v[90:91], v[90:91]
	v_pk_mul_f32 v[164:165], v[92:93], v[92:93]
	v_pk_fma_f32 v[86:87], v[170:171], v[172:173], v[86:87]
	v_pk_mul_f32 v[170:171], v[80:81], v[80:81]
	v_pk_mul_f32 v[172:173], v[82:83], v[82:83]
	v_pk_mul_f32 v[166:167], v[84:85], v[84:85]
	v_pk_mul_f32 v[174:175], v[94:95], v[94:95]
	v_add_f32_e32 v153, v172, v173
	v_add_f32_e32 v170, v170, v171
	v_add_f32_e32 v164, v164, v165
	v_add_f32_e32 v162, v162, v163
	v_pk_mul_f32 v[168:169], v[88:89], v[88:89]
	v_pk_mul_f32 v[176:177], v[86:87], v[86:87]
	v_add_f32_e32 v153, v170, v153
	v_add_f32_e32 v170, v174, v175
	v_add_f32_e32 v162, v162, v164
	v_add_f32_e32 v163, v166, v167
	v_add_f32_e32 v153, v170, v153
	v_add_f32_e32 v170, v176, v177
	v_add_f32_e32 v162, v163, v162
	v_add_f32_e32 v163, v168, v169
	v_add_f32_e32 v153, v170, v153
	v_add_f32_e32 v162, v163, v162
	v_add_f32_e32 v153, v162, v153
	v_mov_b32_e32 v162, v153
	s_nop 1
	v_permlane16_swap_b32 v162, v153
	s_waitcnt lgkmcnt(0)
	v_add_f32_e32 v153, v153, v162
	v_mov_b32_e32 v164, v153
	s_nop 1
	v_permlane32_swap_b32 v164, v153
	v_lshl_add_u64 v[162:163], v[160:161], 2, s[16:17]
	s_and_saveexec_b64 s[30:31], s[0:1]
	s_cbranch_execz .LBB0_1365
	s_waitcnt lgkmcnt(0)
	v_add_f32_e32 v153, v153, v164
	global_atomic_add_f32 v[162:163], v153, off
.LBB0_1365:
	s_or_b64 exec, exec, s[30:31]
	s_waitcnt lgkmcnt(0)
	v_or_b32_e32 v164, 48, v152
	v_ashrrev_i32_e32 v165, 31, v164
	v_lshl_add_u64 v[160:161], v[164:165], 2, s[12:13]
	global_load_dword v153, v[160:161], off
	v_lshlrev_b64 v[160:161], 11, v[164:165]
	v_lshl_add_u64 v[160:161], v[160:161], 0, v[144:145]
	v_lshlrev_b64 v[170:171], 1, v[160:161]
	v_lshl_add_u64 v[174:175], s[52:53], 0, v[170:171]
	v_lshl_add_u64 v[178:179], s[58:59], 0, v[170:171]
	global_load_dwordx4 v[166:169], v[174:175], off
	global_load_dwordx4 v[170:173], v[178:179], off
	s_nop 0
	global_load_dwordx4 v[174:177], v[174:175], off offset:256
	s_nop 0
	global_load_dwordx4 v[178:181], v[178:179], off offset:256
	s_waitcnt vmcnt(4)
	v_fmamk_f32 v153, v153, 0x3a000000, v195
	v_mul_f32_e32 v182, 0x4b800000, v153
	v_cmp_gt_f32_e32 vcc, s61, v153
	s_waitcnt vmcnt(2)
	v_lshlrev_b32_e32 v184, 16, v170
	v_cndmask_b32_e32 v153, v153, v182, vcc
	v_rsq_f32_e32 v153, v153
	s_waitcnt vmcnt(1)
	v_lshlrev_b32_e32 v200, 16, v174
	v_and_b32_e32 v201, 0xffff0000, v174
	v_lshlrev_b32_e32 v182, 16, v166
	v_mul_f32_e32 v174, 0x45800000, v153
	v_cndmask_b32_e32 v153, v153, v174, vcc
	v_mul_f32_e32 v76, v76, v153
	v_mul_f32_e32 v72, v72, v153
	v_mul_f32_e32 v77, v77, v153
	v_mul_f32_e32 v73, v73, v153
	v_mul_f32_e32 v78, v78, v153
	v_mul_f32_e32 v74, v74, v153
	v_mul_f32_e32 v79, v79, v153
	v_mul_f32_e32 v75, v75, v153
	v_mul_f32_e32 v68, v68, v153
	v_mul_f32_e32 v69, v69, v153
	v_mul_f32_e32 v76, 0xbfb8aa3b, v76
	v_mul_f32_e32 v72, 0xbfb8aa3b, v72
	v_mul_f32_e32 v77, 0xbfb8aa3b, v77
	v_mul_f32_e32 v73, 0xbfb8aa3b, v73
	v_mul_f32_e32 v78, 0xbfb8aa3b, v78
	v_mul_f32_e32 v74, 0xbfb8aa3b, v74
	v_mul_f32_e32 v79, 0xbfb8aa3b, v79
	v_mul_f32_e32 v75, 0xbfb8aa3b, v75
	v_mul_f32_e32 v68, 0xbfb8aa3b, v68
	v_mul_f32_e32 v69, 0xbfb8aa3b, v69
	v_exp_f32_e32 v76, v76
	v_exp_f32_e32 v72, v72
	v_exp_f32_e32 v77, v77
	v_exp_f32_e32 v73, v73
	v_exp_f32_e32 v78, v78
	v_exp_f32_e32 v74, v74
	v_exp_f32_e32 v79, v79
	v_exp_f32_e32 v75, v75
	v_exp_f32_e32 v68, v68
	v_exp_f32_e32 v69, v69
	v_mul_f32_e32 v65, v65, v153
	v_mul_f32_e32 v66, v66, v153
	v_mul_f32_e32 v64, v64, v153
	v_mul_f32_e32 v65, 0xbfb8aa3b, v65
	v_mul_f32_e32 v66, 0xbfb8aa3b, v66
	v_mul_f32_e32 v71, v71, v153
	v_mul_f32_e32 v64, 0xbfb8aa3b, v64
	v_exp_f32_e32 v174, v65
	v_add_f32_e32 v65, 1.0, v76
	v_add_f32_e32 v72, 1.0, v72
	v_add_f32_e32 v76, 1.0, v77
	v_add_f32_e32 v73, 1.0, v73
	v_add_f32_e32 v77, 1.0, v78
	v_add_f32_e32 v74, 1.0, v74
	v_add_f32_e32 v79, 1.0, v79
	v_add_f32_e32 v75, 1.0, v75
	v_exp_f32_e32 v66, v66
	v_mul_f32_e32 v71, 0xbfb8aa3b, v71
	v_exp_f32_e32 v64, v64
	v_add_f32_e32 v203, 1.0, v68
	v_add_f32_e32 v207, 1.0, v69
	v_rcp_f32_e32 v68, v72
	v_rcp_f32_e32 v69, v73
	v_rcp_f32_e32 v72, v77
	v_rcp_f32_e32 v78, v74
	v_rcp_f32_e32 v73, v79
	v_rcp_f32_e32 v79, v75
	v_mul_f32_e32 v70, v70, v153
	v_exp_f32_e32 v71, v71
	v_mul_f32_e32 v70, 0xbfb8aa3b, v70
	v_exp_f32_e32 v70, v70
	v_and_b32_e32 v183, 0xffff0000, v166
	v_and_b32_e32 v185, 0xffff0000, v170
	v_lshlrev_b32_e32 v186, 16, v168
	v_and_b32_e32 v187, 0xffff0000, v168
	v_lshlrev_b32_e32 v198, 16, v172
	v_and_b32_e32 v199, 0xffff0000, v172
	v_lshlrev_b32_e32 v166, 16, v167
	v_and_b32_e32 v167, 0xffff0000, v167
	v_lshlrev_b32_e32 v170, 16, v171
	v_and_b32_e32 v171, 0xffff0000, v171
	v_lshlrev_b32_e32 v168, 16, v169
	v_and_b32_e32 v169, 0xffff0000, v169
	v_lshlrev_b32_e32 v172, 16, v173
	v_and_b32_e32 v173, 0xffff0000, v173
	v_add_f32_e32 v66, 1.0, v66
	v_add_f32_e32 v205, 1.0, v64
	v_rcp_f32_e32 v64, v65
	v_rcp_f32_e32 v65, v76
	v_pk_fma_f32 v[76:77], v[72:73], v[170:171], v[166:167]
	v_pk_fma_f32 v[72:73], v[78:79], v[172:173], v[168:169]
	v_add_f32_e32 v78, 1.0, v174
	v_rcp_f32_e32 v174, v66
	v_add_f32_e32 v66, 1.0, v71
	v_rcp_f32_e32 v71, v66
	v_mul_f32_e32 v66, v67, v153
	v_rcp_f32_e32 v206, v205
	v_rcp_f32_e32 v205, v207
	v_rcp_f32_e32 v207, v78
	v_add_f32_e32 v70, 1.0, v70
	v_mul_f32_e32 v66, 0xbfb8aa3b, v66
	v_rcp_f32_e32 v70, v70
	v_exp_f32_e32 v153, v66
	v_pk_fma_f32 v[74:75], v[64:65], v[184:185], v[182:183]
	v_lshlrev_b32_e32 v78, 16, v176
	v_and_b32_e32 v79, 0xffff0000, v176
	s_waitcnt vmcnt(0)
	v_lshlrev_b32_e32 v182, 16, v180
	v_and_b32_e32 v183, 0xffff0000, v180
	v_pk_fma_f32 v[78:79], v[206:207], v[182:183], v[78:79]
	v_lshlrev_b32_e32 v182, 16, v175
	v_and_b32_e32 v183, 0xffff0000, v175
	v_lshlrev_b32_e32 v66, 16, v179
	v_and_b32_e32 v67, 0xffff0000, v179
	v_rcp_f32_e32 v204, v203
	v_pk_fma_f32 v[66:67], v[70:71], v[66:67], v[182:183]
	v_add_f32_e32 v70, 1.0, v153
	v_rcp_f32_e32 v175, v70
	v_lshlrev_b32_e32 v202, 16, v178
	v_and_b32_e32 v203, 0xffff0000, v178
	v_pk_fma_f32 v[64:65], v[204:205], v[202:203], v[200:201]
	v_lshlrev_b32_e32 v70, 16, v177
	v_and_b32_e32 v71, 0xffff0000, v177
	v_lshlrev_b32_e32 v176, 16, v181
	v_and_b32_e32 v177, 0xffff0000, v181
	v_pk_fma_f32 v[68:69], v[68:69], v[198:199], v[186:187]
	v_pk_mul_f32 v[166:167], v[74:75], v[74:75]
	v_pk_mul_f32 v[168:169], v[76:77], v[76:77]
	v_pk_fma_f32 v[70:71], v[174:175], v[176:177], v[70:71]
	v_pk_mul_f32 v[174:175], v[64:65], v[64:65]
	v_pk_mul_f32 v[176:177], v[66:67], v[66:67]
	v_pk_mul_f32 v[170:171], v[68:69], v[68:69]
	v_pk_mul_f32 v[178:179], v[78:79], v[78:79]
	v_add_f32_e32 v153, v176, v177
	v_add_f32_e32 v174, v174, v175
	v_add_f32_e32 v168, v168, v169
	v_add_f32_e32 v166, v166, v167
	v_pk_mul_f32 v[172:173], v[72:73], v[72:73]
	v_pk_mul_f32 v[180:181], v[70:71], v[70:71]
	v_add_f32_e32 v153, v174, v153
	v_add_f32_e32 v174, v178, v179
	v_add_f32_e32 v166, v166, v168
	v_add_f32_e32 v167, v170, v171
	v_add_f32_e32 v153, v174, v153
	v_add_f32_e32 v174, v180, v181
	v_add_f32_e32 v166, v167, v166
	v_add_f32_e32 v167, v172, v173
	v_add_f32_e32 v153, v174, v153
	v_add_f32_e32 v166, v167, v166
	v_add_f32_e32 v153, v166, v153
	v_mov_b32_e32 v166, v153
	s_nop 1
	v_permlane16_swap_b32 v166, v153
	s_waitcnt lgkmcnt(0)
	v_add_f32_e32 v153, v153, v166
	v_mov_b32_e32 v168, v153
	s_nop 1
	v_permlane32_swap_b32 v168, v153
	v_lshl_add_u64 v[166:167], v[164:165], 2, s[16:17]
	s_and_saveexec_b64 s[30:31], s[0:1]
	s_cbranch_execz .LBB0_1367
	s_waitcnt lgkmcnt(0)
	v_add_f32_e32 v153, v153, v168
	global_atomic_add_f32 v[166:167], v153, off
.LBB0_1367:
	s_or_b64 exec, exec, s[30:31]
	global_load_dword v153, v[154:155], off offset:512
	s_waitcnt lgkmcnt(0)
	v_add_u32_e32 v168, 0x80, v152
	v_ashrrev_i32_e32 v169, 31, v168
	v_lshlrev_b64 v[164:165], 11, v[168:169]
	v_lshl_add_u64 v[164:165], v[164:165], 0, v[144:145]
	v_lshlrev_b64 v[174:175], 1, v[164:165]
	v_lshl_add_u64 v[178:179], s[52:53], 0, v[174:175]
	v_lshl_add_u64 v[182:183], s[58:59], 0, v[174:175]
	global_load_dwordx4 v[170:173], v[178:179], off
	global_load_dwordx4 v[174:177], v[182:183], off
	s_nop 0
	global_load_dwordx4 v[178:181], v[178:179], off offset:256
	s_nop 0
	global_load_dwordx4 v[182:185], v[182:183], off offset:256
	s_waitcnt vmcnt(4)
	v_fmamk_f32 v153, v153, 0x3a000000, v195
	v_mul_f32_e32 v186, 0x4b800000, v153
	v_cmp_gt_f32_e32 vcc, s61, v153
	s_waitcnt vmcnt(2)
	v_lshlrev_b32_e32 v198, 16, v174
	v_cndmask_b32_e32 v153, v153, v186, vcc
	v_rsq_f32_e32 v153, v153
	s_waitcnt vmcnt(1)
	v_lshlrev_b32_e32 v204, 16, v178
	v_and_b32_e32 v205, 0xffff0000, v178
	v_lshlrev_b32_e32 v186, 16, v170
	v_mul_f32_e32 v178, 0x45800000, v153
	v_cndmask_b32_e32 v153, v153, v178, vcc
	v_mul_f32_e32 v60, v60, v153
	v_mul_f32_e32 v56, v56, v153
	v_mul_f32_e32 v61, v61, v153
	v_mul_f32_e32 v57, v57, v153
	v_mul_f32_e32 v62, v62, v153
	v_mul_f32_e32 v58, v58, v153
	v_mul_f32_e32 v63, v63, v153
	v_mul_f32_e32 v59, v59, v153
	v_mul_f32_e32 v52, v52, v153
	v_mul_f32_e32 v48, v48, v153
	v_mul_f32_e32 v53, v53, v153
	v_mul_f32_e32 v49, v49, v153
	v_mul_f32_e32 v60, 0xbfb8aa3b, v60
	v_mul_f32_e32 v56, 0xbfb8aa3b, v56
	v_mul_f32_e32 v61, 0xbfb8aa3b, v61
	v_mul_f32_e32 v57, 0xbfb8aa3b, v57
	v_mul_f32_e32 v62, 0xbfb8aa3b, v62
	v_mul_f32_e32 v58, 0xbfb8aa3b, v58
	v_mul_f32_e32 v63, 0xbfb8aa3b, v63
	v_mul_f32_e32 v59, 0xbfb8aa3b, v59
	v_mul_f32_e32 v52, 0xbfb8aa3b, v52
	v_mul_f32_e32 v48, 0xbfb8aa3b, v48
	v_mul_f32_e32 v53, 0xbfb8aa3b, v53
	v_mul_f32_e32 v178, 0xbfb8aa3b, v49
	v_exp_f32_e32 v49, v60
	v_exp_f32_e32 v56, v56
	v_exp_f32_e32 v60, v61
	v_exp_f32_e32 v57, v57
	v_exp_f32_e32 v61, v62
	v_exp_f32_e32 v58, v58
	v_exp_f32_e32 v62, v63
	v_exp_f32_e32 v59, v59
	v_exp_f32_e32 v52, v52
	v_exp_f32_e32 v48, v48
	v_exp_f32_e32 v53, v53
	v_add_f32_e32 v49, 1.0, v49
	v_add_f32_e32 v56, 1.0, v56
	v_add_f32_e32 v60, 1.0, v60
	v_add_f32_e32 v57, 1.0, v57
	v_add_f32_e32 v58, 1.0, v58
	v_add_f32_e32 v63, 1.0, v62
	v_add_f32_e32 v59, 1.0, v59
	v_add_f32_e32 v206, 1.0, v52
	v_add_f32_e32 v207, 1.0, v48
	v_add_f32_e32 v209, 1.0, v53
	v_rcp_f32_e32 v48, v49
	v_rcp_f32_e32 v52, v56
	v_rcp_f32_e32 v49, v60
	v_rcp_f32_e32 v53, v57
	v_rcp_f32_e32 v62, v58
	v_rcp_f32_e32 v57, v63
	v_rcp_f32_e32 v63, v59
	v_mul_f32_e32 v50, v50, v153
	v_mul_f32_e32 v50, 0xbfb8aa3b, v50
	v_mul_f32_e32 v55, v55, v153
	v_exp_f32_e32 v50, v50
	v_mul_f32_e32 v55, 0xbfb8aa3b, v55
	v_and_b32_e32 v187, 0xffff0000, v170
	v_and_b32_e32 v199, 0xffff0000, v174
	v_lshlrev_b32_e32 v200, 16, v172
	v_and_b32_e32 v201, 0xffff0000, v172
	v_lshlrev_b32_e32 v202, 16, v176
	v_and_b32_e32 v203, 0xffff0000, v176
	v_lshlrev_b32_e32 v172, 16, v173
	v_and_b32_e32 v173, 0xffff0000, v173
	v_lshlrev_b32_e32 v176, 16, v177
	v_and_b32_e32 v177, 0xffff0000, v177
	v_mul_f32_e32 v54, v54, v153
	v_exp_f32_e32 v55, v55
	v_pk_fma_f32 v[58:59], v[48:49], v[198:199], v[186:187]
	v_pk_fma_f32 v[48:49], v[52:53], v[202:203], v[200:201]
	v_pk_fma_f32 v[52:53], v[62:63], v[176:177], v[172:173]
	v_exp_f32_e32 v62, v178
	v_mul_f32_e32 v54, 0xbfb8aa3b, v54
	v_exp_f32_e32 v54, v54
	v_add_f32_e32 v50, 1.0, v50
	v_rcp_f32_e32 v178, v50
	v_add_f32_e32 v50, 1.0, v55
	v_add_f32_e32 v62, 1.0, v62
	v_rcp_f32_e32 v55, v50
	v_mul_f32_e32 v50, v51, v153
	v_rcp_f32_e32 v208, v207
	v_rcp_f32_e32 v207, v209
	v_rcp_f32_e32 v209, v62
	v_add_f32_e32 v54, 1.0, v54
	v_mul_f32_e32 v50, 0xbfb8aa3b, v50
	v_rcp_f32_e32 v54, v54
	v_exp_f32_e32 v153, v50
	v_add_f32_e32 v61, 1.0, v61
	v_lshlrev_b32_e32 v62, 16, v180
	v_and_b32_e32 v63, 0xffff0000, v180
	s_waitcnt vmcnt(0)
	v_lshlrev_b32_e32 v186, 16, v184
	v_and_b32_e32 v187, 0xffff0000, v184
	v_rcp_f32_e32 v56, v61
	v_pk_fma_f32 v[62:63], v[208:209], v[186:187], v[62:63]
	v_lshlrev_b32_e32 v186, 16, v179
	v_and_b32_e32 v187, 0xffff0000, v179
	v_lshlrev_b32_e32 v50, 16, v183
	v_and_b32_e32 v51, 0xffff0000, v183
	v_rcp_f32_e32 v206, v206
	v_pk_fma_f32 v[50:51], v[54:55], v[50:51], v[186:187]
	v_add_f32_e32 v54, 1.0, v153
	v_rcp_f32_e32 v179, v54
	v_lshlrev_b32_e32 v170, 16, v171
	v_and_b32_e32 v171, 0xffff0000, v171
	v_lshlrev_b32_e32 v174, 16, v175
	v_and_b32_e32 v175, 0xffff0000, v175
	v_pk_fma_f32 v[60:61], v[56:57], v[174:175], v[170:171]
	v_lshlrev_b32_e32 v56, 16, v182
	v_and_b32_e32 v57, 0xffff0000, v182
	v_pk_fma_f32 v[56:57], v[206:207], v[56:57], v[204:205]
	v_lshlrev_b32_e32 v54, 16, v181
	v_and_b32_e32 v55, 0xffff0000, v181
	v_lshlrev_b32_e32 v180, 16, v185
	v_and_b32_e32 v181, 0xffff0000, v185
	v_pk_mul_f32 v[170:171], v[58:59], v[58:59]
	v_pk_mul_f32 v[172:173], v[60:61], v[60:61]
	v_pk_fma_f32 v[54:55], v[178:179], v[180:181], v[54:55]
	v_pk_mul_f32 v[178:179], v[56:57], v[56:57]
	v_pk_mul_f32 v[180:181], v[50:51], v[50:51]
	v_pk_mul_f32 v[174:175], v[48:49], v[48:49]
	v_pk_mul_f32 v[182:183], v[62:63], v[62:63]
	v_add_f32_e32 v153, v180, v181
	v_add_f32_e32 v178, v178, v179
	v_add_f32_e32 v172, v172, v173
	v_add_f32_e32 v170, v170, v171
	v_pk_mul_f32 v[176:177], v[52:53], v[52:53]
	v_pk_mul_f32 v[184:185], v[54:55], v[54:55]
	v_add_f32_e32 v153, v178, v153
	v_add_f32_e32 v178, v182, v183
	v_add_f32_e32 v170, v170, v172
	v_add_f32_e32 v171, v174, v175
	v_add_f32_e32 v153, v178, v153
	v_add_f32_e32 v178, v184, v185
	v_add_f32_e32 v170, v171, v170
	v_add_f32_e32 v171, v176, v177
	v_add_f32_e32 v153, v178, v153
	v_add_f32_e32 v170, v171, v170
	v_add_f32_e32 v153, v170, v153
	v_mov_b32_e32 v170, v153
	s_nop 1
	v_permlane16_swap_b32 v170, v153
	s_waitcnt lgkmcnt(0)
	v_add_f32_e32 v153, v153, v170
	v_mov_b32_e32 v170, v153
	s_nop 1
	v_permlane32_swap_b32 v170, v153
	s_and_saveexec_b64 s[30:31], s[0:1]
	s_cbranch_execz .LBB0_1369
	v_lshl_add_u64 v[168:169], v[168:169], 2, s[16:17]
	s_waitcnt lgkmcnt(0)
	v_add_f32_e32 v153, v153, v170
	global_atomic_add_f32 v[168:169], v153, off
.LBB0_1369:
	s_or_b64 exec, exec, s[30:31]
	global_load_dword v153, v[154:155], off offset:576
	s_waitcnt lgkmcnt(0)
	v_add_u32_e32 v170, 0x90, v152
	v_ashrrev_i32_e32 v171, 31, v170
	v_lshlrev_b64 v[168:169], 11, v[170:171]
	v_lshl_add_u64 v[168:169], v[168:169], 0, v[144:145]
	v_lshlrev_b64 v[176:177], 1, v[168:169]
	v_lshl_add_u64 v[180:181], s[52:53], 0, v[176:177]
	v_lshl_add_u64 v[184:185], s[58:59], 0, v[176:177]
	global_load_dwordx4 v[172:175], v[180:181], off
	global_load_dwordx4 v[176:179], v[184:185], off
	s_nop 0
	global_load_dwordx4 v[180:183], v[180:181], off offset:256
	s_nop 0
	global_load_dwordx4 v[184:187], v[184:185], off offset:256
	s_waitcnt vmcnt(4)
	v_fmamk_f32 v153, v153, 0x3a000000, v195
	v_mul_f32_e32 v198, 0x4b800000, v153
	v_cmp_gt_f32_e32 vcc, s61, v153
	s_waitcnt vmcnt(2)
	v_lshlrev_b32_e32 v200, 16, v176
	v_cndmask_b32_e32 v153, v153, v198, vcc
	v_rsq_f32_e32 v153, v153
	s_waitcnt vmcnt(1)
	v_lshlrev_b32_e32 v206, 16, v180
	v_and_b32_e32 v207, 0xffff0000, v180
	v_lshlrev_b32_e32 v198, 16, v172
	v_mul_f32_e32 v180, 0x45800000, v153
	v_cndmask_b32_e32 v153, v153, v180, vcc
	v_mul_f32_e32 v44, v44, v153
	v_mul_f32_e32 v40, v40, v153
	v_mul_f32_e32 v45, v45, v153
	v_mul_f32_e32 v41, v41, v153
	v_mul_f32_e32 v46, v46, v153
	v_mul_f32_e32 v42, v42, v153
	v_mul_f32_e32 v47, v47, v153
	v_mul_f32_e32 v43, v43, v153
	v_mul_f32_e32 v36, v36, v153
	v_mul_f32_e32 v32, v32, v153
	v_mul_f32_e32 v37, v37, v153
	v_mul_f32_e32 v33, v33, v153
	v_mul_f32_e32 v44, 0xbfb8aa3b, v44
	v_mul_f32_e32 v40, 0xbfb8aa3b, v40
	v_mul_f32_e32 v45, 0xbfb8aa3b, v45
	v_mul_f32_e32 v41, 0xbfb8aa3b, v41
	v_mul_f32_e32 v46, 0xbfb8aa3b, v46
	v_mul_f32_e32 v42, 0xbfb8aa3b, v42
	v_mul_f32_e32 v47, 0xbfb8aa3b, v47
	v_mul_f32_e32 v43, 0xbfb8aa3b, v43
	v_mul_f32_e32 v36, 0xbfb8aa3b, v36
	v_mul_f32_e32 v32, 0xbfb8aa3b, v32
	v_mul_f32_e32 v37, 0xbfb8aa3b, v37
	v_mul_f32_e32 v180, 0xbfb8aa3b, v33
	v_exp_f32_e32 v33, v44
	v_exp_f32_e32 v40, v40
	v_exp_f32_e32 v44, v45
	v_exp_f32_e32 v41, v41
	v_exp_f32_e32 v45, v46
	v_exp_f32_e32 v42, v42
	v_exp_f32_e32 v46, v47
	v_exp_f32_e32 v43, v43
	v_exp_f32_e32 v36, v36
	v_exp_f32_e32 v32, v32
	v_exp_f32_e32 v37, v37
	v_add_f32_e32 v33, 1.0, v33
	v_add_f32_e32 v40, 1.0, v40
	v_add_f32_e32 v44, 1.0, v44
	v_add_f32_e32 v41, 1.0, v41
	v_add_f32_e32 v42, 1.0, v42
	v_add_f32_e32 v47, 1.0, v46
	v_add_f32_e32 v43, 1.0, v43
	v_add_f32_e32 v208, 1.0, v36
	v_add_f32_e32 v209, 1.0, v32
	v_add_f32_e32 v211, 1.0, v37
	v_rcp_f32_e32 v32, v33
	v_rcp_f32_e32 v36, v40
	v_rcp_f32_e32 v33, v44
	v_rcp_f32_e32 v37, v41
	v_rcp_f32_e32 v46, v42
	v_rcp_f32_e32 v41, v47
	v_rcp_f32_e32 v47, v43
	v_mul_f32_e32 v34, v34, v153
	v_mul_f32_e32 v34, 0xbfb8aa3b, v34
	v_mul_f32_e32 v39, v39, v153
	v_exp_f32_e32 v34, v34
	v_mul_f32_e32 v39, 0xbfb8aa3b, v39
	v_and_b32_e32 v199, 0xffff0000, v172
	v_and_b32_e32 v201, 0xffff0000, v176
	v_lshlrev_b32_e32 v202, 16, v174
	v_and_b32_e32 v203, 0xffff0000, v174
	v_lshlrev_b32_e32 v204, 16, v178
	v_and_b32_e32 v205, 0xffff0000, v178
	v_lshlrev_b32_e32 v174, 16, v175
	v_and_b32_e32 v175, 0xffff0000, v175
	v_lshlrev_b32_e32 v178, 16, v179
	v_and_b32_e32 v179, 0xffff0000, v179
	v_mul_f32_e32 v38, v38, v153
	v_exp_f32_e32 v39, v39
	v_pk_fma_f32 v[42:43], v[32:33], v[200:201], v[198:199]
	v_pk_fma_f32 v[32:33], v[36:37], v[204:205], v[202:203]
	v_pk_fma_f32 v[36:37], v[46:47], v[178:179], v[174:175]
	v_exp_f32_e32 v46, v180
	v_mul_f32_e32 v38, 0xbfb8aa3b, v38
	v_exp_f32_e32 v38, v38
	v_add_f32_e32 v34, 1.0, v34
	v_rcp_f32_e32 v180, v34
	v_add_f32_e32 v34, 1.0, v39
	v_add_f32_e32 v46, 1.0, v46
	v_rcp_f32_e32 v39, v34
	v_mul_f32_e32 v34, v35, v153
	v_rcp_f32_e32 v210, v209
	v_rcp_f32_e32 v209, v211
	v_rcp_f32_e32 v211, v46
	v_add_f32_e32 v38, 1.0, v38
	v_mul_f32_e32 v34, 0xbfb8aa3b, v34
	v_rcp_f32_e32 v38, v38
	v_exp_f32_e32 v153, v34
	v_add_f32_e32 v45, 1.0, v45
	v_lshlrev_b32_e32 v46, 16, v182
	v_and_b32_e32 v47, 0xffff0000, v182
	s_waitcnt vmcnt(0)
	v_lshlrev_b32_e32 v198, 16, v186
	v_and_b32_e32 v199, 0xffff0000, v186
	v_rcp_f32_e32 v40, v45
	v_pk_fma_f32 v[46:47], v[210:211], v[198:199], v[46:47]
	v_lshlrev_b32_e32 v198, 16, v181
	v_and_b32_e32 v199, 0xffff0000, v181
	v_lshlrev_b32_e32 v34, 16, v185
	v_and_b32_e32 v35, 0xffff0000, v185
	v_rcp_f32_e32 v208, v208
	v_pk_fma_f32 v[34:35], v[38:39], v[34:35], v[198:199]
	v_add_f32_e32 v38, 1.0, v153
	v_rcp_f32_e32 v181, v38
	v_lshlrev_b32_e32 v172, 16, v173
	v_and_b32_e32 v173, 0xffff0000, v173
	v_lshlrev_b32_e32 v176, 16, v177
	v_and_b32_e32 v177, 0xffff0000, v177
	v_pk_fma_f32 v[44:45], v[40:41], v[176:177], v[172:173]
	v_lshlrev_b32_e32 v40, 16, v184
	v_and_b32_e32 v41, 0xffff0000, v184
	v_pk_fma_f32 v[40:41], v[208:209], v[40:41], v[206:207]
	v_lshlrev_b32_e32 v38, 16, v183
	v_and_b32_e32 v39, 0xffff0000, v183
	v_lshlrev_b32_e32 v182, 16, v187
	v_and_b32_e32 v183, 0xffff0000, v187
	v_pk_mul_f32 v[172:173], v[42:43], v[42:43]
	v_pk_mul_f32 v[174:175], v[44:45], v[44:45]
	v_pk_fma_f32 v[38:39], v[180:181], v[182:183], v[38:39]
	v_pk_mul_f32 v[180:181], v[40:41], v[40:41]
	v_pk_mul_f32 v[182:183], v[34:35], v[34:35]
	v_pk_mul_f32 v[176:177], v[32:33], v[32:33]
	v_pk_mul_f32 v[184:185], v[46:47], v[46:47]
	v_add_f32_e32 v153, v182, v183
	v_add_f32_e32 v180, v180, v181
	v_add_f32_e32 v174, v174, v175
	v_add_f32_e32 v172, v172, v173
	v_pk_mul_f32 v[178:179], v[36:37], v[36:37]
	v_pk_mul_f32 v[186:187], v[38:39], v[38:39]
	v_add_f32_e32 v153, v180, v153
	v_add_f32_e32 v180, v184, v185
	v_add_f32_e32 v172, v172, v174
	v_add_f32_e32 v173, v176, v177
	v_add_f32_e32 v153, v180, v153
	v_add_f32_e32 v180, v186, v187
	v_add_f32_e32 v172, v173, v172
	v_add_f32_e32 v173, v178, v179
	v_add_f32_e32 v153, v180, v153
	v_add_f32_e32 v172, v173, v172
	v_add_f32_e32 v153, v172, v153
	v_mov_b32_e32 v172, v153
	s_nop 1
	v_permlane16_swap_b32 v172, v153
	s_waitcnt lgkmcnt(0)
	v_add_f32_e32 v153, v153, v172
	v_mov_b32_e32 v172, v153
	s_nop 1
	v_permlane32_swap_b32 v172, v153
	s_and_saveexec_b64 s[30:31], s[0:1]
	s_cbranch_execz .LBB0_1371
	v_lshl_add_u64 v[170:171], v[170:171], 2, s[16:17]
	s_waitcnt lgkmcnt(0)
	v_add_f32_e32 v153, v153, v172
	global_atomic_add_f32 v[170:171], v153, off
.LBB0_1371:
	s_or_b64 exec, exec, s[30:31]
	global_load_dword v153, v[154:155], off offset:640
	s_waitcnt lgkmcnt(0)
	v_add_u32_e32 v172, 0xa0, v152
	v_ashrrev_i32_e32 v173, 31, v172
	v_lshlrev_b64 v[170:171], 11, v[172:173]
	v_lshl_add_u64 v[170:171], v[170:171], 0, v[144:145]
	v_lshlrev_b64 v[178:179], 1, v[170:171]
	v_lshl_add_u64 v[182:183], s[52:53], 0, v[178:179]
	v_lshl_add_u64 v[186:187], s[58:59], 0, v[178:179]
	global_load_dwordx4 v[174:177], v[182:183], off
	global_load_dwordx4 v[178:181], v[186:187], off
	s_nop 0
	global_load_dwordx4 v[182:185], v[182:183], off offset:256
	s_nop 0
	global_load_dwordx4 v[198:201], v[186:187], off offset:256
	s_waitcnt vmcnt(4)
	v_fmamk_f32 v153, v153, 0x3a000000, v195
	v_mul_f32_e32 v186, 0x4b800000, v153
	v_cmp_gt_f32_e32 vcc, s61, v153
	s_waitcnt vmcnt(2)
	v_lshlrev_b32_e32 v202, 16, v178
	v_cndmask_b32_e32 v153, v153, v186, vcc
	v_rsq_f32_e32 v153, v153
	s_waitcnt vmcnt(1)
	v_lshlrev_b32_e32 v208, 16, v182
	v_and_b32_e32 v209, 0xffff0000, v182
	v_lshlrev_b32_e32 v186, 16, v174
	v_mul_f32_e32 v182, 0x45800000, v153
	v_cndmask_b32_e32 v153, v153, v182, vcc
	v_mul_f32_e32 v28, v28, v153
	v_mul_f32_e32 v24, v24, v153
	v_mul_f32_e32 v29, v29, v153
	v_mul_f32_e32 v25, v25, v153
	v_mul_f32_e32 v30, v30, v153
	v_mul_f32_e32 v26, v26, v153
	v_mul_f32_e32 v31, v31, v153
	v_mul_f32_e32 v27, v27, v153
	v_mul_f32_e32 v20, v20, v153
	v_mul_f32_e32 v16, v16, v153
	v_mul_f32_e32 v21, v21, v153
	v_mul_f32_e32 v17, v17, v153
	v_mul_f32_e32 v28, 0xbfb8aa3b, v28
	v_mul_f32_e32 v24, 0xbfb8aa3b, v24
	v_mul_f32_e32 v29, 0xbfb8aa3b, v29
	v_mul_f32_e32 v25, 0xbfb8aa3b, v25
	v_mul_f32_e32 v30, 0xbfb8aa3b, v30
	v_mul_f32_e32 v26, 0xbfb8aa3b, v26
	v_mul_f32_e32 v31, 0xbfb8aa3b, v31
	v_mul_f32_e32 v27, 0xbfb8aa3b, v27
	v_mul_f32_e32 v20, 0xbfb8aa3b, v20
	v_mul_f32_e32 v16, 0xbfb8aa3b, v16
	v_mul_f32_e32 v21, 0xbfb8aa3b, v21
	v_mul_f32_e32 v182, 0xbfb8aa3b, v17
	v_exp_f32_e32 v17, v28
	v_exp_f32_e32 v24, v24
	v_exp_f32_e32 v28, v29
	v_exp_f32_e32 v25, v25
	v_exp_f32_e32 v29, v30
	v_exp_f32_e32 v26, v26
	v_exp_f32_e32 v30, v31
	v_exp_f32_e32 v27, v27
	v_exp_f32_e32 v20, v20
	v_exp_f32_e32 v16, v16
	v_exp_f32_e32 v21, v21
	v_add_f32_e32 v17, 1.0, v17
	v_add_f32_e32 v24, 1.0, v24
	v_add_f32_e32 v28, 1.0, v28
	v_add_f32_e32 v25, 1.0, v25
	v_add_f32_e32 v26, 1.0, v26
	v_add_f32_e32 v31, 1.0, v30
	v_add_f32_e32 v27, 1.0, v27
	v_add_f32_e32 v210, 1.0, v20
	v_add_f32_e32 v211, 1.0, v16
	v_add_f32_e32 v213, 1.0, v21
	v_rcp_f32_e32 v16, v17
	v_rcp_f32_e32 v20, v24
	v_rcp_f32_e32 v17, v28
	v_rcp_f32_e32 v21, v25
	v_rcp_f32_e32 v30, v26
	v_rcp_f32_e32 v25, v31
	v_rcp_f32_e32 v31, v27
	v_mul_f32_e32 v18, v18, v153
	v_mul_f32_e32 v18, 0xbfb8aa3b, v18
	v_mul_f32_e32 v23, v23, v153
	v_exp_f32_e32 v18, v18
	v_mul_f32_e32 v23, 0xbfb8aa3b, v23
	v_and_b32_e32 v187, 0xffff0000, v174
	v_and_b32_e32 v203, 0xffff0000, v178
	v_lshlrev_b32_e32 v204, 16, v176
	v_and_b32_e32 v205, 0xffff0000, v176
	v_lshlrev_b32_e32 v206, 16, v180
	v_and_b32_e32 v207, 0xffff0000, v180
	v_lshlrev_b32_e32 v176, 16, v177
	v_and_b32_e32 v177, 0xffff0000, v177
	v_lshlrev_b32_e32 v180, 16, v181
	v_and_b32_e32 v181, 0xffff0000, v181
	v_mul_f32_e32 v22, v22, v153
	v_exp_f32_e32 v23, v23
	v_pk_fma_f32 v[26:27], v[16:17], v[202:203], v[186:187]
	v_pk_fma_f32 v[16:17], v[20:21], v[206:207], v[204:205]
	v_pk_fma_f32 v[20:21], v[30:31], v[180:181], v[176:177]
	v_exp_f32_e32 v30, v182
	v_mul_f32_e32 v22, 0xbfb8aa3b, v22
	v_exp_f32_e32 v22, v22
	v_add_f32_e32 v18, 1.0, v18
	v_rcp_f32_e32 v182, v18
	v_add_f32_e32 v18, 1.0, v23
	v_add_f32_e32 v30, 1.0, v30
	v_rcp_f32_e32 v23, v18
	v_mul_f32_e32 v18, v19, v153
	v_rcp_f32_e32 v212, v211
	v_rcp_f32_e32 v211, v213
	v_rcp_f32_e32 v213, v30
	v_add_f32_e32 v22, 1.0, v22
	v_mul_f32_e32 v18, 0xbfb8aa3b, v18
	v_rcp_f32_e32 v22, v22
	v_exp_f32_e32 v153, v18
	v_add_f32_e32 v29, 1.0, v29
	v_lshlrev_b32_e32 v30, 16, v184
	v_and_b32_e32 v31, 0xffff0000, v184
	s_waitcnt vmcnt(0)
	v_lshlrev_b32_e32 v186, 16, v200
	v_and_b32_e32 v187, 0xffff0000, v200
	v_rcp_f32_e32 v24, v29
	v_pk_fma_f32 v[30:31], v[212:213], v[186:187], v[30:31]
	v_lshlrev_b32_e32 v186, 16, v183
	v_and_b32_e32 v187, 0xffff0000, v183
	v_lshlrev_b32_e32 v18, 16, v199
	v_and_b32_e32 v19, 0xffff0000, v199
	v_rcp_f32_e32 v210, v210
	v_pk_fma_f32 v[18:19], v[22:23], v[18:19], v[186:187]
	v_add_f32_e32 v22, 1.0, v153
	v_rcp_f32_e32 v183, v22
	v_lshlrev_b32_e32 v174, 16, v175
	v_and_b32_e32 v175, 0xffff0000, v175
	v_lshlrev_b32_e32 v178, 16, v179
	v_and_b32_e32 v179, 0xffff0000, v179
	v_pk_fma_f32 v[28:29], v[24:25], v[178:179], v[174:175]
	v_lshlrev_b32_e32 v24, 16, v198
	v_and_b32_e32 v25, 0xffff0000, v198
	v_pk_fma_f32 v[24:25], v[210:211], v[24:25], v[208:209]
	v_lshlrev_b32_e32 v22, 16, v185
	v_and_b32_e32 v23, 0xffff0000, v185
	v_lshlrev_b32_e32 v184, 16, v201
	v_and_b32_e32 v185, 0xffff0000, v201
	v_pk_mul_f32 v[174:175], v[26:27], v[26:27]
	v_pk_mul_f32 v[176:177], v[28:29], v[28:29]
	v_pk_fma_f32 v[22:23], v[182:183], v[184:185], v[22:23]
	v_pk_mul_f32 v[182:183], v[24:25], v[24:25]
	v_pk_mul_f32 v[184:185], v[18:19], v[18:19]
	v_pk_mul_f32 v[178:179], v[16:17], v[16:17]
	v_pk_mul_f32 v[186:187], v[30:31], v[30:31]
	v_add_f32_e32 v153, v184, v185
	v_add_f32_e32 v182, v182, v183
	v_add_f32_e32 v176, v176, v177
	v_add_f32_e32 v174, v174, v175
	v_pk_mul_f32 v[180:181], v[20:21], v[20:21]
	v_pk_mul_f32 v[198:199], v[22:23], v[22:23]
	v_add_f32_e32 v153, v182, v153
	v_add_f32_e32 v182, v186, v187
	v_add_f32_e32 v174, v174, v176
	v_add_f32_e32 v175, v178, v179
	v_add_f32_e32 v153, v182, v153
	v_add_f32_e32 v182, v198, v199
	v_add_f32_e32 v174, v175, v174
	v_add_f32_e32 v175, v180, v181
	v_add_f32_e32 v153, v182, v153
	v_add_f32_e32 v174, v175, v174
	v_add_f32_e32 v153, v174, v153
	v_mov_b32_e32 v174, v153
	s_nop 1
	v_permlane16_swap_b32 v174, v153
	s_waitcnt lgkmcnt(0)
	v_add_f32_e32 v153, v153, v174
	v_mov_b32_e32 v174, v153
	s_nop 1
	v_permlane32_swap_b32 v174, v153
	s_and_saveexec_b64 s[30:31], s[0:1]
	s_cbranch_execz .LBB0_1373
	v_lshl_add_u64 v[172:173], v[172:173], 2, s[16:17]
	s_waitcnt lgkmcnt(0)
	v_add_f32_e32 v153, v153, v174
	global_atomic_add_f32 v[172:173], v153, off
.LBB0_1373:
	s_or_b64 exec, exec, s[30:31]
	global_load_dword v202, v[154:155], off offset:704
	v_add_u32_e32 v186, 0xb0, v152
	v_ashrrev_i32_e32 v187, 31, v186
	v_lshlrev_b64 v[152:153], 11, v[186:187]
	v_lshl_add_u64 v[152:153], v[152:153], 0, v[144:145]
	v_lshlrev_b64 v[154:155], 1, v[152:153]
	v_lshl_add_u64 v[180:181], s[52:53], 0, v[154:155]
	s_waitcnt lgkmcnt(0)
	global_load_dwordx4 v[172:175], v[180:181], off
	v_lshl_add_u64 v[154:155], s[58:59], 0, v[154:155]
	global_load_dwordx4 v[176:179], v[154:155], off
	global_load_dwordx4 v[182:185], v[180:181], off offset:256
	global_load_dwordx4 v[198:201], v[154:155], off offset:256
	s_waitcnt vmcnt(4)
	v_fmamk_f32 v154, v202, 0x3a000000, v195
	v_mul_f32_e32 v155, 0x4b800000, v154
	v_cmp_gt_f32_e32 vcc, s61, v154
	s_waitcnt vmcnt(2)
	v_lshlrev_b32_e32 v204, 16, v178
	v_cndmask_b32_e32 v154, v154, v155, vcc
	v_rsq_f32_e32 v210, v154
	v_lshlrev_b32_e32 v154, 16, v172
	v_and_b32_e32 v155, 0xffff0000, v172
	s_waitcnt vmcnt(1)
	v_lshlrev_b32_e32 v208, 16, v182
	v_mul_f32_e32 v172, 0x45800000, v210
	v_and_b32_e32 v209, 0xffff0000, v182
	v_cndmask_b32_e32 v182, v210, v172, vcc
	v_mul_f32_e32 v10, v10, v182
	v_mul_f32_e32 v11, v11, v182
	v_mul_f32_e32 v12, v12, v182
	v_mul_f32_e32 v8, v8, v182
	v_mul_f32_e32 v13, v13, v182
	v_mul_f32_e32 v14, v14, v182
	v_mul_f32_e32 v4, v4, v182
	v_mul_f32_e32 v5, v5, v182
	v_mul_f32_e32 v10, 0xbfb8aa3b, v10
	v_mul_f32_e32 v11, 0xbfb8aa3b, v11
	v_mul_f32_e32 v0, v0, v182
	v_mul_f32_e32 v1, v1, v182
	v_mul_f32_e32 v12, 0xbfb8aa3b, v12
	v_mul_f32_e32 v8, 0xbfb8aa3b, v8
	v_mul_f32_e32 v13, 0xbfb8aa3b, v13
	v_mul_f32_e32 v14, 0xbfb8aa3b, v14
	v_mul_f32_e32 v4, 0xbfb8aa3b, v4
	v_mul_f32_e32 v5, 0xbfb8aa3b, v5
	v_exp_f32_e32 v10, v10
	v_exp_f32_e32 v11, v11
	v_mul_f32_e32 v0, 0xbfb8aa3b, v0
	v_mul_f32_e32 v210, 0xbfb8aa3b, v1
	v_exp_f32_e32 v1, v12
	v_exp_f32_e32 v8, v8
	v_exp_f32_e32 v12, v13
	v_exp_f32_e32 v13, v14
	v_exp_f32_e32 v4, v4
	v_exp_f32_e32 v5, v5
	v_exp_f32_e32 v0, v0
	v_mul_f32_e32 v15, v15, v182
	v_mul_f32_e32 v9, v9, v182
	v_mul_f32_e32 v15, 0xbfb8aa3b, v15
	v_add_f32_e32 v10, 1.0, v10
	v_add_f32_e32 v11, 1.0, v11
	v_lshlrev_b32_e32 v206, 16, v173
	v_and_b32_e32 v207, 0xffff0000, v173
	v_mul_f32_e32 v9, 0xbfb8aa3b, v9
	v_exp_f32_e32 v14, v15
	v_add_f32_e32 v1, 1.0, v1
	v_add_f32_e32 v8, 1.0, v8
	v_add_f32_e32 v12, 1.0, v12
	v_add_f32_e32 v13, 1.0, v13
	v_add_f32_e32 v15, 1.0, v4
	v_add_f32_e32 v173, 1.0, v5
	v_rcp_f32_e32 v10, v10
	v_rcp_f32_e32 v11, v11
	v_mul_f32_e32 v6, v6, v182
	v_mul_f32_e32 v7, v7, v182
	v_exp_f32_e32 v9, v9
	v_add_f32_e32 v172, 1.0, v0
	v_rcp_f32_e32 v0, v1
	v_rcp_f32_e32 v4, v8
	v_rcp_f32_e32 v1, v12
	v_rcp_f32_e32 v8, v13
	v_rcp_f32_e32 v12, v15
	v_rcp_f32_e32 v13, v173
	v_exp_f32_e32 v15, v210
	v_mul_f32_e32 v6, 0xbfb8aa3b, v6
	v_mul_f32_e32 v2, v2, v182
	v_mul_f32_e32 v7, 0xbfb8aa3b, v7
	v_mul_f32_e32 v3, v3, v182
	v_exp_f32_e32 v6, v6
	v_mul_f32_e32 v2, 0xbfb8aa3b, v2
	v_exp_f32_e32 v7, v7
	v_mul_f32_e32 v3, 0xbfb8aa3b, v3
	v_lshlrev_b32_e32 v202, 16, v174
	v_and_b32_e32 v203, 0xffff0000, v174
	v_and_b32_e32 v205, 0xffff0000, v178
	v_lshlrev_b32_e32 v174, 16, v175
	v_and_b32_e32 v175, 0xffff0000, v175
	v_lshlrev_b32_e32 v178, 16, v179
	v_and_b32_e32 v179, 0xffff0000, v179
	v_exp_f32_e32 v2, v2
	v_exp_f32_e32 v3, v3
	v_pk_fma_f32 v[174:175], v[10:11], v[178:179], v[174:175]
	s_waitcnt vmcnt(0)
	v_lshlrev_b32_e32 v178, 16, v198
	v_and_b32_e32 v179, 0xffff0000, v198
	v_add_f32_e32 v9, 1.0, v9
	v_add_f32_e32 v14, 1.0, v14
	v_pk_fma_f32 v[178:179], v[12:13], v[178:179], v[208:209]
	v_add_f32_e32 v12, 1.0, v15
	v_rcp_f32_e32 v5, v9
	v_rcp_f32_e32 v9, v14
	v_rcp_f32_e32 v14, v172
	v_rcp_f32_e32 v15, v12
	v_add_f32_e32 v6, 1.0, v6
	v_add_f32_e32 v7, 1.0, v7
	v_rcp_f32_e32 v6, v6
	v_add_f32_e32 v2, 1.0, v2
	v_rcp_f32_e32 v7, v7
	v_add_f32_e32 v3, 1.0, v3
	v_lshlrev_b32_e32 v180, 16, v176
	v_and_b32_e32 v181, 0xffff0000, v176
	v_rcp_f32_e32 v2, v2
	v_rcp_f32_e32 v3, v3
	v_pk_fma_f32 v[172:173], v[0:1], v[180:181], v[154:155]
	v_lshlrev_b32_e32 v12, 16, v184
	v_and_b32_e32 v13, 0xffff0000, v184
	v_lshlrev_b32_e32 v180, 16, v200
	v_and_b32_e32 v181, 0xffff0000, v200
	v_pk_fma_f32 v[180:181], v[14:15], v[180:181], v[12:13]
	v_lshlrev_b32_e32 v12, 16, v183
	v_and_b32_e32 v13, 0xffff0000, v183
	v_lshlrev_b32_e32 v14, 16, v199
	v_and_b32_e32 v15, 0xffff0000, v199
	v_pk_fma_f32 v[182:183], v[6:7], v[14:15], v[12:13]
	v_lshlrev_b32_e32 v6, 16, v185
	v_and_b32_e32 v7, 0xffff0000, v185
	v_lshlrev_b32_e32 v12, 16, v201
	v_and_b32_e32 v13, 0xffff0000, v201
	v_pk_fma_f32 v[184:185], v[2:3], v[12:13], v[6:7]
	v_pk_mul_f32 v[2:3], v[178:179], v[178:179]
	v_pk_mul_f32 v[6:7], v[182:183], v[182:183]
	v_lshlrev_b32_e32 v176, 16, v177
	v_and_b32_e32 v177, 0xffff0000, v177
	v_pk_mul_f32 v[12:13], v[180:181], v[180:181]
	v_add_f32_e32 v6, v6, v7
	v_add_f32_e32 v2, v2, v3
	v_pk_fma_f32 v[176:177], v[8:9], v[176:177], v[206:207]
	v_pk_mul_f32 v[14:15], v[184:185], v[184:185]
	v_add_f32_e32 v2, v2, v6
	v_add_f32_e32 v3, v12, v13
	v_pk_fma_f32 v[154:155], v[4:5], v[204:205], v[202:203]
	v_pk_mul_f32 v[0:1], v[172:173], v[172:173]
	v_pk_mul_f32 v[4:5], v[176:177], v[176:177]
	v_add_f32_e32 v2, v3, v2
	v_add_f32_e32 v3, v14, v15
	v_pk_mul_f32 v[8:9], v[154:155], v[154:155]
	v_add_f32_e32 v2, v3, v2
	v_add_f32_e32 v3, v4, v5
	v_add_f32_e32 v0, v0, v1
	v_pk_mul_f32 v[10:11], v[174:175], v[174:175]
	v_add_f32_e32 v0, v0, v3
	v_add_f32_e32 v1, v8, v9
	v_add_f32_e32 v0, v1, v0
	v_add_f32_e32 v1, v10, v11
	v_add_f32_e32 v0, v1, v0
	v_add_f32_e32 v0, v0, v2
	v_mov_b32_e32 v1, v0
	s_nop 1
	v_permlane16_swap_b32 v1, v0
	s_waitcnt lgkmcnt(0)
	v_add_f32_e32 v0, v0, v1
	v_mov_b32_e32 v1, v0
	s_nop 1
	v_permlane32_swap_b32 v1, v0
	s_and_saveexec_b64 s[30:31], s[0:1]
	s_cbranch_execz .LBB0_1375
	v_lshl_add_u64 v[2:3], v[186:187], 2, s[16:17]
	s_waitcnt lgkmcnt(0)
	v_add_f32_e32 v0, v0, v1
	global_atomic_add_f32 v[2:3], v0, off
